# removed 30 provably redundant s_waitcnt lgkmcnt(0) (second of two identical consecutive waits) in the GEMM MFMA slots
# baseline (speedup 1.0000x reference)
; #define PG8_STAGE(bufoff, gbase, voff) do { _Pragma("unroll") for (int _i = 0; _i < 2; ++_i) \
;         __builtin_amdgcn_global_load_lds((const unsigned*)((const char*)(gbase) + (voff)[_i]), (PG8_LAS unsigned*)(lds + (bufoff) + ldsw + _i * 8192), 16, 0, 0); } while (0)
; #define PG8_LDA(dst, b, h) do { _Pragma("unroll") for (int m = 0; m < 4; ++m) _Pragma("unroll") for (int k = 0; k < 2; ++k) dst[m][k] = *(const PG8_LAS bf16x8*)(lds + PG8_SA(b, h) + aoff + m * 2048 + k * 1024); } while (0)
; #define PG8_WAIT_V(n) asm volatile("s_waitcnt vmcnt(" #n ")" ::: "memory")
; template <class Epi, class Sched>
; __device__ __forceinline__ void gemm_phase(PG8_LAS unsigned char* lds, const Gemm g, const Sched& S, const Epi& E) {
;     ...
;         for (int t = 0; t < nt; t += 2) {
;             const bool last = (t == nt - 2);
;             const char* a1 = cA + (size_t)(t + 1) * kstep;
;             const char* a2 = last ? nA : cA + (size_t)(t + 2) * kstep; const char* b2 = last ? nB : cB + (size_t)(t + 2) * kstep;
;             const char* a3 = a2 + kstep; const char* b3 = b2 + kstep;
;             if (last && has_next) S.a_ready(nxt);
;             PG8_LDB(B0, 0, 0); PG8_SCHED; PG8_LDA(At, 0, 0); PG8_STAGE(PG8_SA(1, 1), a1 + hstep, voffA);
;             PG8_WAIT_L(8); PG8_BAR; PG8_WAIT_L(0); PG8_MMA(0, 0, At, B0); PG8_BAR; PG8_SCHED;
;             PG8_LDB(B1, 0, 1); PG8_STAGE(PG8_SB(0, 0), b2, voffB);
;             PG8_BAR; PG8_WAIT_L(0); PG8_MMA(0, 1, At, B1); PG8_BAR;
;             PG8_LDA(At, 0, 1); PG8_STAGE(PG8_SA(0, 0), a2, voffA);
;             PG8_BAR; PG8_WAIT_L(0); PG8_MMA(1, 0, At, B0); PG8_BAR; PG8_SCHED;
;             PG8_STAGE(PG8_SB(0, 1), b2 + hstep, voffB);
;             PG8_WAIT_V(6); PG8_BAR; PG8_MMA(1, 1, At, B1); PG8_BAR;
;             PG8_LDB(B0, 1, 0); PG8_SCHED; PG8_LDA(At, 1, 0); PG8_STAGE(PG8_SA(0, 1), a2 + hstep, voffA);
;             PG8_WAIT_L(8); PG8_BAR; PG8_WAIT_L(0); PG8_MMA(0, 0, At, B0); PG8_BAR; PG8_SCHED;
;             PG8_LDB(B1, 1, 1); PG8_STAGE(PG8_SB(1, 0), b3, voffB);
;             PG8_BAR; PG8_WAIT_L(0); PG8_MMA(0, 1, At, B1); PG8_BAR;
;             PG8_LDA(At, 1, 1); PG8_STAGE(PG8_SA(1, 0), a3, voffA);
;             PG8_BAR; PG8_WAIT_L(0); PG8_MMA(1, 0, At, B0); PG8_BAR; PG8_SCHED;
;             PG8_STAGE(PG8_SB(1, 1), b3 + hstep, voffB);
;             PG8_WAIT_V(6); PG8_BAR; PG8_MMA(1, 1, At, B1); PG8_BAR;
.LBB0_185:
	s_add_u32 s16, s14, 0xfffc0080
	s_addc_u32 s17, s15, -1
	s_add_i32 s80, 0, 0x10000
	v_add_u32_e32 v140, s80, v231
	ds_read_b128 v[128:131], v140
	ds_read_b128 v[132:135], v140 offset:1024
	ds_read_b128 v[136:139], v140 offset:2048
	ds_read_b128 v[140:143], v140 offset:3072
	s_cmp_eq_u32 s79, 12
	s_cselect_b32 s19, s7, s17
	s_cselect_b32 s18, s13, s16
	s_cselect_b32 s17, s1, s78
	s_cselect_b32 s16, s76, s77
	v_lshl_add_u64 v[176:177], s[14:15], 0, v[200:201]
	s_add_i32 m0, s46, 0xc000
	ds_read_b128 v[144:147], v232
	ds_read_b128 v[148:151], v232 offset:1024
	ds_read_b128 v[152:155], v232 offset:2048
	ds_read_b128 v[156:159], v232 offset:3072
	ds_read_b128 v[160:163], v232 offset:4096
	ds_read_b128 v[164:167], v232 offset:5120
	ds_read_b128 v[168:171], v232 offset:6144
	ds_read_b128 v[172:175], v232 offset:7168
	global_load_lds_dwordx4 v[176:177], off
	v_lshl_add_u64 v[176:177], s[14:15], 0, v[202:203]
	s_add_i32 m0, s46, 0xe000
	s_nop 0
	global_load_lds_dwordx4 v[176:177], off
	s_waitcnt lgkmcnt(8)
	s_barrier
	s_waitcnt lgkmcnt(0)
	v_mfma_f32_16x16x32_bf16 v[124:127], v[128:131], v[144:147], v[124:127]
	v_mfma_f32_16x16x32_bf16 v[116:119], v[136:139], v[144:147], v[116:119]
	v_mfma_f32_16x16x32_bf16 v[108:111], v[128:131], v[152:155], v[108:111]
	v_mfma_f32_16x16x32_bf16 v[100:103], v[136:139], v[152:155], v[100:103]
	v_mfma_f32_16x16x32_bf16 v[92:95], v[128:131], v[160:163], v[92:95]
	v_mfma_f32_16x16x32_bf16 v[84:87], v[136:139], v[160:163], v[84:87]
	v_mfma_f32_16x16x32_bf16 v[76:79], v[128:131], v[168:171], v[76:79]
	v_mfma_f32_16x16x32_bf16 v[68:71], v[136:139], v[168:171], v[68:71]
	v_mfma_f32_16x16x32_bf16 v[124:127], v[132:135], v[148:151], v[124:127]
	v_mfma_f32_16x16x32_bf16 v[116:119], v[140:143], v[148:151], v[116:119]
	v_mfma_f32_16x16x32_bf16 v[108:111], v[132:135], v[156:159], v[108:111]
	v_mfma_f32_16x16x32_bf16 v[100:103], v[140:143], v[156:159], v[100:103]
	v_mfma_f32_16x16x32_bf16 v[92:95], v[132:135], v[164:167], v[92:95]
	v_mfma_f32_16x16x32_bf16 v[84:87], v[140:143], v[164:167], v[84:87]
	v_mfma_f32_16x16x32_bf16 v[76:79], v[132:135], v[172:175], v[76:79]
	v_mfma_f32_16x16x32_bf16 v[68:71], v[140:143], v[172:175], v[68:71]
	s_barrier
	s_add_i32 s82, 0, 0x14000
	s_add_i32 s80, s80, s21
	v_add_u32_e32 v180, s82, v231
	v_lshl_add_u64 v[218:219], s[16:17], 0, v[188:189]
	s_mov_b32 m0, s80
	ds_read_b128 v[176:179], v180
	ds_read_b128 v[206:209], v180 offset:1024
	ds_read_b128 v[210:213], v180 offset:2048
	ds_read_b128 v[214:217], v180 offset:3072
	global_load_lds_dwordx4 v[218:219], off
	v_lshl_add_u64 v[220:221], s[16:17], 0, v[184:185]
	s_add_i32 m0, s80, 0x2000
	s_nop 0
	global_load_lds_dwordx4 v[220:221], off
	s_barrier
	s_waitcnt lgkmcnt(0)
	v_mfma_f32_16x16x32_bf16 v[120:123], v[176:179], v[144:147], v[120:123]
	v_mfma_f32_16x16x32_bf16 v[112:115], v[210:213], v[144:147], v[112:115]
	v_mfma_f32_16x16x32_bf16 v[104:107], v[176:179], v[152:155], v[104:107]
	v_mfma_f32_16x16x32_bf16 v[96:99], v[210:213], v[152:155], v[96:99]
	v_mfma_f32_16x16x32_bf16 v[88:91], v[176:179], v[160:163], v[88:91]
	v_mfma_f32_16x16x32_bf16 v[80:83], v[210:213], v[160:163], v[80:83]
	v_mfma_f32_16x16x32_bf16 v[72:75], v[176:179], v[168:171], v[72:75]
	v_mfma_f32_16x16x32_bf16 v[64:67], v[210:213], v[168:171], v[64:67]
	v_mfma_f32_16x16x32_bf16 v[120:123], v[206:209], v[148:151], v[120:123]
	v_mfma_f32_16x16x32_bf16 v[112:115], v[214:217], v[148:151], v[112:115]
	v_mfma_f32_16x16x32_bf16 v[104:107], v[206:209], v[156:159], v[104:107]
	v_mfma_f32_16x16x32_bf16 v[96:99], v[214:217], v[156:159], v[96:99]
	v_mfma_f32_16x16x32_bf16 v[88:91], v[206:209], v[164:167], v[88:91]
	v_mfma_f32_16x16x32_bf16 v[80:83], v[214:217], v[164:167], v[80:83]
	v_mfma_f32_16x16x32_bf16 v[72:75], v[206:209], v[172:175], v[72:75]
	v_mfma_f32_16x16x32_bf16 v[64:67], v[214:217], v[172:175], v[64:67]
	s_mov_b32 m0, s46
	v_lshl_add_u64 v[222:223], s[18:19], 0, v[190:191]
	s_barrier
	ds_read_b128 v[144:147], v232 offset:16384
	ds_read_b128 v[148:151], v232 offset:17408
	ds_read_b128 v[152:155], v232 offset:18432
	ds_read_b128 v[156:159], v232 offset:19456
	ds_read_b128 v[160:163], v232 offset:20480
	ds_read_b128 v[164:167], v232 offset:21504
	ds_read_b128 v[168:171], v232 offset:22528
	ds_read_b128 v[172:175], v232 offset:23552
	global_load_lds_dwordx4 v[222:223], off
	v_lshl_add_u64 v[224:225], s[18:19], 0, v[186:187]
	s_mov_b32 m0, s47
	s_nop 0
	global_load_lds_dwordx4 v[224:225], off
	s_barrier
	s_waitcnt lgkmcnt(0)
	v_mfma_f32_16x16x32_bf16 v[60:63], v[128:131], v[144:147], v[60:63]
	v_mfma_f32_16x16x32_bf16 v[52:55], v[136:139], v[144:147], v[52:55]
	v_mfma_f32_16x16x32_bf16 v[44:47], v[128:131], v[152:155], v[44:47]
	v_mfma_f32_16x16x32_bf16 v[36:39], v[136:139], v[152:155], v[36:39]
	v_mfma_f32_16x16x32_bf16 v[28:31], v[128:131], v[160:163], v[28:31]
	v_mfma_f32_16x16x32_bf16 v[20:23], v[136:139], v[160:163], v[20:23]
	v_mfma_f32_16x16x32_bf16 v[12:15], v[128:131], v[168:171], v[12:15]
	v_mfma_f32_16x16x32_bf16 v[4:7], v[136:139], v[168:171], v[4:7]
	v_mfma_f32_16x16x32_bf16 v[60:63], v[132:135], v[148:151], v[60:63]
	v_mfma_f32_16x16x32_bf16 v[52:55], v[140:143], v[148:151], v[52:55]
	v_mfma_f32_16x16x32_bf16 v[44:47], v[132:135], v[156:159], v[44:47]
	v_mfma_f32_16x16x32_bf16 v[36:39], v[140:143], v[156:159], v[36:39]
	v_mfma_f32_16x16x32_bf16 v[28:31], v[132:135], v[164:167], v[28:31]
	v_mfma_f32_16x16x32_bf16 v[20:23], v[140:143], v[164:167], v[20:23]
	v_mfma_f32_16x16x32_bf16 v[12:15], v[132:135], v[172:175], v[12:15]
	v_mfma_f32_16x16x32_bf16 v[4:7], v[140:143], v[172:175], v[4:7]
	s_barrier
; #define PG8_STAGE(bufoff, gbase, voff) do { _Pragma("unroll") for (int _i = 0; _i < 2; ++_i) \
;         __builtin_amdgcn_global_load_lds((const unsigned*)((const char*)(gbase) + (voff)[_i]), (PG8_LAS unsigned*)(lds + (bufoff) + ldsw + _i * 8192), 16, 0, 0); } while (0)
; #define PG8_LDA(dst, b, h) do { _Pragma("unroll") for (int m = 0; m < 4; ++m) _Pragma("unroll") for (int k = 0; k < 2; ++k) dst[m][k] = *(const PG8_LAS bf16x8*)(lds + PG8_SA(b, h) + aoff + m * 2048 + k * 1024); } while (0)
; #define PG8_WAIT_V(n) asm volatile("s_waitcnt vmcnt(" #n ")" ::: "memory")
; template <class Epi, class Sched>
; __device__ __forceinline__ void gemm_phase(PG8_LAS unsigned char* lds, const Gemm g, const Sched& S, const Epi& E) {
;     ...
;         for (int t = 0; t < nt; t += 2) {
;             const bool last = (t == nt - 2);
;             const char* a1 = cA + (size_t)(t + 1) * kstep;
;             const char* a2 = last ? nA : cA + (size_t)(t + 2) * kstep; const char* b2 = last ? nB : cB + (size_t)(t + 2) * kstep;
;             const char* a3 = a2 + kstep; const char* b3 = b2 + kstep;
;             if (last && has_next) S.a_ready(nxt);
;             PG8_LDB(B0, 0, 0); PG8_SCHED; PG8_LDA(At, 0, 0); PG8_STAGE(PG8_SA(1, 1), a1 + hstep, voffA);
;             PG8_WAIT_L(8); PG8_BAR; PG8_WAIT_L(0); PG8_MMA(0, 0, At, B0); PG8_BAR; PG8_SCHED;
;             PG8_LDB(B1, 0, 1); PG8_STAGE(PG8_SB(0, 0), b2, voffB);
;             PG8_BAR; PG8_WAIT_L(0); PG8_MMA(0, 1, At, B1); PG8_BAR;
;             PG8_LDA(At, 0, 1); PG8_STAGE(PG8_SA(0, 0), a2, voffA);
;             PG8_BAR; PG8_WAIT_L(0); PG8_MMA(1, 0, At, B0); PG8_BAR; PG8_SCHED;
;             PG8_STAGE(PG8_SB(0, 1), b2 + hstep, voffB);
;             PG8_WAIT_V(6); PG8_BAR; PG8_MMA(1, 1, At, B1); PG8_BAR;
;             PG8_LDB(B0, 1, 0); PG8_SCHED; PG8_LDA(At, 1, 0); PG8_STAGE(PG8_SA(0, 1), a2 + hstep, voffA);
;             PG8_WAIT_L(8); PG8_BAR; PG8_WAIT_L(0); PG8_MMA(0, 0, At, B0); PG8_BAR; PG8_SCHED;
;             PG8_LDB(B1, 1, 1); PG8_STAGE(PG8_SB(1, 0), b3, voffB);
;             PG8_BAR; PG8_WAIT_L(0); PG8_MMA(0, 1, At, B1); PG8_BAR;
;             PG8_LDA(At, 1, 1); PG8_STAGE(PG8_SA(1, 0), a3, voffA);
;             PG8_BAR; PG8_WAIT_L(0); PG8_MMA(1, 0, At, B0); PG8_BAR; PG8_SCHED;
;             PG8_STAGE(PG8_SB(1, 1), b3 + hstep, voffB);
;             PG8_WAIT_V(6); PG8_BAR; PG8_MMA(1, 1, At, B1); PG8_BAR;
	s_add_u32 s80, s16, 0x40000
	s_addc_u32 s81, s17, 0
	s_add_i32 s82, s82, s21
	v_lshl_add_u64 v[128:129], s[80:81], 0, v[188:189]
	s_mov_b32 m0, s82
	s_nop 0
	global_load_lds_dwordx4 v[128:129], off
	v_lshl_add_u64 v[128:129], s[80:81], 0, v[184:185]
	s_add_i32 m0, s82, 0x2000
	s_nop 0
	global_load_lds_dwordx4 v[128:129], off
	s_waitcnt vmcnt(6)
	s_barrier
	v_mfma_f32_16x16x32_bf16 v[56:59], v[176:179], v[144:147], v[56:59]
	v_mfma_f32_16x16x32_bf16 v[48:51], v[210:213], v[144:147], v[48:51]
	v_mfma_f32_16x16x32_bf16 v[40:43], v[176:179], v[152:155], v[40:43]
	v_mfma_f32_16x16x32_bf16 v[32:35], v[210:213], v[152:155], v[32:35]
	v_mfma_f32_16x16x32_bf16 v[24:27], v[176:179], v[160:163], v[24:27]
	v_mfma_f32_16x16x32_bf16 v[16:19], v[210:213], v[160:163], v[16:19]
	v_mfma_f32_16x16x32_bf16 v[8:11], v[176:179], v[168:171], v[8:11]
	v_mfma_f32_16x16x32_bf16 v[0:3], v[210:213], v[168:171], v[0:3]
	v_mfma_f32_16x16x32_bf16 v[56:59], v[206:209], v[148:151], v[56:59]
	v_mfma_f32_16x16x32_bf16 v[48:51], v[214:217], v[148:151], v[48:51]
	v_mfma_f32_16x16x32_bf16 v[40:43], v[206:209], v[156:159], v[40:43]
	v_mfma_f32_16x16x32_bf16 v[32:35], v[214:217], v[156:159], v[32:35]
	v_mfma_f32_16x16x32_bf16 v[24:27], v[206:209], v[164:167], v[24:27]
	v_mfma_f32_16x16x32_bf16 v[16:19], v[214:217], v[164:167], v[16:19]
	v_mfma_f32_16x16x32_bf16 v[8:11], v[206:209], v[172:175], v[8:11]
	v_mfma_f32_16x16x32_bf16 v[0:3], v[214:217], v[172:175], v[0:3]
	s_add_i32 s80, 0, 0x18000
	v_add_u32_e32 v140, s80, v231
	s_barrier
	ds_read_b128 v[128:131], v140
	ds_read_b128 v[132:135], v140 offset:1024
	ds_read_b128 v[136:139], v140 offset:2048
	ds_read_b128 v[140:143], v140 offset:3072
	s_add_u32 s18, s18, 0x40000
	s_addc_u32 s19, s19, 0
	s_mov_b32 m0, s70
	v_lshl_add_u64 v[176:177], s[18:19], 0, v[190:191]
	ds_read_b128 v[144:147], v232 offset:32768
	ds_read_b128 v[148:151], v232 offset:33792
	ds_read_b128 v[152:155], v232 offset:34816
	ds_read_b128 v[156:159], v232 offset:35840
	ds_read_b128 v[160:163], v232 offset:36864
	ds_read_b128 v[164:167], v232 offset:37888
	ds_read_b128 v[168:171], v232 offset:38912
	ds_read_b128 v[172:175], v232 offset:39936
	global_load_lds_dwordx4 v[176:177], off
	v_lshl_add_u64 v[176:177], s[18:19], 0, v[186:187]
	s_mov_b32 m0, s71
	s_nop 0
	global_load_lds_dwordx4 v[176:177], off
	s_waitcnt lgkmcnt(8)
	s_barrier
	s_waitcnt lgkmcnt(0)
	v_mfma_f32_16x16x32_bf16 v[124:127], v[128:131], v[144:147], v[124:127]
	v_mfma_f32_16x16x32_bf16 v[116:119], v[136:139], v[144:147], v[116:119]
	v_mfma_f32_16x16x32_bf16 v[108:111], v[128:131], v[152:155], v[108:111]
	v_mfma_f32_16x16x32_bf16 v[100:103], v[136:139], v[152:155], v[100:103]
	v_mfma_f32_16x16x32_bf16 v[92:95], v[128:131], v[160:163], v[92:95]
	v_mfma_f32_16x16x32_bf16 v[84:87], v[136:139], v[160:163], v[84:87]
	v_mfma_f32_16x16x32_bf16 v[76:79], v[128:131], v[168:171], v[76:79]
	v_mfma_f32_16x16x32_bf16 v[68:71], v[136:139], v[168:171], v[68:71]
	v_mfma_f32_16x16x32_bf16 v[124:127], v[132:135], v[148:151], v[124:127]
	v_mfma_f32_16x16x32_bf16 v[116:119], v[140:143], v[148:151], v[116:119]
	v_mfma_f32_16x16x32_bf16 v[108:111], v[132:135], v[156:159], v[108:111]
	v_mfma_f32_16x16x32_bf16 v[100:103], v[140:143], v[156:159], v[100:103]
	v_mfma_f32_16x16x32_bf16 v[92:95], v[132:135], v[164:167], v[92:95]
	v_mfma_f32_16x16x32_bf16 v[84:87], v[140:143], v[164:167], v[84:87]
	v_mfma_f32_16x16x32_bf16 v[76:79], v[132:135], v[172:175], v[76:79]
	v_mfma_f32_16x16x32_bf16 v[68:71], v[140:143], v[172:175], v[68:71]
	s_barrier
	s_add_i32 s18, 0, 0x1c000
	s_add_i32 s19, s80, s21
	v_add_u32_e32 v180, s18, v231
	v_lshl_add_u64 v[218:219], v[218:219], 0, s[38:39]
	s_mov_b32 m0, s19
	ds_read_b128 v[176:179], v180
	ds_read_b128 v[206:209], v180 offset:1024
	ds_read_b128 v[210:213], v180 offset:2048
	ds_read_b128 v[214:217], v180 offset:3072
	global_load_lds_dwordx4 v[218:219], off
	v_lshl_add_u64 v[218:219], v[220:221], 0, s[38:39]
	s_add_i32 m0, s19, 0x2000
	s_nop 0
	global_load_lds_dwordx4 v[218:219], off
	s_barrier
	s_waitcnt lgkmcnt(0)
	v_mfma_f32_16x16x32_bf16 v[120:123], v[176:179], v[144:147], v[120:123]
	v_mfma_f32_16x16x32_bf16 v[112:115], v[210:213], v[144:147], v[112:115]
	v_mfma_f32_16x16x32_bf16 v[104:107], v[176:179], v[152:155], v[104:107]
	v_mfma_f32_16x16x32_bf16 v[96:99], v[210:213], v[152:155], v[96:99]
	v_mfma_f32_16x16x32_bf16 v[88:91], v[176:179], v[160:163], v[88:91]
	v_mfma_f32_16x16x32_bf16 v[80:83], v[210:213], v[160:163], v[80:83]
	v_mfma_f32_16x16x32_bf16 v[72:75], v[176:179], v[168:171], v[72:75]
	v_mfma_f32_16x16x32_bf16 v[64:67], v[210:213], v[168:171], v[64:67]
	v_mfma_f32_16x16x32_bf16 v[120:123], v[206:209], v[148:151], v[120:123]
	v_mfma_f32_16x16x32_bf16 v[112:115], v[214:217], v[148:151], v[112:115]
	v_mfma_f32_16x16x32_bf16 v[104:107], v[206:209], v[156:159], v[104:107]
	v_mfma_f32_16x16x32_bf16 v[96:99], v[214:217], v[156:159], v[96:99]
	v_mfma_f32_16x16x32_bf16 v[88:91], v[206:209], v[164:167], v[88:91]
	v_mfma_f32_16x16x32_bf16 v[80:83], v[214:217], v[164:167], v[80:83]
	v_mfma_f32_16x16x32_bf16 v[72:75], v[206:209], v[172:175], v[72:75]
	v_mfma_f32_16x16x32_bf16 v[64:67], v[214:217], v[172:175], v[64:67]
	s_mov_b32 m0, s72
	v_lshl_add_u64 v[218:219], v[222:223], 0, s[38:39]
	s_barrier
	ds_read_b128 v[144:147], v232 offset:49152
	ds_read_b128 v[148:151], v232 offset:50176
	ds_read_b128 v[152:155], v232 offset:51200
	ds_read_b128 v[156:159], v232 offset:52224
	ds_read_b128 v[160:163], v232 offset:53248
	ds_read_b128 v[164:167], v232 offset:54272
	ds_read_b128 v[168:171], v232 offset:55296
	ds_read_b128 v[172:175], v232 offset:56320
	global_load_lds_dwordx4 v[218:219], off
	v_lshl_add_u64 v[218:219], v[224:225], 0, s[38:39]
	s_mov_b32 m0, s73
	s_nop 0
	global_load_lds_dwordx4 v[218:219], off
	s_barrier
; #define PG8_STAGE(bufoff, gbase, voff) do { _Pragma("unroll") for (int _i = 0; _i < 2; ++_i) \
;         __builtin_amdgcn_global_load_lds((const unsigned*)((const char*)(gbase) + (voff)[_i]), (PG8_LAS unsigned*)(lds + (bufoff) + ldsw + _i * 8192), 16, 0, 0); } while (0)
; #define PG8_LDA(dst, b, h) do { _Pragma("unroll") for (int m = 0; m < 4; ++m) _Pragma("unroll") for (int k = 0; k < 2; ++k) dst[m][k] = *(const PG8_LAS bf16x8*)(lds + PG8_SA(b, h) + aoff + m * 2048 + k * 1024); } while (0)
; #define PG8_WAIT_V(n) asm volatile("s_waitcnt vmcnt(" #n ")" ::: "memory")
; template <class Epi, class Sched>
; __device__ __forceinline__ void gemm_phase(PG8_LAS unsigned char* lds, const Gemm g, const Sched& S, const Epi& E) {
;     ...
;         for (int t = 0; t < nt; t += 2) {
;             const bool last = (t == nt - 2);
;             const char* a1 = cA + (size_t)(t + 1) * kstep;
;             const char* a2 = last ? nA : cA + (size_t)(t + 2) * kstep; const char* b2 = last ? nB : cB + (size_t)(t + 2) * kstep;
;             const char* a3 = a2 + kstep; const char* b3 = b2 + kstep;
;             if (last && has_next) S.a_ready(nxt);
;             PG8_LDB(B0, 0, 0); PG8_SCHED; PG8_LDA(At, 0, 0); PG8_STAGE(PG8_SA(1, 1), a1 + hstep, voffA);
;             PG8_WAIT_L(8); PG8_BAR; PG8_WAIT_L(0); PG8_MMA(0, 0, At, B0); PG8_BAR; PG8_SCHED;
;             PG8_LDB(B1, 0, 1); PG8_STAGE(PG8_SB(0, 0), b2, voffB);
;             PG8_BAR; PG8_WAIT_L(0); PG8_MMA(0, 1, At, B1); PG8_BAR;
;             PG8_LDA(At, 0, 1); PG8_STAGE(PG8_SA(0, 0), a2, voffA);
;             PG8_BAR; PG8_WAIT_L(0); PG8_MMA(1, 0, At, B0); PG8_BAR; PG8_SCHED;
;             PG8_STAGE(PG8_SB(0, 1), b2 + hstep, voffB);
;             PG8_WAIT_V(6); PG8_BAR; PG8_MMA(1, 1, At, B1); PG8_BAR;
;             PG8_LDB(B0, 1, 0); PG8_SCHED; PG8_LDA(At, 1, 0); PG8_STAGE(PG8_SA(0, 1), a2 + hstep, voffA);
;             PG8_WAIT_L(8); PG8_BAR; PG8_WAIT_L(0); PG8_MMA(0, 0, At, B0); PG8_BAR; PG8_SCHED;
;             PG8_LDB(B1, 1, 1); PG8_STAGE(PG8_SB(1, 0), b3, voffB);
;             PG8_BAR; PG8_WAIT_L(0); PG8_MMA(0, 1, At, B1); PG8_BAR;
;             PG8_LDA(At, 1, 1); PG8_STAGE(PG8_SA(1, 0), a3, voffA);
;             PG8_BAR; PG8_WAIT_L(0); PG8_MMA(1, 0, At, B0); PG8_BAR; PG8_SCHED;
;             PG8_STAGE(PG8_SB(1, 1), b3 + hstep, voffB);
;             PG8_WAIT_V(6); PG8_BAR; PG8_MMA(1, 1, At, B1); PG8_BAR;
	s_waitcnt lgkmcnt(0)
	v_mfma_f32_16x16x32_bf16 v[60:63], v[128:131], v[144:147], v[60:63]
	v_mfma_f32_16x16x32_bf16 v[52:55], v[136:139], v[144:147], v[52:55]
	v_mfma_f32_16x16x32_bf16 v[44:47], v[128:131], v[152:155], v[44:47]
	v_mfma_f32_16x16x32_bf16 v[36:39], v[136:139], v[152:155], v[36:39]
	v_mfma_f32_16x16x32_bf16 v[28:31], v[128:131], v[160:163], v[28:31]
	v_mfma_f32_16x16x32_bf16 v[20:23], v[136:139], v[160:163], v[20:23]
	v_mfma_f32_16x16x32_bf16 v[12:15], v[128:131], v[168:171], v[12:15]
	v_mfma_f32_16x16x32_bf16 v[4:7], v[136:139], v[168:171], v[4:7]
	v_mfma_f32_16x16x32_bf16 v[60:63], v[132:135], v[148:151], v[60:63]
	v_mfma_f32_16x16x32_bf16 v[52:55], v[140:143], v[148:151], v[52:55]
	v_mfma_f32_16x16x32_bf16 v[44:47], v[132:135], v[156:159], v[44:47]
	v_mfma_f32_16x16x32_bf16 v[36:39], v[140:143], v[156:159], v[36:39]
	v_mfma_f32_16x16x32_bf16 v[28:31], v[132:135], v[164:167], v[28:31]
	v_mfma_f32_16x16x32_bf16 v[20:23], v[140:143], v[164:167], v[20:23]
	v_mfma_f32_16x16x32_bf16 v[12:15], v[132:135], v[172:175], v[12:15]
	v_mfma_f32_16x16x32_bf16 v[4:7], v[140:143], v[172:175], v[4:7]
	s_barrier
	s_add_u32 s16, s16, 0x40080
	s_addc_u32 s17, s17, 0
	s_add_i32 s18, s18, s21
	v_lshl_add_u64 v[128:129], s[16:17], 0, v[188:189]
	s_mov_b32 m0, s18
	s_nop 0
	global_load_lds_dwordx4 v[128:129], off
	v_lshl_add_u64 v[128:129], s[16:17], 0, v[184:185]
	s_add_i32 m0, s18, 0x2000
	s_nop 0
	global_load_lds_dwordx4 v[128:129], off
	s_waitcnt vmcnt(6)
	s_barrier
	v_mfma_f32_16x16x32_bf16 v[56:59], v[176:179], v[144:147], v[56:59]
	v_mfma_f32_16x16x32_bf16 v[48:51], v[210:213], v[144:147], v[48:51]
	v_mfma_f32_16x16x32_bf16 v[40:43], v[176:179], v[152:155], v[40:43]
	v_mfma_f32_16x16x32_bf16 v[32:35], v[210:213], v[152:155], v[32:35]
	v_mfma_f32_16x16x32_bf16 v[24:27], v[176:179], v[160:163], v[24:27]
	v_mfma_f32_16x16x32_bf16 v[16:19], v[210:213], v[160:163], v[16:19]
	v_mfma_f32_16x16x32_bf16 v[8:11], v[176:179], v[168:171], v[8:11]
	v_mfma_f32_16x16x32_bf16 v[0:3], v[210:213], v[168:171], v[0:3]
	v_mfma_f32_16x16x32_bf16 v[56:59], v[206:209], v[148:151], v[56:59]
	v_mfma_f32_16x16x32_bf16 v[48:51], v[214:217], v[148:151], v[48:51]
	v_mfma_f32_16x16x32_bf16 v[40:43], v[206:209], v[156:159], v[40:43]
	v_mfma_f32_16x16x32_bf16 v[32:35], v[214:217], v[156:159], v[32:35]
	v_mfma_f32_16x16x32_bf16 v[24:27], v[206:209], v[164:167], v[24:27]
	v_mfma_f32_16x16x32_bf16 v[16:19], v[214:217], v[164:167], v[16:19]
	v_mfma_f32_16x16x32_bf16 v[8:11], v[206:209], v[172:175], v[8:11]
	v_mfma_f32_16x16x32_bf16 v[0:3], v[214:217], v[172:175], v[0:3]
	s_add_i32 s79, s79, 2
	s_add_u32 s14, s14, 0x100
	s_addc_u32 s15, s15, 0
	s_add_u32 s77, s77, 0x100
	s_addc_u32 s78, s78, 0
	s_cmp_gt_u32 s79, 13
	s_barrier
	s_cbranch_scc0 .LBB0_185
	s_cmp_gt_i32 s75, 7
	s_mov_b64 s[14:15], -1
	s_cbranch_scc0 .LBB0_188
; DI void store8(bf16_t* p, f32x4 a, f32x4 b) { u32x4 w = {cvt_pk_bf16(a[0], a[1]), cvt_pk_bf16(a[2], a[3]), cvt_pk_bf16(b[0], b[1]), cvt_pk_bf16(b[2], b[3])}; *(u32x4*)p = w; }
;     DI void operator()(const AccT& acc, const pg8::Unit& u, int wr, int wc, int fr, int fq) const {
;     ...
;             bf16_t* dst = v + (pn - 8) * 256 + cl;
; #pragma unroll
;             for (int ai = 0; ai < 2; ++ai)
; #pragma unroll
;                 for (int m = 0; m < 4; ++m) { const size_t row = (size_t)pm * 256 + lrow0 + ai * 128 + m * 16;
; #pragma unroll
;                     for (int bj = 0; bj < 2; ++bj) store8(dst + row * 2048 + bj * 128, acc[ai][bj][m][0], acc[ai][bj][m][1]); }
	s_lshl_b32 s14, s75, 9
	s_mov_b32 s15, s68
	s_ashr_i32 s13, s12, 31
	v_lshl_add_u64 v[128:129], v[196:197], 0, s[14:15]
	s_lshl_b64 s[14:15], s[12:13], 20
	v_lshl_add_u64 v[128:129], v[128:129], 0, s[14:15]
	v_lshl_add_u64 v[128:129], v[128:129], 0, v[194:195]
	v_cvt_pk_bf16_f32 v130, v124, v125
	v_cvt_pk_bf16_f32 v131, v126, v127
	v_cvt_pk_bf16_f32 v132, v116, v117
	v_cvt_pk_bf16_f32 v133, v118, v119
	s_mov_b32 s1, 0xf000
	global_store_dwordx4 v[128:129], v[130:133], off offset:-4096
	v_add_co_u32_e32 v134, vcc, s1, v128
	s_nop 0
	v_cvt_pk_bf16_f32 v130, v120, v121
	v_cvt_pk_bf16_f32 v131, v122, v123
	v_cvt_pk_bf16_f32 v132, v112, v113
	v_cvt_pk_bf16_f32 v133, v114, v115
	global_store_dwordx4 v[128:129], v[130:133], off offset:-3840
	v_addc_co_u32_e32 v135, vcc, 0, v129, vcc
	s_nop 0
	v_cvt_pk_bf16_f32 v130, v108, v109
	v_cvt_pk_bf16_f32 v131, v110, v111
	v_cvt_pk_bf16_f32 v132, v100, v101
	v_cvt_pk_bf16_f32 v133, v102, v103
	s_mov_b32 s1, 0x1f000
	global_store_dwordx4 v[134:135], v[130:133], off
	s_mov_b64 s[14:15], 0
	s_nop 0
	v_cvt_pk_bf16_f32 v130, v104, v105
	v_cvt_pk_bf16_f32 v131, v106, v107
	v_cvt_pk_bf16_f32 v132, v96, v97
	v_cvt_pk_bf16_f32 v133, v98, v99
	global_store_dwordx4 v[134:135], v[130:133], off offset:256
	v_add_co_u32_e32 v134, vcc, s1, v128
	s_nop 0
	v_cvt_pk_bf16_f32 v130, v92, v93
	v_cvt_pk_bf16_f32 v131, v94, v95
	v_cvt_pk_bf16_f32 v132, v84, v85
	v_cvt_pk_bf16_f32 v133, v86, v87
	s_nop 0
	v_addc_co_u32_e32 v135, vcc, 0, v129, vcc
	s_mov_b32 s1, 0x2f000
	global_store_dwordx4 v[134:135], v[130:133], off
	s_nop 1
	v_cvt_pk_bf16_f32 v130, v88, v89
	v_cvt_pk_bf16_f32 v131, v90, v91
	v_cvt_pk_bf16_f32 v132, v80, v81
	v_cvt_pk_bf16_f32 v133, v82, v83
	global_store_dwordx4 v[134:135], v[130:133], off offset:256
	v_add_co_u32_e32 v134, vcc, s1, v128
	s_nop 0
	v_cvt_pk_bf16_f32 v130, v76, v77
	v_cvt_pk_bf16_f32 v131, v78, v79
	v_cvt_pk_bf16_f32 v132, v68, v69
	v_cvt_pk_bf16_f32 v133, v70, v71
	s_nop 0
	v_addc_co_u32_e32 v135, vcc, 0, v129, vcc
	s_mov_b32 s1, 0x7f000
	global_store_dwordx4 v[134:135], v[130:133], off
	s_nop 1
	v_cvt_pk_bf16_f32 v130, v72, v73
	v_cvt_pk_bf16_f32 v131, v74, v75
	v_cvt_pk_bf16_f32 v132, v64, v65
	v_cvt_pk_bf16_f32 v133, v66, v67
	global_store_dwordx4 v[134:135], v[130:133], off offset:256
	v_add_co_u32_e32 v134, vcc, s1, v128
	s_nop 0
	v_cvt_pk_bf16_f32 v130, v60, v61
	v_cvt_pk_bf16_f32 v131, v62, v63
	v_cvt_pk_bf16_f32 v132, v52, v53
	v_cvt_pk_bf16_f32 v133, v54, v55
	s_nop 0
	v_addc_co_u32_e32 v135, vcc, 0, v129, vcc
	s_mov_b32 s1, 0x8f000
	global_store_dwordx4 v[134:135], v[130:133], off
	s_nop 1
	v_cvt_pk_bf16_f32 v130, v56, v57
	v_cvt_pk_bf16_f32 v131, v58, v59
	v_cvt_pk_bf16_f32 v132, v48, v49
	v_cvt_pk_bf16_f32 v133, v50, v51
	global_store_dwordx4 v[134:135], v[130:133], off offset:256
	v_add_co_u32_e32 v134, vcc, s1, v128
	s_nop 0
	v_cvt_pk_bf16_f32 v130, v44, v45
	v_cvt_pk_bf16_f32 v131, v46, v47
	v_cvt_pk_bf16_f32 v132, v36, v37
	v_cvt_pk_bf16_f32 v133, v38, v39
	s_nop 0
	v_addc_co_u32_e32 v135, vcc, 0, v129, vcc
	s_mov_b32 s1, 0x9f000
	global_store_dwordx4 v[134:135], v[130:133], off
	s_nop 1
	v_cvt_pk_bf16_f32 v130, v40, v41
	v_cvt_pk_bf16_f32 v131, v42, v43
	v_cvt_pk_bf16_f32 v132, v32, v33
	v_cvt_pk_bf16_f32 v133, v34, v35
	global_store_dwordx4 v[134:135], v[130:133], off offset:256
	v_add_co_u32_e32 v134, vcc, s1, v128
	s_nop 0
	v_cvt_pk_bf16_f32 v130, v28, v29
	v_cvt_pk_bf16_f32 v131, v30, v31
	v_cvt_pk_bf16_f32 v132, v20, v21
	v_cvt_pk_bf16_f32 v133, v22, v23
	s_nop 0
	v_addc_co_u32_e32 v135, vcc, 0, v129, vcc
	s_mov_b32 s1, 0xaf000
	global_store_dwordx4 v[134:135], v[130:133], off
	s_nop 1
	v_cvt_pk_bf16_f32 v130, v24, v25
	v_cvt_pk_bf16_f32 v131, v26, v27
	v_cvt_pk_bf16_f32 v132, v16, v17
	v_cvt_pk_bf16_f32 v133, v18, v19
	global_store_dwordx4 v[134:135], v[130:133], off offset:256
	v_add_co_u32_e32 v134, vcc, s1, v128
	s_nop 0
	v_cvt_pk_bf16_f32 v130, v12, v13
	v_cvt_pk_bf16_f32 v131, v14, v15
	v_cvt_pk_bf16_f32 v132, v4, v5
	v_cvt_pk_bf16_f32 v133, v6, v7
	s_nop 0
	v_addc_co_u32_e32 v135, vcc, 0, v129, vcc
	global_store_dwordx4 v[134:135], v[130:133], off
	v_cvt_pk_bf16_f32 v128, v8, v9
	v_cvt_pk_bf16_f32 v129, v10, v11
	s_nop 1
	v_cvt_pk_bf16_f32 v130, v0, v1
	v_cvt_pk_bf16_f32 v131, v2, v3
	global_store_dwordx4 v[134:135], v[128:131], off offset:256

; #define PG8_STAGE(bufoff, gbase, voff) do { _Pragma("unroll") for (int _i = 0; _i < 2; ++_i) \
;         __builtin_amdgcn_global_load_lds((const unsigned*)((const char*)(gbase) + (voff)[_i]), (PG8_LAS unsigned*)(lds + (bufoff) + ldsw + _i * 8192), 16, 0, 0); } while (0)
; #define PG8_LDA(dst, b, h) do { _Pragma("unroll") for (int m = 0; m < 4; ++m) _Pragma("unroll") for (int k = 0; k < 2; ++k) dst[m][k] = *(const PG8_LAS bf16x8*)(lds + PG8_SA(b, h) + aoff + m * 2048 + k * 1024); } while (0)
; #define PG8_LDB(dst, b, h) do { _Pragma("unroll") for (int n = 0; n < 2; ++n) _Pragma("unroll") for (int k = 0; k < 2; ++k) dst[n][k] = *(const PG8_LAS bf16x8*)(lds + PG8_SB(b, h) + boff + n * 2048 + k * 1024); } while (0)
; #define PG8_MMA(ai, bj, At, Bt) do { __builtin_amdgcn_s_setprio(1); _Pragma("unroll") for (int m = 0; m < 4; ++m) _Pragma("unroll") for (int n = 0; n < 2; ++n) _Pragma("unroll") for (int k = 0; k < 2; ++k) \
;         acc[ai][bj][m][n] = __builtin_amdgcn_mfma_f32_16x16x32_bf16(Bt[n][k], At[m][k], acc[ai][bj][m][n], 0, 0, 0); __builtin_amdgcn_s_setprio(0); } while (0)
; #define PG8_WAIT_L(n) asm volatile("s_waitcnt lgkmcnt(" #n ")" ::: "memory")
; #define PG8_BAR __builtin_amdgcn_s_barrier()
; #define PG8_SCHED __builtin_amdgcn_sched_barrier(0)
; template <class Epi, class Sched>
; __device__ __forceinline__ void gemm_phase(PG8_LAS unsigned char* lds, const Gemm g, const Sched& S, const Epi& E) {
;     ...
;             PG8_LDB(B0, 0, 0); PG8_SCHED; PG8_LDA(At, 0, 0); PG8_STAGE(PG8_SA(1, 1), a1 + hstep, voffA);
;             PG8_WAIT_L(8); PG8_BAR; PG8_WAIT_L(0); PG8_MMA(0, 0, At, B0); PG8_BAR; PG8_SCHED;
;             PG8_LDB(B1, 0, 1); PG8_STAGE(PG8_SB(0, 0), b2, voffB);
;             PG8_BAR; PG8_WAIT_L(0); PG8_MMA(0, 1, At, B1); PG8_BAR;
;             PG8_LDA(At, 0, 1); PG8_STAGE(PG8_SA(0, 0), a2, voffA);
;             PG8_BAR; PG8_WAIT_L(0); PG8_MMA(1, 0, At, B0); PG8_BAR; PG8_SCHED;
.LBB0_516:
	s_add_u32 s70, s20, 0xfffc0080
	s_addc_u32 s71, s21, -1
	s_add_i32 vcc_lo, 0, 0x10000
	v_add_u32_e32 v68, vcc_lo, v206
	ds_read_b128 v[48:51], v68
	ds_read_b128 v[56:59], v68 offset:1024
	ds_read_b128 v[60:63], v68 offset:2048
	ds_read_b128 v[68:71], v68 offset:3072
	s_cmp_eq_u32 s89, 12
	s_cselect_b32 s73, s11, s71
	s_cselect_b32 s72, s17, s70
	s_cselect_b32 s71, s9, s88
	s_cselect_b32 s70, s82, s83
	v_lshl_add_u64 v[192:193], s[20:21], 0, v[176:177]
	s_add_i32 m0, s19, 0xc000
	ds_read_b128 v[128:131], v208
	ds_read_b128 v[140:143], v208 offset:1024
	ds_read_b128 v[148:151], v208 offset:2048
	ds_read_b128 v[156:159], v208 offset:3072
	ds_read_b128 v[160:163], v208 offset:4096
	ds_read_b128 v[164:167], v208 offset:5120
	ds_read_b128 v[184:187], v208 offset:6144
	ds_read_b128 v[188:191], v208 offset:7168
	global_load_lds_dwordx4 v[192:193], off
	v_lshl_add_u64 v[192:193], s[20:21], 0, v[178:179]
	s_add_i32 m0, s19, 0xe000
	s_nop 0
	global_load_lds_dwordx4 v[192:193], off
	s_waitcnt lgkmcnt(8)
	s_barrier
	s_waitcnt lgkmcnt(0)
	v_mfma_f32_16x16x32_bf16 v[152:155], v[48:51], v[128:131], v[152:155]
	v_mfma_f32_16x16x32_bf16 v[144:147], v[60:63], v[128:131], v[144:147]
	v_mfma_f32_16x16x32_bf16 v[124:127], v[48:51], v[148:151], v[124:127]
	v_mfma_f32_16x16x32_bf16 v[120:123], v[60:63], v[148:151], v[120:123]
	v_mfma_f32_16x16x32_bf16 v[108:111], v[48:51], v[160:163], v[108:111]
	v_mfma_f32_16x16x32_bf16 v[104:107], v[60:63], v[160:163], v[104:107]
	v_mfma_f32_16x16x32_bf16 v[92:95], v[48:51], v[184:187], v[92:95]
	v_mfma_f32_16x16x32_bf16 v[88:91], v[60:63], v[184:187], v[88:91]
	v_mfma_f32_16x16x32_bf16 v[152:155], v[56:59], v[140:143], v[152:155]
	v_mfma_f32_16x16x32_bf16 v[144:147], v[68:71], v[140:143], v[144:147]
	v_mfma_f32_16x16x32_bf16 v[124:127], v[56:59], v[156:159], v[124:127]
	v_mfma_f32_16x16x32_bf16 v[120:123], v[68:71], v[156:159], v[120:123]
	v_mfma_f32_16x16x32_bf16 v[108:111], v[56:59], v[164:167], v[108:111]
	v_mfma_f32_16x16x32_bf16 v[104:107], v[68:71], v[164:167], v[104:107]
	v_mfma_f32_16x16x32_bf16 v[92:95], v[56:59], v[188:191], v[92:95]
	v_mfma_f32_16x16x32_bf16 v[88:91], v[68:71], v[188:191], v[88:91]
	s_barrier
	s_add_i32 s69, 0, 0x14000
	v_add_u32_e32 v204, s69, v206
	s_add_i32 vcc_lo, vcc_lo, s74
	ds_read_b128 v[192:195], v204
	ds_read_b128 v[196:199], v204 offset:1024
	ds_read_b128 v[200:203], v204 offset:2048
	ds_read_b128 v[210:213], v204 offset:3072
	v_lshl_add_u64 v[204:205], s[70:71], 0, v[180:181]
	s_mov_b32 m0, vcc_lo
	v_lshl_add_u64 v[214:215], s[70:71], 0, v[168:169]
	global_load_lds_dwordx4 v[204:205], off
	s_add_i32 m0, vcc_lo, 0x2000
	s_nop 0
	global_load_lds_dwordx4 v[214:215], off
	s_barrier
	s_waitcnt lgkmcnt(0)
	v_mfma_f32_16x16x32_bf16 v[136:139], v[192:195], v[128:131], v[136:139]
	v_mfma_f32_16x16x32_bf16 v[116:119], v[192:195], v[148:151], v[116:119]
	v_mfma_f32_16x16x32_bf16 v[112:115], v[200:203], v[148:151], v[112:115]
	v_mfma_f32_16x16x32_bf16 v[100:103], v[192:195], v[160:163], v[100:103]
	v_mfma_f32_16x16x32_bf16 v[96:99], v[200:203], v[160:163], v[96:99]
	v_mfma_f32_16x16x32_bf16 v[84:87], v[192:195], v[184:187], v[84:87]
	v_mfma_f32_16x16x32_bf16 v[80:83], v[200:203], v[184:187], v[80:83]
	v_mfma_f32_16x16x32_bf16 v[136:139], v[196:199], v[140:143], v[136:139]
	v_mfma_f32_16x16x32_bf16 v[128:131], v[200:203], v[128:131], v[132:135]
	v_mfma_f32_16x16x32_bf16 v[116:119], v[196:199], v[156:159], v[116:119]
	v_mfma_f32_16x16x32_bf16 v[112:115], v[210:213], v[156:159], v[112:115]
	v_mfma_f32_16x16x32_bf16 v[100:103], v[196:199], v[164:167], v[100:103]
	v_mfma_f32_16x16x32_bf16 v[96:99], v[210:213], v[164:167], v[96:99]
	v_mfma_f32_16x16x32_bf16 v[84:87], v[196:199], v[188:191], v[84:87]
	v_mfma_f32_16x16x32_bf16 v[80:83], v[210:213], v[188:191], v[80:83]
	v_mfma_f32_16x16x32_bf16 v[128:131], v[210:213], v[140:143], v[128:131]
	s_mov_b32 m0, s19
	v_lshl_add_u64 v[216:217], s[72:73], 0, v[172:173]
	s_barrier
	ds_read_b128 v[132:135], v208 offset:16384
	ds_read_b128 v[140:143], v208 offset:17408
	ds_read_b128 v[148:151], v208 offset:18432
	ds_read_b128 v[156:159], v208 offset:19456
	ds_read_b128 v[160:163], v208 offset:20480
	ds_read_b128 v[164:167], v208 offset:21504
	ds_read_b128 v[184:187], v208 offset:22528
	ds_read_b128 v[188:191], v208 offset:23552
	global_load_lds_dwordx4 v[216:217], off
	v_lshl_add_u64 v[218:219], s[72:73], 0, v[170:171]
	s_mov_b32 m0, s76
	s_nop 0
	global_load_lds_dwordx4 v[218:219], off
	s_barrier
	s_waitcnt lgkmcnt(0)
	v_mfma_f32_16x16x32_bf16 v[76:79], v[48:51], v[132:135], v[76:79]
	v_mfma_f32_16x16x32_bf16 v[72:75], v[60:63], v[132:135], v[72:75]
	v_mfma_f32_16x16x32_bf16 v[44:47], v[48:51], v[148:151], v[44:47]
	v_mfma_f32_16x16x32_bf16 v[40:43], v[60:63], v[148:151], v[40:43]
	v_mfma_f32_16x16x32_bf16 v[28:31], v[48:51], v[160:163], v[28:31]
	v_mfma_f32_16x16x32_bf16 v[24:27], v[60:63], v[160:163], v[24:27]
	v_mfma_f32_16x16x32_bf16 v[12:15], v[48:51], v[184:187], v[12:15]
	v_mfma_f32_16x16x32_bf16 v[8:11], v[60:63], v[184:187], v[8:11]
	v_mfma_f32_16x16x32_bf16 v[76:79], v[56:59], v[140:143], v[76:79]
	v_mfma_f32_16x16x32_bf16 v[72:75], v[68:71], v[140:143], v[72:75]
	v_mfma_f32_16x16x32_bf16 v[44:47], v[56:59], v[156:159], v[44:47]
	v_mfma_f32_16x16x32_bf16 v[40:43], v[68:71], v[156:159], v[40:43]
	v_mfma_f32_16x16x32_bf16 v[28:31], v[56:59], v[164:167], v[28:31]
	v_mfma_f32_16x16x32_bf16 v[24:27], v[68:71], v[164:167], v[24:27]
	v_mfma_f32_16x16x32_bf16 v[12:15], v[56:59], v[188:191], v[12:15]
	v_mfma_f32_16x16x32_bf16 v[8:11], v[68:71], v[188:191], v[8:11]
	s_barrier
; #define PG8_STAGE(bufoff, gbase, voff) do { _Pragma("unroll") for (int _i = 0; _i < 2; ++_i) \
;         __builtin_amdgcn_global_load_lds((const unsigned*)((const char*)(gbase) + (voff)[_i]), (PG8_LAS unsigned*)(lds + (bufoff) + ldsw + _i * 8192), 16, 0, 0); } while (0)
; #define PG8_LDA(dst, b, h) do { _Pragma("unroll") for (int m = 0; m < 4; ++m) _Pragma("unroll") for (int k = 0; k < 2; ++k) dst[m][k] = *(const PG8_LAS bf16x8*)(lds + PG8_SA(b, h) + aoff + m * 2048 + k * 1024); } while (0)
; #define PG8_LDB(dst, b, h) do { _Pragma("unroll") for (int n = 0; n < 2; ++n) _Pragma("unroll") for (int k = 0; k < 2; ++k) dst[n][k] = *(const PG8_LAS bf16x8*)(lds + PG8_SB(b, h) + boff + n * 2048 + k * 1024); } while (0)
; #define PG8_MMA(ai, bj, At, Bt) do { __builtin_amdgcn_s_setprio(1); _Pragma("unroll") for (int m = 0; m < 4; ++m) _Pragma("unroll") for (int n = 0; n < 2; ++n) _Pragma("unroll") for (int k = 0; k < 2; ++k) \
;         acc[ai][bj][m][n] = __builtin_amdgcn_mfma_f32_16x16x32_bf16(Bt[n][k], At[m][k], acc[ai][bj][m][n], 0, 0, 0); __builtin_amdgcn_s_setprio(0); } while (0)
; #define PG8_WAIT_V(n) asm volatile("s_waitcnt vmcnt(" #n ")" ::: "memory")
; #define PG8_WAIT_L(n) asm volatile("s_waitcnt lgkmcnt(" #n ")" ::: "memory")
; #define PG8_BAR __builtin_amdgcn_s_barrier()
; #define PG8_SCHED __builtin_amdgcn_sched_barrier(0)
; template <class Epi, class Sched>
; __device__ __forceinline__ void gemm_phase(PG8_LAS unsigned char* lds, const Gemm g, const Sched& S, const Epi& E) {
;     ...
;             PG8_STAGE(PG8_SB(0, 1), b2 + hstep, voffB);
;             PG8_WAIT_V(6); PG8_BAR; PG8_MMA(1, 1, At, B1); PG8_BAR;
;             PG8_LDB(B0, 1, 0); PG8_SCHED; PG8_LDA(At, 1, 0); PG8_STAGE(PG8_SA(0, 1), a2 + hstep, voffA);
;             PG8_WAIT_L(8); PG8_BAR; PG8_WAIT_L(0); PG8_MMA(0, 0, At, B0); PG8_BAR; PG8_SCHED;
;             PG8_LDB(B1, 1, 1); PG8_STAGE(PG8_SB(1, 0), b3, voffB);
;             PG8_BAR; PG8_WAIT_L(0); PG8_MMA(0, 1, At, B1); PG8_BAR;
;             PG8_LDA(At, 1, 1); PG8_STAGE(PG8_SA(1, 0), a3, voffA);
;             PG8_BAR; PG8_WAIT_L(0); PG8_MMA(1, 0, At, B0); PG8_BAR; PG8_SCHED;
	s_add_u32 vcc_lo, s70, 0x40000
	s_addc_u32 vcc_hi, s71, 0
	s_add_i32 s69, s69, s74
	v_lshl_add_u64 v[48:49], vcc, 0, v[180:181]
	s_mov_b32 m0, s69
	s_nop 0
	global_load_lds_dwordx4 v[48:49], off
	v_lshl_add_u64 v[48:49], vcc, 0, v[168:169]
	s_add_i32 m0, s69, 0x2000
	s_nop 0
	global_load_lds_dwordx4 v[48:49], off
	s_waitcnt vmcnt(6)
	s_barrier
	v_mfma_f32_16x16x32_bf16 v[52:55], v[200:203], v[132:135], v[52:55]
	v_mfma_f32_16x16x32_bf16 v[36:39], v[192:195], v[148:151], v[36:39]
	v_mfma_f32_16x16x32_bf16 v[32:35], v[200:203], v[148:151], v[32:35]
	v_mfma_f32_16x16x32_bf16 v[20:23], v[192:195], v[160:163], v[20:23]
	v_mfma_f32_16x16x32_bf16 v[16:19], v[200:203], v[160:163], v[16:19]
	v_mfma_f32_16x16x32_bf16 v[4:7], v[192:195], v[184:187], v[4:7]
	v_mfma_f32_16x16x32_bf16 v[0:3], v[200:203], v[184:187], v[0:3]
	v_mfma_f32_16x16x32_bf16 v[48:51], v[192:195], v[132:135], v[64:67]
	v_mfma_f32_16x16x32_bf16 v[52:55], v[210:213], v[140:143], v[52:55]
	v_mfma_f32_16x16x32_bf16 v[36:39], v[196:199], v[156:159], v[36:39]
	v_mfma_f32_16x16x32_bf16 v[32:35], v[210:213], v[156:159], v[32:35]
	v_mfma_f32_16x16x32_bf16 v[20:23], v[196:199], v[164:167], v[20:23]
	v_mfma_f32_16x16x32_bf16 v[16:19], v[210:213], v[164:167], v[16:19]
	v_mfma_f32_16x16x32_bf16 v[4:7], v[196:199], v[188:191], v[4:7]
	v_mfma_f32_16x16x32_bf16 v[0:3], v[210:213], v[188:191], v[0:3]
	v_mfma_f32_16x16x32_bf16 v[48:51], v[196:199], v[140:143], v[48:51]
	s_add_i32 s69, 0, 0x18000
	v_add_u32_e32 v68, s69, v206
	s_barrier
	ds_read_b128 v[56:59], v68
	ds_read_b128 v[60:63], v68 offset:1024
	ds_read_b128 v[64:67], v68 offset:2048
	ds_read_b128 v[68:71], v68 offset:3072
	s_add_u32 s72, s72, 0x40000
	s_addc_u32 s73, s73, 0
	s_mov_b32 m0, s77
	v_lshl_add_u64 v[192:193], s[72:73], 0, v[172:173]
	ds_read_b128 v[132:135], v208 offset:32768
	ds_read_b128 v[140:143], v208 offset:33792
	ds_read_b128 v[148:151], v208 offset:34816
	ds_read_b128 v[156:159], v208 offset:35840
	ds_read_b128 v[160:163], v208 offset:36864
	ds_read_b128 v[164:167], v208 offset:37888
	ds_read_b128 v[184:187], v208 offset:38912
	ds_read_b128 v[188:191], v208 offset:39936
	global_load_lds_dwordx4 v[192:193], off
	v_lshl_add_u64 v[192:193], s[72:73], 0, v[170:171]
	s_mov_b32 m0, s78
	s_nop 0
	global_load_lds_dwordx4 v[192:193], off
	s_waitcnt lgkmcnt(8)
	s_barrier
	s_waitcnt lgkmcnt(0)
	v_mfma_f32_16x16x32_bf16 v[152:155], v[56:59], v[132:135], v[152:155]
	v_mfma_f32_16x16x32_bf16 v[144:147], v[64:67], v[132:135], v[144:147]
	v_mfma_f32_16x16x32_bf16 v[124:127], v[56:59], v[148:151], v[124:127]
	v_mfma_f32_16x16x32_bf16 v[120:123], v[64:67], v[148:151], v[120:123]
	v_mfma_f32_16x16x32_bf16 v[108:111], v[56:59], v[160:163], v[108:111]
	v_mfma_f32_16x16x32_bf16 v[104:107], v[64:67], v[160:163], v[104:107]
	v_mfma_f32_16x16x32_bf16 v[92:95], v[56:59], v[184:187], v[92:95]
	v_mfma_f32_16x16x32_bf16 v[88:91], v[64:67], v[184:187], v[88:91]
	v_mfma_f32_16x16x32_bf16 v[152:155], v[60:63], v[140:143], v[152:155]
	v_mfma_f32_16x16x32_bf16 v[144:147], v[68:71], v[140:143], v[144:147]
	v_mfma_f32_16x16x32_bf16 v[124:127], v[60:63], v[156:159], v[124:127]
	v_mfma_f32_16x16x32_bf16 v[120:123], v[68:71], v[156:159], v[120:123]
	v_mfma_f32_16x16x32_bf16 v[108:111], v[60:63], v[164:167], v[108:111]
	v_mfma_f32_16x16x32_bf16 v[104:107], v[68:71], v[164:167], v[104:107]
	v_mfma_f32_16x16x32_bf16 v[92:95], v[60:63], v[188:191], v[92:95]
	v_mfma_f32_16x16x32_bf16 v[88:91], v[68:71], v[188:191], v[88:91]
	s_barrier
	s_add_i32 s72, 0, 0x1c000
	s_add_i32 s69, s69, s74
	v_add_u32_e32 v209, s72, v206
	v_lshl_add_u64 v[204:205], v[204:205], 0, s[38:39]
	s_mov_b32 m0, s69
	ds_read_b128 v[192:195], v209
	ds_read_b128 v[196:199], v209 offset:1024
	ds_read_b128 v[200:203], v209 offset:2048
	ds_read_b128 v[210:213], v209 offset:3072
	global_load_lds_dwordx4 v[204:205], off
	v_lshl_add_u64 v[204:205], v[214:215], 0, s[38:39]
	s_add_i32 m0, s69, 0x2000
	s_nop 0
	global_load_lds_dwordx4 v[204:205], off
	s_barrier
	s_waitcnt lgkmcnt(0)
	v_mfma_f32_16x16x32_bf16 v[136:139], v[192:195], v[132:135], v[136:139]
	v_mfma_f32_16x16x32_bf16 v[128:131], v[200:203], v[132:135], v[128:131]
	v_mfma_f32_16x16x32_bf16 v[116:119], v[192:195], v[148:151], v[116:119]
	v_mfma_f32_16x16x32_bf16 v[112:115], v[200:203], v[148:151], v[112:115]
	v_mfma_f32_16x16x32_bf16 v[100:103], v[192:195], v[160:163], v[100:103]
	v_mfma_f32_16x16x32_bf16 v[96:99], v[200:203], v[160:163], v[96:99]
	v_mfma_f32_16x16x32_bf16 v[84:87], v[192:195], v[184:187], v[84:87]
	v_mfma_f32_16x16x32_bf16 v[80:83], v[200:203], v[184:187], v[80:83]
	v_mfma_f32_16x16x32_bf16 v[136:139], v[196:199], v[140:143], v[136:139]
	v_mfma_f32_16x16x32_bf16 v[132:135], v[210:213], v[140:143], v[128:131]
	v_mfma_f32_16x16x32_bf16 v[116:119], v[196:199], v[156:159], v[116:119]
	v_mfma_f32_16x16x32_bf16 v[112:115], v[210:213], v[156:159], v[112:115]
	v_mfma_f32_16x16x32_bf16 v[100:103], v[196:199], v[164:167], v[100:103]
	v_mfma_f32_16x16x32_bf16 v[96:99], v[210:213], v[164:167], v[96:99]
	v_mfma_f32_16x16x32_bf16 v[84:87], v[196:199], v[188:191], v[84:87]
	v_mfma_f32_16x16x32_bf16 v[80:83], v[210:213], v[188:191], v[80:83]
	s_mov_b32 m0, s79
	v_lshl_add_u64 v[204:205], v[216:217], 0, s[38:39]
	s_barrier
	ds_read_b128 v[128:131], v208 offset:49152
	ds_read_b128 v[140:143], v208 offset:50176
	ds_read_b128 v[148:151], v208 offset:51200
	ds_read_b128 v[156:159], v208 offset:52224
	ds_read_b128 v[160:163], v208 offset:53248
	ds_read_b128 v[164:167], v208 offset:54272
	ds_read_b128 v[184:187], v208 offset:55296
	ds_read_b128 v[188:191], v208 offset:56320
	global_load_lds_dwordx4 v[204:205], off
	v_lshl_add_u64 v[204:205], v[218:219], 0, s[38:39]
	s_mov_b32 m0, s80
	s_nop 0
	global_load_lds_dwordx4 v[204:205], off
	s_barrier
; #define PG8_STAGE(bufoff, gbase, voff) do { _Pragma("unroll") for (int _i = 0; _i < 2; ++_i) \
;         __builtin_amdgcn_global_load_lds((const unsigned*)((const char*)(gbase) + (voff)[_i]), (PG8_LAS unsigned*)(lds + (bufoff) + ldsw + _i * 8192), 16, 0, 0); } while (0)
; #define PG8_LDA(dst, b, h) do { _Pragma("unroll") for (int m = 0; m < 4; ++m) _Pragma("unroll") for (int k = 0; k < 2; ++k) dst[m][k] = *(const PG8_LAS bf16x8*)(lds + PG8_SA(b, h) + aoff + m * 2048 + k * 1024); } while (0)
; #define PG8_WAIT_V(n) asm volatile("s_waitcnt vmcnt(" #n ")" ::: "memory")
; #define PG8_WAIT_L(n) asm volatile("s_waitcnt lgkmcnt(" #n ")" ::: "memory")
; template <class Epi, class Sched>
; __device__ __forceinline__ void gemm_phase(PG8_LAS unsigned char* lds, const Gemm g, const Sched& S, const Epi& E) {
;     ...
;             PG8_WAIT_V(6); PG8_BAR; PG8_MMA(1, 1, At, B1); PG8_BAR;
;             PG8_LDB(B0, 1, 0); PG8_SCHED; PG8_LDA(At, 1, 0); PG8_STAGE(PG8_SA(0, 1), a2 + hstep, voffA);
;             PG8_WAIT_L(8); PG8_BAR; PG8_WAIT_L(0); PG8_MMA(0, 0, At, B0); PG8_BAR; PG8_SCHED;
;             PG8_LDB(B1, 1, 1); PG8_STAGE(PG8_SB(1, 0), b3, voffB);
;             PG8_BAR; PG8_WAIT_L(0); PG8_MMA(0, 1, At, B1); PG8_BAR;
;             PG8_LDA(At, 1, 1); PG8_STAGE(PG8_SA(1, 0), a3, voffA);
;             PG8_BAR; PG8_WAIT_L(0); PG8_MMA(1, 0, At, B0); PG8_BAR; PG8_SCHED;
;             PG8_STAGE(PG8_SB(1, 1), b3 + hstep, voffB);
;             PG8_WAIT_V(6); PG8_BAR; PG8_MMA(1, 1, At, B1); PG8_BAR;
;         }
;         E(acc, cur, wr, wc, fr, fq); S.done(cur);
;     DI void operator()(const AccT& acc, const pg8::Unit& u, int wr, int wc, int fr, int fq) const {
;         const int col0 = u.pn * 256 + wc * 32 + 8 * fq, head = u.pn >> 1;
;         f32x4 g0[2], g1[2];
; #pragma unroll
;         for (int bj = 0; bj < 2; ++bj) { g0[bj] = *(const f32x4*)(gn + col0 + bj * 128); g1[bj] = *(const f32x4*)(gn + col0 + bj * 128 + 4); }
; #pragma unroll
;         for (int ai = 0; ai < 2; ++ai) {
;             float2 st[4]; u32x4 ov[4][2];
; #pragma unroll
;             for (int m = 0; m < 4; ++m) { const size_t row = (size_t)u.pm * 256 + wr * 64 + fr + ai * 128 + m * 16;
;                 st[m] = *(const float2*)(stats + (row * 4 + head) * 2);
; #pragma unroll
;                 for (int bj = 0; bj < 2; ++bj) ov[m][bj] = *(const u32x4*)(o + row * 2048 + col0 + bj * 128); }
	s_waitcnt lgkmcnt(0)
	v_mfma_f32_16x16x32_bf16 v[76:79], v[56:59], v[128:131], v[76:79]
	v_mfma_f32_16x16x32_bf16 v[72:75], v[64:67], v[128:131], v[72:75]
	v_mfma_f32_16x16x32_bf16 v[44:47], v[56:59], v[148:151], v[44:47]
	v_mfma_f32_16x16x32_bf16 v[40:43], v[64:67], v[148:151], v[40:43]
	v_mfma_f32_16x16x32_bf16 v[28:31], v[56:59], v[160:163], v[28:31]
	v_mfma_f32_16x16x32_bf16 v[24:27], v[64:67], v[160:163], v[24:27]
	v_mfma_f32_16x16x32_bf16 v[12:15], v[56:59], v[184:187], v[12:15]
	v_mfma_f32_16x16x32_bf16 v[8:11], v[64:67], v[184:187], v[8:11]
	v_mfma_f32_16x16x32_bf16 v[76:79], v[60:63], v[140:143], v[76:79]
	v_mfma_f32_16x16x32_bf16 v[72:75], v[68:71], v[140:143], v[72:75]
	v_mfma_f32_16x16x32_bf16 v[44:47], v[60:63], v[156:159], v[44:47]
	v_mfma_f32_16x16x32_bf16 v[40:43], v[68:71], v[156:159], v[40:43]
	v_mfma_f32_16x16x32_bf16 v[28:31], v[60:63], v[164:167], v[28:31]
	v_mfma_f32_16x16x32_bf16 v[24:27], v[68:71], v[164:167], v[24:27]
	v_mfma_f32_16x16x32_bf16 v[12:15], v[60:63], v[188:191], v[12:15]
	v_mfma_f32_16x16x32_bf16 v[8:11], v[68:71], v[188:191], v[8:11]
	s_barrier
	s_add_u32 s70, s70, 0x40080
	s_addc_u32 s71, s71, 0
	s_add_i32 s69, s72, s74
	v_lshl_add_u64 v[56:57], s[70:71], 0, v[180:181]
	s_mov_b32 m0, s69
	s_nop 0
	global_load_lds_dwordx4 v[56:57], off
	v_lshl_add_u64 v[56:57], s[70:71], 0, v[168:169]
	s_add_i32 m0, s69, 0x2000
	s_nop 0
	global_load_lds_dwordx4 v[56:57], off
	s_waitcnt vmcnt(6)
	s_barrier
	v_mfma_f32_16x16x32_bf16 v[48:51], v[192:195], v[128:131], v[48:51]
	v_mfma_f32_16x16x32_bf16 v[64:67], v[196:199], v[140:143], v[48:51]
	v_mfma_f32_16x16x32_bf16 v[48:51], v[200:203], v[128:131], v[52:55]
	v_mfma_f32_16x16x32_bf16 v[36:39], v[192:195], v[148:151], v[36:39]
	v_mfma_f32_16x16x32_bf16 v[32:35], v[200:203], v[148:151], v[32:35]
	v_mfma_f32_16x16x32_bf16 v[20:23], v[192:195], v[160:163], v[20:23]
	v_mfma_f32_16x16x32_bf16 v[16:19], v[200:203], v[160:163], v[16:19]
	v_mfma_f32_16x16x32_bf16 v[4:7], v[192:195], v[184:187], v[4:7]
	v_mfma_f32_16x16x32_bf16 v[0:3], v[200:203], v[184:187], v[0:3]
	v_mfma_f32_16x16x32_bf16 v[52:55], v[210:213], v[140:143], v[48:51]
	v_mfma_f32_16x16x32_bf16 v[36:39], v[196:199], v[156:159], v[36:39]
	v_mfma_f32_16x16x32_bf16 v[32:35], v[210:213], v[156:159], v[32:35]
	v_mfma_f32_16x16x32_bf16 v[20:23], v[196:199], v[164:167], v[20:23]
	v_mfma_f32_16x16x32_bf16 v[16:19], v[210:213], v[164:167], v[16:19]
	v_mfma_f32_16x16x32_bf16 v[4:7], v[196:199], v[188:191], v[4:7]
	v_mfma_f32_16x16x32_bf16 v[0:3], v[210:213], v[188:191], v[0:3]
	s_add_i32 s89, s89, 2
	s_add_u32 s20, s20, 0x100
	s_addc_u32 s21, s21, 0
	s_add_u32 s83, s83, 0x100
	s_addc_u32 s88, s88, 0
	s_cmp_gt_u32 s89, 13
	s_barrier
	s_cbranch_scc0 .LBB0_516
	v_lshl_or_b32 v48, s18, 8, v207
	s_ashr_i32 s20, s18, 1
	s_ashr_i32 s17, s16, 31
	v_ashrrev_i32_e32 v49, 31, v48
	s_lshl_b64 s[16:17], s[16:17], 8
	s_ashr_i32 s21, s20, 31
	v_lshl_add_u64 v[188:189], s[16:17], 0, v[174:175]
	s_lshl_b64 s[16:17], s[20:21], 3
	v_lshlrev_b64 v[184:185], 1, v[48:49]
	s_add_u32 s16, s60, s16
	v_lshl_add_u64 v[186:187], s[96:97], 0, v[184:185]
	v_lshlrev_b64 v[128:129], 12, v[188:189]
	v_lshl_add_u64 v[56:57], v[48:49], 2, s[6:7]
	s_addc_u32 s17, s61, s17
	v_lshlrev_b64 v[48:49], 5, v[188:189]
	v_lshl_add_u64 v[130:131], v[186:187], 0, v[128:129]
	global_load_dwordx4 v[60:63], v[56:57], off
	v_lshl_add_u64 v[48:49], s[16:17], 0, v[48:49]
	global_load_dwordx4 v[210:213], v[130:131], off
	global_load_dwordx2 v[204:205], v[48:49], off
	v_mul_f32_e32 v48, 0xbfb8aa3b, v152
	v_mul_f32_e32 v49, 0xbfb8aa3b, v153
	v_mul_f32_e32 v50, 0xbfb8aa3b, v154
	v_mul_f32_e32 v51, 0xbfb8aa3b, v155
	v_mul_f32_e32 v58, 0xbfb8aa3b, v144
	v_mul_f32_e32 v59, 0xbfb8aa3b, v145
	v_mul_f32_e32 v68, 0xbfb8aa3b, v146
	v_mul_f32_e32 v69, 0xbfb8aa3b, v147
	v_mov_b32_e32 v214, v152
	v_exp_f32_e32 v152, v48
	v_exp_f32_e32 v156, v49
	v_exp_f32_e32 v157, v50
	v_exp_f32_e32 v158, v51
	v_exp_f32_e32 v159, v58
	v_exp_f32_e32 v160, v59
	v_exp_f32_e32 v161, v68
	v_exp_f32_e32 v162, v69
	global_load_dwordx4 v[68:71], v[56:57], off offset:16
	global_load_dwordx4 v[48:51], v[56:57], off offset:528
	s_nop 0
	global_load_dwordx4 v[56:59], v[56:57], off offset:512
	v_add_f32_e32 v209, 1.0, v156
	global_load_dwordx4 v[164:167], v[130:131], off offset:256
	v_rcp_f32_e32 v220, v209
	v_or_b32_e32 v140, 16, v188
	v_mov_b32_e32 v141, v189
	v_or_b32_e32 v148, 48, v188
	v_mov_b32_e32 v149, v189
	v_or_b32_e32 v142, 32, v188
	v_mov_b32_e32 v143, v189
	v_lshlrev_b64 v[202:203], 12, v[140:141]
	v_lshlrev_b64 v[190:191], 12, v[148:149]
	v_lshlrev_b64 v[150:151], 5, v[140:141]
	v_lshlrev_b64 v[140:141], 5, v[142:143]
	v_lshlrev_b64 v[196:197], 12, v[142:143]
	v_lshlrev_b64 v[142:143], 5, v[148:149]
	v_lshl_add_u64 v[128:129], s[96:97], 0, v[128:129]
	v_lshl_add_u64 v[130:131], v[186:187], 0, v[202:203]
	v_lshl_add_u64 v[218:219], v[186:187], 0, v[190:191]
	v_add_f32_e32 v152, 1.0, v152
	v_lshl_add_u64 v[216:217], s[16:17], 0, v[150:151]
	v_lshl_add_u64 v[198:199], s[16:17], 0, v[140:141]
	v_lshl_add_u64 v[200:201], v[186:187], 0, v[196:197]
	v_lshl_add_u64 v[194:195], s[16:17], 0, v[142:143]
	v_lshl_add_u64 v[192:193], v[128:129], 0, v[184:185]
	v_add_f32_e32 v215, 1.0, v157
	v_add_f32_e32 v221, 1.0, v158
	v_add_f32_e32 v223, 1.0, v159
	v_add_f32_e32 v225, 1.0, v160
	v_add_f32_e32 v227, 1.0, v161
	v_add_f32_e32 v229, 1.0, v162
	global_load_dwordx4 v[160:163], v[130:131], off
	global_load_dwordx4 v[156:159], v[130:131], off offset:256
	global_load_dwordx4 v[148:151], v[200:201], off offset:256
	global_load_dwordx4 v[140:143], v[218:219], off
	s_nop 0
	global_load_dwordx4 v[128:131], v[218:219], off offset:256
	v_rcp_f32_e32 v218, v152
	v_rcp_f32_e32 v224, v221
	v_rcp_f32_e32 v226, v223
	v_rcp_f32_e32 v228, v225
	v_rcp_f32_e32 v232, v227
	v_rcp_f32_e32 v234, v229
	v_rcp_f32_e32 v222, v215
	s_mov_b64 s[20:21], 0x90
	s_mov_b32 s18, s8
	s_mov_b64 s[70:71], s[14:15]
	s_waitcnt vmcnt(0)
; DI float bflo(unsigned w) { return __uint_as_float(w << 16); }
; DI float bfhi(unsigned w) { return __uint_as_float(w & 0xffff0000u); }
; DI void store8(bf16_t* p, f32x4 a, f32x4 b) { u32x4 w = {cvt_pk_bf16(a[0], a[1]), cvt_pk_bf16(a[2], a[3]), cvt_pk_bf16(b[0], b[1]), cvt_pk_bf16(b[2], b[3])}; *(u32x4*)p = w; }
; DI f32x4 silu4(f32x4 v) { f32x4 r; r[0] = silu_f(v[0]); r[1] = silu_f(v[1]); r[2] = silu_f(v[2]); r[3] = silu_f(v[3]); return r; }
;     DI void operator()(const AccT& acc, const pg8::Unit& u, int wr, int wc, int fr, int fq) const {
;     ...
;             for (int m = 0; m < 4; ++m) { const size_t row = (size_t)u.pm * 256 + wr * 64 + fr + ai * 128 + m * 16;
;                 st[m] = *(const float2*)(stats + (row * 4 + head) * 2);
; #pragma unroll
;                 for (int bj = 0; bj < 2; ++bj) ov[m][bj] = *(const u32x4*)(o + row * 2048 + col0 + bj * 128); }
; #pragma unroll
;             for (int m = 0; m < 4; ++m) { const size_t row = (size_t)u.pm * 256 + wr * 64 + fr + ai * 128 + m * 16;
;                 const float mean = st[m].x * (1.f / 512.f), var = fmaxf(st[m].y * (1.f / 512.f) - mean * mean, 0.f), rstd = rsqrtf(var + 1e-5f);
; #pragma unroll
;                 for (int bj = 0; bj < 2; ++bj) { bf16_t* op = o + row * 2048 + col0 + bj * 128; const u32x4 w = ov[m][bj];
;                     const f32x4 s0 = silu4(acc[ai][bj][m][0]), s1 = silu4(acc[ai][bj][m][1]);
;                     f32x4 y0, y1;
;                     y0[0] = (bflo(w[0]) - mean) * rstd * g0[bj][0] * s0[0]; y0[1] = (bfhi(w[0]) - mean) * rstd * g0[bj][1] * s0[1];
;                     y0[2] = (bflo(w[1]) - mean) * rstd * g0[bj][2] * s0[2]; y0[3] = (bfhi(w[1]) - mean) * rstd * g0[bj][3] * s0[3];
;                     y1[0] = (bflo(w[2]) - mean) * rstd * g1[bj][0] * s1[0]; y1[1] = (bfhi(w[2]) - mean) * rstd * g1[bj][1] * s1[1];
;                     y1[2] = (bflo(w[3]) - mean) * rstd * g1[bj][2] * s1[2]; y1[3] = (bfhi(w[3]) - mean) * rstd * g1[bj][3] * s1[3];
;                     store8(op, y0, y1); } } }
	v_mov_b32_e32 v215, v60
	v_lshlrev_b32_e32 v152, 16, v210
	v_pk_mul_f32 v[204:205], v[204:205], s[54:55] op_sel_hi:[1,0]
	s_nop 0
	v_fma_f32 v205, -v204, v204, v205
	v_max_f32_e32 v205, 0, v205
	v_add_f32_e32 v205, 0x3727c5ac, v205
	v_mul_f32_e32 v209, 0x4b800000, v205
	v_cmp_gt_f32_e32 vcc, s94, v205
	v_sub_f32_e32 v152, v152, v204
	s_nop 0
	v_cndmask_b32_e32 v205, v205, v209, vcc
	v_rsq_f32_e32 v205, v205
	v_and_b32_e32 v209, 0xffff0000, v210
	v_sub_f32_e32 v209, v209, v204
	v_mul_f32_e32 v210, 0x45800000, v205
	v_cndmask_b32_e32 v205, v205, v210, vcc
	v_mul_f32_e32 v221, v209, v205
	v_lshlrev_b32_e32 v209, 16, v211
	v_sub_f32_e32 v209, v209, v204
	v_mul_f32_e32 v223, v209, v205
	v_and_b32_e32 v209, 0xffff0000, v211
	v_sub_f32_e32 v209, v209, v204
	v_mul_f32_e32 v225, v209, v205
	v_lshlrev_b32_e32 v209, 16, v212
	v_sub_f32_e32 v209, v209, v204
	v_mul_f32_e32 v227, v209, v205
	v_and_b32_e32 v209, 0xffff0000, v212
	v_sub_f32_e32 v209, v209, v204
	v_mul_f32_e32 v229, v209, v205
	v_lshlrev_b32_e32 v209, 16, v213
	v_sub_f32_e32 v209, v209, v204
	v_mul_f32_e32 v233, v209, v205
	v_and_b32_e32 v209, 0xffff0000, v213
	global_load_dwordx2 v[212:213], v[216:217], off
	v_mov_b32_e32 v210, v155
	v_mov_b32_e32 v211, v63
	v_pk_mul_f32 v[210:211], v[210:211], v[224:225]
	v_sub_f32_e32 v209, v209, v204
	v_mul_f32_e32 v155, v210, v211
	v_mov_b32_e32 v210, v144
	v_mov_b32_e32 v211, v68
	v_pk_mul_f32 v[210:211], v[210:211], v[226:227]
	v_mul_f32_e32 v235, v209, v205
	v_mul_f32_e32 v144, v210, v211
	v_mov_b32_e32 v210, v145
	v_mov_b32_e32 v211, v69
	v_pk_mul_f32 v[210:211], v[210:211], v[228:229]
	v_mul_f32_e32 v219, v152, v205
	v_mul_f32_e32 v145, v210, v211
	v_mov_b32_e32 v210, v146
	v_mov_b32_e32 v211, v70
	v_pk_mul_f32 v[210:211], v[210:211], v[232:233]
	v_pk_mul_f32 v[214:215], v[214:215], v[218:219]
	v_mul_f32_e32 v146, v210, v211
	v_mov_b32_e32 v210, v147
	v_mov_b32_e32 v211, v71
	v_pk_mul_f32 v[210:211], v[210:211], v[234:235]
	v_mul_f32_e32 v147, 0xbfb8aa3b, v136
	v_exp_f32_e32 v209, v147
	v_mul_f32_e32 v147, v210, v211
	v_mul_f32_e32 v210, 0xbfb8aa3b, v137
	v_exp_f32_e32 v211, v210
	v_mul_f32_e32 v152, v214, v215
	v_mov_b32_e32 v214, v153
	v_mov_b32_e32 v215, v61
	v_pk_mul_f32 v[214:215], v[214:215], v[220:221]
	v_add_f32_e32 v209, 1.0, v209
	v_mul_f32_e32 v153, v214, v215
	v_mov_b32_e32 v214, v154
	v_mov_b32_e32 v215, v62
	v_pk_mul_f32 v[214:215], v[214:215], v[222:223]
	v_rcp_f32_e32 v210, v209
	v_add_f32_e32 v209, 1.0, v211
	v_mul_f32_e32 v211, 0xbfb8aa3b, v138
	v_mul_f32_e32 v154, v214, v215
	v_exp_f32_e32 v211, v211
	v_mul_f32_e32 v214, 0xbfb8aa3b, v139
	v_exp_f32_e32 v215, v214
	v_rcp_f32_e32 v214, v209
	v_add_f32_e32 v209, 1.0, v211
	v_mul_f32_e32 v211, 0xbfb8aa3b, v132
	v_rcp_f32_e32 v216, v209
	v_add_f32_e32 v209, 1.0, v215
	v_exp_f32_e32 v211, v211
	v_mul_f32_e32 v215, 0xbfb8aa3b, v133
	v_exp_f32_e32 v215, v215
	v_rcp_f32_e32 v218, v209
	v_add_f32_e32 v209, 1.0, v211
	v_mul_f32_e32 v211, 0xbfb8aa3b, v134
	v_rcp_f32_e32 v220, v209
	v_add_f32_e32 v209, 1.0, v215
	v_exp_f32_e32 v211, v211
	v_mul_f32_e32 v215, 0xbfb8aa3b, v135
	v_exp_f32_e32 v215, v215
	v_rcp_f32_e32 v222, v209
	v_add_f32_e32 v209, 1.0, v211
	v_rcp_f32_e32 v224, v209
	v_add_f32_e32 v209, 1.0, v215
	v_rcp_f32_e32 v226, v209
	v_lshlrev_b32_e32 v209, 16, v164
	v_and_b32_e32 v164, 0xffff0000, v164
	v_sub_f32_e32 v164, v164, v204
	v_mul_f32_e32 v215, v164, v205
	v_lshlrev_b32_e32 v164, 16, v165
	v_sub_f32_e32 v164, v164, v204
	v_mul_f32_e32 v217, v164, v205
	v_and_b32_e32 v164, 0xffff0000, v165
	v_sub_f32_e32 v164, v164, v204
	v_mul_f32_e32 v219, v164, v205
	v_mov_b32_e32 v164, v139
	v_mov_b32_e32 v165, v59
	v_pk_mul_f32 v[164:165], v[164:165], v[218:219]
	v_sub_f32_e32 v209, v209, v204
	v_mul_f32_e32 v139, v164, v165
	v_lshlrev_b32_e32 v164, 16, v166
	v_sub_f32_e32 v164, v164, v204
	v_mul_f32_e32 v221, v164, v205
	v_mov_b32_e32 v164, v132
	v_and_b32_e32 v132, 0xffff0000, v166
	v_sub_f32_e32 v132, v132, v204
	v_mov_b32_e32 v165, v48
	v_mul_f32_e32 v223, v132, v205
	v_mov_b32_e32 v132, v133
	v_mov_b32_e32 v133, v49
	v_pk_mul_f32 v[164:165], v[164:165], v[220:221]
	v_pk_mul_f32 v[132:133], v[132:133], v[222:223]
	v_mul_f32_e32 v164, v164, v165
	v_mul_f32_e32 v165, v132, v133
	v_lshlrev_b32_e32 v132, 16, v167
	v_sub_f32_e32 v132, v132, v204
	v_mul_f32_e32 v225, v132, v205
	v_mov_b32_e32 v132, v134
	v_mov_b32_e32 v133, v50
	v_pk_mul_f32 v[132:133], v[132:133], v[224:225]
	v_mul_f32_e32 v211, v209, v205
	v_mul_f32_e32 v166, v132, v133
	v_and_b32_e32 v132, 0xffff0000, v167
	v_sub_f32_e32 v132, v132, v204
	v_mul_f32_e32 v227, v132, v205
	v_mov_b32_e32 v132, v135
	s_waitcnt vmcnt(0)
; DI float bflo(unsigned w) { return __uint_as_float(w << 16); }
; DI float bfhi(unsigned w) { return __uint_as_float(w & 0xffff0000u); }
; DI void store8(bf16_t* p, f32x4 a, f32x4 b) { u32x4 w = {cvt_pk_bf16(a[0], a[1]), cvt_pk_bf16(a[2], a[3]), cvt_pk_bf16(b[0], b[1]), cvt_pk_bf16(b[2], b[3])}; *(u32x4*)p = w; }
; DI f32x4 silu4(f32x4 v) { f32x4 r; r[0] = silu_f(v[0]); r[1] = silu_f(v[1]); r[2] = silu_f(v[2]); r[3] = silu_f(v[3]); return r; }
;     DI void operator()(const AccT& acc, const pg8::Unit& u, int wr, int wc, int fr, int fq) const {
;     ...
;             for (int m = 0; m < 4; ++m) { const size_t row = (size_t)u.pm * 256 + wr * 64 + fr + ai * 128 + m * 16;
;                 st[m] = *(const float2*)(stats + (row * 4 + head) * 2);
; #pragma unroll
;                 for (int bj = 0; bj < 2; ++bj) ov[m][bj] = *(const u32x4*)(o + row * 2048 + col0 + bj * 128); }
; #pragma unroll
;             for (int m = 0; m < 4; ++m) { const size_t row = (size_t)u.pm * 256 + wr * 64 + fr + ai * 128 + m * 16;
;                 const float mean = st[m].x * (1.f / 512.f), var = fmaxf(st[m].y * (1.f / 512.f) - mean * mean, 0.f), rstd = rsqrtf(var + 1e-5f);
; #pragma unroll
;                 for (int bj = 0; bj < 2; ++bj) { bf16_t* op = o + row * 2048 + col0 + bj * 128; const u32x4 w = ov[m][bj];
;                     const f32x4 s0 = silu4(acc[ai][bj][m][0]), s1 = silu4(acc[ai][bj][m][1]);
;                     f32x4 y0, y1;
;                     y0[0] = (bflo(w[0]) - mean) * rstd * g0[bj][0] * s0[0]; y0[1] = (bfhi(w[0]) - mean) * rstd * g0[bj][1] * s0[1];
;                     y0[2] = (bflo(w[1]) - mean) * rstd * g0[bj][2] * s0[2]; y0[3] = (bfhi(w[1]) - mean) * rstd * g0[bj][3] * s0[3];
;                     y1[0] = (bflo(w[2]) - mean) * rstd * g1[bj][0] * s1[0]; y1[1] = (bfhi(w[2]) - mean) * rstd * g1[bj][1] * s1[1];
;                     y1[2] = (bflo(w[3]) - mean) * rstd * g1[bj][2] * s1[2]; y1[3] = (bfhi(w[3]) - mean) * rstd * g1[bj][3] * s1[3];
;                     store8(op, y0, y1); } } }
	v_pk_mul_f32 v[134:135], v[212:213], s[54:55] op_sel_hi:[1,0]
	v_mov_b32_e32 v228, v136
	v_fma_f32 v133, -v134, v134, v135
	v_max_f32_e32 v133, 0, v133
	v_add_f32_e32 v133, 0x3727c5ac, v133
	v_mul_f32_e32 v135, 0x4b800000, v133
	v_cmp_gt_f32_e32 vcc, s94, v133
	v_mov_b32_e32 v229, v56
	v_mul_f32_e32 v204, 0xbfb8aa3b, v126
	v_cndmask_b32_e32 v133, v133, v135, vcc
	v_rsq_f32_e32 v167, v133
	v_mov_b32_e32 v133, v51
	v_pk_mul_f32 v[132:133], v[132:133], v[226:227]
	v_pk_mul_f32 v[210:211], v[228:229], v[210:211]
	v_mul_f32_e32 v135, v132, v133
	v_mul_f32_e32 v132, 0x45800000, v167
	v_cndmask_b32_e32 v167, v167, v132, vcc
	v_lshl_add_u64 v[132:133], s[96:97], 0, v[202:203]
	v_mul_f32_e32 v203, 0xbfb8aa3b, v125
	v_exp_f32_e32 v203, v203
	v_exp_f32_e32 v205, v204
	v_mul_f32_e32 v204, 0xbfb8aa3b, v127
	v_mul_f32_e32 v136, v210, v211
	v_mov_b32_e32 v210, v137
	v_mov_b32_e32 v211, v57
	v_exp_f32_e32 v209, v204
	v_pk_mul_f32 v[210:211], v[210:211], v[214:215]
	v_add_f32_e32 v203, 1.0, v203
	v_mul_f32_e32 v137, v210, v211
	v_mov_b32_e32 v210, v138
	v_mov_b32_e32 v211, v58
	v_pk_mul_f32 v[210:211], v[210:211], v[216:217]
	v_rcp_f32_e32 v204, v203
	v_add_f32_e32 v203, 1.0, v205
	v_mul_f32_e32 v205, 0xbfb8aa3b, v120
	v_mul_f32_e32 v138, v210, v211
	v_rcp_f32_e32 v210, v203
	v_add_f32_e32 v203, 1.0, v209
	v_exp_f32_e32 v205, v205
	v_mul_f32_e32 v209, 0xbfb8aa3b, v121
	v_exp_f32_e32 v209, v209
	v_rcp_f32_e32 v212, v203
	v_add_f32_e32 v203, 1.0, v205
	v_mul_f32_e32 v205, 0xbfb8aa3b, v122
	v_rcp_f32_e32 v214, v203
	v_add_f32_e32 v203, 1.0, v209
	v_exp_f32_e32 v205, v205
	v_mul_f32_e32 v209, 0xbfb8aa3b, v123
	v_exp_f32_e32 v209, v209
	v_rcp_f32_e32 v216, v203
	v_add_f32_e32 v203, 1.0, v205
	v_rcp_f32_e32 v218, v203
	v_add_f32_e32 v203, 1.0, v209
	v_rcp_f32_e32 v220, v203
	v_lshlrev_b32_e32 v203, 16, v160
	v_and_b32_e32 v160, 0xffff0000, v160
	v_sub_f32_e32 v160, v160, v134
	v_mul_f32_e32 v205, v160, v167
	v_lshlrev_b32_e32 v160, 16, v161
	v_sub_f32_e32 v160, v160, v134
	v_mul_f32_e32 v211, v160, v167
	v_and_b32_e32 v160, 0xffff0000, v161
	v_sub_f32_e32 v160, v160, v134
	v_mul_f32_e32 v213, v160, v167
	v_mov_b32_e32 v160, v127
	v_mov_b32_e32 v161, v63
	v_pk_mul_f32 v[160:161], v[160:161], v[212:213]
	v_mul_f32_e32 v202, 0xbfb8aa3b, v124
	v_mul_f32_e32 v127, v160, v161
	v_lshlrev_b32_e32 v160, 16, v162
	v_sub_f32_e32 v160, v160, v134
	v_exp_f32_e32 v202, v202
	v_mul_f32_e32 v215, v160, v167
	v_mov_b32_e32 v160, v120
	v_and_b32_e32 v120, 0xffff0000, v162
	v_sub_f32_e32 v120, v120, v134
	v_mov_b32_e32 v161, v68
	v_mul_f32_e32 v217, v120, v167
	v_mov_b32_e32 v120, v121
	v_mov_b32_e32 v121, v69
	v_pk_mul_f32 v[160:161], v[160:161], v[214:215]
	v_pk_mul_f32 v[120:121], v[120:121], v[216:217]
	v_add_f32_e32 v202, 1.0, v202
	v_mul_f32_e32 v160, v160, v161
	v_mul_f32_e32 v161, v120, v121
	v_lshlrev_b32_e32 v120, 16, v163
	v_rcp_f32_e32 v202, v202
	v_sub_f32_e32 v120, v120, v134
	v_mul_f32_e32 v219, v120, v167
	v_mov_b32_e32 v120, v122
	v_mov_b32_e32 v121, v70
	v_sub_f32_e32 v203, v203, v134
	v_pk_mul_f32 v[120:121], v[120:121], v[218:219]
	v_mul_f32_e32 v203, v203, v167
	v_mov_b32_e32 v222, v124
	v_mov_b32_e32 v223, v60
	v_mul_f32_e32 v162, v120, v121
	v_mul_f32_e32 v121, 0xbfb8aa3b, v116
	v_pk_mul_f32 v[202:203], v[222:223], v[202:203]
	v_and_b32_e32 v120, 0xffff0000, v163
	v_exp_f32_e32 v122, v121
	v_mul_f32_e32 v124, v202, v203
	v_mov_b32_e32 v202, v125
	v_mov_b32_e32 v203, v61
	v_sub_f32_e32 v120, v120, v134
	v_pk_mul_f32 v[202:203], v[202:203], v[204:205]
	v_mul_f32_e32 v221, v120, v167
	v_mov_b32_e32 v120, v123
	v_mov_b32_e32 v121, v71
	v_mul_f32_e32 v125, v202, v203
	v_mov_b32_e32 v202, v126
	v_mov_b32_e32 v203, v62
	v_pk_mul_f32 v[120:121], v[120:121], v[220:221]
	v_pk_mul_f32 v[202:203], v[202:203], v[210:211]
	v_mul_f32_e32 v163, v120, v121
	v_add_f32_e32 v120, 1.0, v122
	v_mul_f32_e32 v121, 0xbfb8aa3b, v117
	v_mul_f32_e32 v126, v202, v203
	v_exp_f32_e32 v203, v121
	v_rcp_f32_e32 v202, v120
	global_load_dwordx4 v[120:123], v[200:201], off
	s_nop 0
	global_load_dwordx2 v[198:199], v[198:199], off
	v_mul_f32_e32 v201, 0xbfb8aa3b, v118
	v_add_f32_e32 v200, 1.0, v203
	v_exp_f32_e32 v201, v201
	v_mul_f32_e32 v203, 0xbfb8aa3b, v119
	v_exp_f32_e32 v203, v203
	v_mul_f32_e32 v205, 0xbfb8aa3b, v113
	v_add_f32_e32 v201, 1.0, v201
	v_rcp_f32_e32 v204, v201
	v_add_f32_e32 v201, 1.0, v203
	v_mul_f32_e32 v203, 0xbfb8aa3b, v112
	v_exp_f32_e32 v203, v203
	v_exp_f32_e32 v205, v205
	v_rcp_f32_e32 v210, v201
	v_rcp_f32_e32 v200, v200
	v_add_f32_e32 v201, 1.0, v203
	v_mul_f32_e32 v203, 0xbfb8aa3b, v114
	v_rcp_f32_e32 v212, v201
	v_add_f32_e32 v201, 1.0, v205
	v_exp_f32_e32 v203, v203
	v_mul_f32_e32 v205, 0xbfb8aa3b, v115
	v_exp_f32_e32 v205, v205
	v_rcp_f32_e32 v214, v201
	v_add_f32_e32 v201, 1.0, v203
	v_rcp_f32_e32 v216, v201
	v_add_f32_e32 v201, 1.0, v205
	v_rcp_f32_e32 v218, v201
	v_lshlrev_b32_e32 v201, 16, v156
	v_mov_b32_e32 v220, v116
	v_and_b32_e32 v116, 0xffff0000, v156
	v_sub_f32_e32 v201, v201, v134
	v_sub_f32_e32 v116, v116, v134
	v_mul_f32_e32 v203, v201, v167
	v_mul_f32_e32 v201, v116, v167
	v_mov_b32_e32 v116, v117
	v_mov_b32_e32 v117, v57
	v_mov_b32_e32 v221, v56
	v_pk_mul_f32 v[116:117], v[116:117], v[200:201]
	v_pk_mul_f32 v[202:203], v[220:221], v[202:203]
	v_mul_f32_e32 v220, v116, v117
	v_lshlrev_b32_e32 v116, 16, v157
	v_sub_f32_e32 v116, v116, v134
	v_mul_f32_e32 v205, v116, v167
	v_mov_b32_e32 v116, v118
	v_mov_b32_e32 v117, v58
	v_pk_mul_f32 v[116:117], v[116:117], v[204:205]
	v_mul_f32_e32 v118, 0xbfb8aa3b, v110
	v_mul_f32_e32 v221, v116, v117
	v_and_b32_e32 v116, 0xffff0000, v157
	v_sub_f32_e32 v116, v116, v134
	v_mul_f32_e32 v211, v116, v167
	v_mov_b32_e32 v116, v119
	v_mov_b32_e32 v117, v59
	v_pk_mul_f32 v[116:117], v[116:117], v[210:211]
	v_exp_f32_e32 v119, v118
	v_mul_f32_e32 v210, v116, v117
	v_lshlrev_b32_e32 v116, 16, v158
	v_sub_f32_e32 v116, v116, v134
	v_mul_f32_e32 v213, v116, v167
	v_mov_b32_e32 v116, v112
	v_and_b32_e32 v112, 0xffff0000, v158
	v_sub_f32_e32 v112, v112, v134
	v_mul_f32_e32 v215, v112, v167
	v_mov_b32_e32 v112, v113
	v_mov_b32_e32 v113, v49
	v_mov_b32_e32 v117, v48
	v_pk_mul_f32 v[112:113], v[112:113], v[214:215]
	v_pk_mul_f32 v[116:117], v[116:117], v[212:213]
	v_mul_f32_e32 v212, v112, v113
	v_lshlrev_b32_e32 v112, 16, v159
	v_sub_f32_e32 v112, v112, v134
	v_mul_f32_e32 v217, v112, v167
	v_mov_b32_e32 v112, v114
	v_mov_b32_e32 v113, v50
	v_pk_mul_f32 v[112:113], v[112:113], v[216:217]
	v_mul_f32_e32 v211, v116, v117
	v_mul_f32_e32 v213, v112, v113
	v_and_b32_e32 v112, 0xffff0000, v159
	v_sub_f32_e32 v112, v112, v134
	v_mul_f32_e32 v117, 0xbfb8aa3b, v109
	v_mul_f32_e32 v219, v112, v167
	v_mov_b32_e32 v112, v115
	s_waitcnt vmcnt(0)
; DI float bflo(unsigned w) { return __uint_as_float(w << 16); }
; DI float bfhi(unsigned w) { return __uint_as_float(w & 0xffff0000u); }
; DI void store8(bf16_t* p, f32x4 a, f32x4 b) { u32x4 w = {cvt_pk_bf16(a[0], a[1]), cvt_pk_bf16(a[2], a[3]), cvt_pk_bf16(b[0], b[1]), cvt_pk_bf16(b[2], b[3])}; *(u32x4*)p = w; }
; DI f32x4 silu4(f32x4 v) { f32x4 r; r[0] = silu_f(v[0]); r[1] = silu_f(v[1]); r[2] = silu_f(v[2]); r[3] = silu_f(v[3]); return r; }
;     DI void operator()(const AccT& acc, const pg8::Unit& u, int wr, int wc, int fr, int fq) const {
;     ...
;             for (int m = 0; m < 4; ++m) { const size_t row = (size_t)u.pm * 256 + wr * 64 + fr + ai * 128 + m * 16;
;                 st[m] = *(const float2*)(stats + (row * 4 + head) * 2);
; #pragma unroll
;                 for (int bj = 0; bj < 2; ++bj) ov[m][bj] = *(const u32x4*)(o + row * 2048 + col0 + bj * 128); }
; #pragma unroll
;             for (int m = 0; m < 4; ++m) { const size_t row = (size_t)u.pm * 256 + wr * 64 + fr + ai * 128 + m * 16;
;                 const float mean = st[m].x * (1.f / 512.f), var = fmaxf(st[m].y * (1.f / 512.f) - mean * mean, 0.f), rstd = rsqrtf(var + 1e-5f);
; #pragma unroll
;                 for (int bj = 0; bj < 2; ++bj) { bf16_t* op = o + row * 2048 + col0 + bj * 128; const u32x4 w = ov[m][bj];
;                     const f32x4 s0 = silu4(acc[ai][bj][m][0]), s1 = silu4(acc[ai][bj][m][1]);
;                     f32x4 y0, y1;
;                     y0[0] = (bflo(w[0]) - mean) * rstd * g0[bj][0] * s0[0]; y0[1] = (bfhi(w[0]) - mean) * rstd * g0[bj][1] * s0[1];
;                     y0[2] = (bflo(w[1]) - mean) * rstd * g0[bj][2] * s0[2]; y0[3] = (bfhi(w[1]) - mean) * rstd * g0[bj][3] * s0[3];
;                     y1[0] = (bflo(w[2]) - mean) * rstd * g1[bj][0] * s1[0]; y1[1] = (bfhi(w[2]) - mean) * rstd * g1[bj][1] * s1[1];
;                     y1[2] = (bflo(w[3]) - mean) * rstd * g1[bj][2] * s1[2]; y1[3] = (bfhi(w[3]) - mean) * rstd * g1[bj][3] * s1[3];
;                     store8(op, y0, y1); } } }
	v_pk_mul_f32 v[114:115], v[198:199], s[54:55] op_sel_hi:[1,0]
	v_exp_f32_e32 v117, v117
	v_fma_f32 v113, -v114, v114, v115
	v_mul_f32_e32 v118, 0xbfb8aa3b, v111
	v_max_f32_e32 v113, 0, v113
	v_exp_f32_e32 v157, v118
	v_add_f32_e32 v113, 0x3727c5ac, v113
	v_mul_f32_e32 v115, 0x4b800000, v113
	v_cmp_gt_f32_e32 vcc, s94, v113
	v_add_f32_e32 v117, 1.0, v117
	v_rcp_f32_e32 v118, v117
	v_cndmask_b32_e32 v113, v113, v115, vcc
	v_add_f32_e32 v117, 1.0, v119
	v_mul_f32_e32 v119, 0xbfb8aa3b, v104
	v_rsq_f32_e32 v115, v113
	v_rcp_f32_e32 v156, v117
	v_add_f32_e32 v117, 1.0, v157
	v_exp_f32_e32 v119, v119
	v_mul_f32_e32 v157, 0xbfb8aa3b, v105
	v_exp_f32_e32 v157, v157
	v_mov_b32_e32 v113, v51
	v_pk_mul_f32 v[112:113], v[112:113], v[218:219]
	v_mul_f32_e32 v116, 0xbfb8aa3b, v108
	v_mul_f32_e32 v134, v112, v113
	v_mul_f32_e32 v112, 0x45800000, v115
	v_rcp_f32_e32 v158, v117
	v_add_f32_e32 v117, 1.0, v119
	v_mul_f32_e32 v119, 0xbfb8aa3b, v106
	v_cndmask_b32_e32 v115, v115, v112, vcc
	v_lshl_add_u64 v[112:113], s[96:97], 0, v[196:197]
	v_exp_f32_e32 v116, v116
	v_rcp_f32_e32 v196, v117
	v_add_f32_e32 v117, 1.0, v157
	v_exp_f32_e32 v119, v119
	v_mul_f32_e32 v157, 0xbfb8aa3b, v107
	v_exp_f32_e32 v157, v157
	v_add_f32_e32 v116, 1.0, v116
	v_rcp_f32_e32 v198, v117
	v_add_f32_e32 v117, 1.0, v119
	v_rcp_f32_e32 v116, v116
	v_rcp_f32_e32 v200, v117
	v_add_f32_e32 v117, 1.0, v157
	v_mov_b32_e32 v204, v108
	v_and_b32_e32 v108, 0xffff0000, v120
	v_mul_f32_e32 v209, v202, v203
	v_rcp_f32_e32 v202, v117
	v_lshlrev_b32_e32 v117, 16, v120
	v_sub_f32_e32 v108, v108, v114
	v_sub_f32_e32 v117, v117, v114
	v_mul_f32_e32 v119, v108, v115
	v_mov_b32_e32 v108, v109
	v_mov_b32_e32 v109, v61
	v_mul_f32_e32 v117, v117, v115
	v_mov_b32_e32 v205, v60
	v_pk_mul_f32 v[108:109], v[108:109], v[118:119]
	v_pk_mul_f32 v[116:117], v[204:205], v[116:117]
	v_mul_f32_e32 v204, v108, v109
	v_lshlrev_b32_e32 v108, 16, v121
	v_sub_f32_e32 v108, v108, v114
	v_mul_f32_e32 v157, v108, v115
	v_mov_b32_e32 v108, v110
	v_mov_b32_e32 v109, v62
	v_pk_mul_f32 v[108:109], v[108:109], v[156:157]
	global_load_dwordx2 v[156:157], v[194:195], off
	v_mul_f32_e32 v205, v108, v109
	v_and_b32_e32 v108, 0xffff0000, v121
	v_sub_f32_e32 v108, v108, v114
	v_mul_f32_e32 v159, v108, v115
	v_mov_b32_e32 v108, v111
	v_mov_b32_e32 v109, v63
	v_pk_mul_f32 v[108:109], v[108:109], v[158:159]
	v_mul_f32_e32 v167, v116, v117
	v_mul_f32_e32 v214, v108, v109
	v_lshlrev_b32_e32 v108, 16, v122
	v_sub_f32_e32 v108, v108, v114
	v_mul_f32_e32 v197, v108, v115
	v_mov_b32_e32 v108, v104
	v_and_b32_e32 v104, 0xffff0000, v122
	v_sub_f32_e32 v104, v104, v114
	v_mul_f32_e32 v199, v104, v115
	v_mov_b32_e32 v104, v105
	v_mov_b32_e32 v105, v69
	v_mov_b32_e32 v109, v68
	v_pk_mul_f32 v[104:105], v[104:105], v[198:199]
	v_pk_mul_f32 v[108:109], v[108:109], v[196:197]
	v_mul_f32_e32 v197, v104, v105
	v_lshlrev_b32_e32 v104, 16, v123
	v_sub_f32_e32 v104, v104, v114
	v_mul_f32_e32 v201, v104, v115
	v_mov_b32_e32 v104, v106
	v_mov_b32_e32 v105, v70
	v_pk_mul_f32 v[104:105], v[104:105], v[200:201]
	v_mul_f32_e32 v106, 0xbfb8aa3b, v100
	v_mul_f32_e32 v198, v104, v105
	v_and_b32_e32 v104, 0xffff0000, v123
	v_sub_f32_e32 v104, v104, v114
	v_mul_f32_e32 v203, v104, v115
	v_mov_b32_e32 v104, v107
	v_exp_f32_e32 v106, v106
	v_mul_f32_e32 v107, 0xbfb8aa3b, v101
	v_exp_f32_e32 v107, v107
	v_mov_b32_e32 v105, v71
	v_pk_mul_f32 v[104:105], v[104:105], v[202:203]
	v_mul_f32_e32 v196, v108, v109
	v_mul_f32_e32 v199, v104, v105
	v_add_f32_e32 v104, 1.0, v106
	v_mul_f32_e32 v106, 0xbfb8aa3b, v102
	v_add_f32_e32 v105, 1.0, v107
	v_exp_f32_e32 v107, v106
	v_mul_f32_e32 v106, 0xbfb8aa3b, v103
	v_exp_f32_e32 v109, v106
	v_rcp_f32_e32 v106, v105
	v_add_f32_e32 v105, 1.0, v107
	v_mul_f32_e32 v107, 0xbfb8aa3b, v96
	v_rcp_f32_e32 v108, v105
	v_add_f32_e32 v105, 1.0, v109
	v_exp_f32_e32 v107, v107
	v_mul_f32_e32 v109, 0xbfb8aa3b, v97
	v_exp_f32_e32 v109, v109
	v_rcp_f32_e32 v110, v105
	v_add_f32_e32 v105, 1.0, v107
	v_mul_f32_e32 v107, 0xbfb8aa3b, v98
	v_rcp_f32_e32 v116, v105
	v_add_f32_e32 v105, 1.0, v109
	v_exp_f32_e32 v107, v107
	v_mul_f32_e32 v109, 0xbfb8aa3b, v99
	v_exp_f32_e32 v109, v109
	v_rcp_f32_e32 v118, v105
	v_add_f32_e32 v105, 1.0, v107
	v_rcp_f32_e32 v104, v104
	v_rcp_f32_e32 v120, v105
	v_add_f32_e32 v105, 1.0, v109
	v_rcp_f32_e32 v122, v105
	v_lshlrev_b32_e32 v105, 16, v148
	v_mov_b32_e32 v158, v100
	v_and_b32_e32 v100, 0xffff0000, v148
	v_sub_f32_e32 v105, v105, v114
	v_sub_f32_e32 v100, v100, v114
	v_mul_f32_e32 v105, v105, v115
	v_mov_b32_e32 v159, v56
	v_mul_f32_e32 v107, v100, v115
	v_mov_b32_e32 v100, v101
	v_mov_b32_e32 v101, v57
	v_pk_mul_f32 v[104:105], v[158:159], v[104:105]
	v_pk_mul_f32 v[100:101], v[100:101], v[106:107]
	v_mul_f32_e32 v104, v104, v105
	v_mul_f32_e32 v105, v100, v101
	v_lshlrev_b32_e32 v100, 16, v149
	v_sub_f32_e32 v100, v100, v114
	v_mul_f32_e32 v109, v100, v115
	v_mov_b32_e32 v100, v102
	v_mov_b32_e32 v101, v58
	v_pk_mul_f32 v[100:101], v[100:101], v[108:109]
	v_lshl_add_u64 v[132:133], v[132:133], 0, v[184:185]
	v_mul_f32_e32 v102, v100, v101
	v_and_b32_e32 v100, 0xffff0000, v149
	v_sub_f32_e32 v100, v100, v114
	v_mul_f32_e32 v111, v100, v115
	v_mov_b32_e32 v100, v103
	v_mov_b32_e32 v101, v59
	v_pk_mul_f32 v[100:101], v[100:101], v[110:111]
	v_lshl_add_u64 v[112:113], v[112:113], 0, v[184:185]
	v_mul_f32_e32 v103, v100, v101
	v_lshlrev_b32_e32 v100, 16, v150
	v_sub_f32_e32 v100, v100, v114
	v_mul_f32_e32 v117, v100, v115
	v_mov_b32_e32 v100, v96
	v_and_b32_e32 v96, 0xffff0000, v150
	v_sub_f32_e32 v96, v96, v114
	v_mov_b32_e32 v101, v48
	v_mul_f32_e32 v119, v96, v115
	v_mov_b32_e32 v96, v97
	v_mov_b32_e32 v97, v49
; DI float bflo(unsigned w) { return __uint_as_float(w << 16); }
; DI float bfhi(unsigned w) { return __uint_as_float(w & 0xffff0000u); }
; DI void store8(bf16_t* p, f32x4 a, f32x4 b) { u32x4 w = {cvt_pk_bf16(a[0], a[1]), cvt_pk_bf16(a[2], a[3]), cvt_pk_bf16(b[0], b[1]), cvt_pk_bf16(b[2], b[3])}; *(u32x4*)p = w; }
; DI f32x4 silu4(f32x4 v) { f32x4 r; r[0] = silu_f(v[0]); r[1] = silu_f(v[1]); r[2] = silu_f(v[2]); r[3] = silu_f(v[3]); return r; }
;     DI void operator()(const AccT& acc, const pg8::Unit& u, int wr, int wc, int fr, int fq) const {
;     ...
;             for (int m = 0; m < 4; ++m) { const size_t row = (size_t)u.pm * 256 + wr * 64 + fr + ai * 128 + m * 16;
;                 st[m] = *(const float2*)(stats + (row * 4 + head) * 2);
; #pragma unroll
;                 for (int bj = 0; bj < 2; ++bj) ov[m][bj] = *(const u32x4*)(o + row * 2048 + col0 + bj * 128); }
; #pragma unroll
;             for (int m = 0; m < 4; ++m) { const size_t row = (size_t)u.pm * 256 + wr * 64 + fr + ai * 128 + m * 16;
;                 const float mean = st[m].x * (1.f / 512.f), var = fmaxf(st[m].y * (1.f / 512.f) - mean * mean, 0.f), rstd = rsqrtf(var + 1e-5f);
; #pragma unroll
;                 for (int bj = 0; bj < 2; ++bj) { bf16_t* op = o + row * 2048 + col0 + bj * 128; const u32x4 w = ov[m][bj];
;                     const f32x4 s0 = silu4(acc[ai][bj][m][0]), s1 = silu4(acc[ai][bj][m][1]);
;                     f32x4 y0, y1;
;                     y0[0] = (bflo(w[0]) - mean) * rstd * g0[bj][0] * s0[0]; y0[1] = (bfhi(w[0]) - mean) * rstd * g0[bj][1] * s0[1];
;                     y0[2] = (bflo(w[1]) - mean) * rstd * g0[bj][2] * s0[2]; y0[3] = (bfhi(w[1]) - mean) * rstd * g0[bj][3] * s0[3];
;                     y1[0] = (bflo(w[2]) - mean) * rstd * g1[bj][0] * s1[0]; y1[1] = (bfhi(w[2]) - mean) * rstd * g1[bj][1] * s1[1];
;                     y1[2] = (bflo(w[3]) - mean) * rstd * g1[bj][2] * s1[2]; y1[3] = (bfhi(w[3]) - mean) * rstd * g1[bj][3] * s1[3];
;                     store8(op, y0, y1); } } }
	v_pk_mul_f32 v[100:101], v[100:101], v[116:117]
	v_pk_mul_f32 v[96:97], v[96:97], v[118:119]
	v_mul_f32_e32 v100, v100, v101
	v_mul_f32_e32 v101, v96, v97
	v_lshlrev_b32_e32 v96, 16, v151
	v_sub_f32_e32 v96, v96, v114
	v_mul_f32_e32 v121, v96, v115
	v_mov_b32_e32 v96, v98
	v_mov_b32_e32 v97, v50
	v_pk_mul_f32 v[96:97], v[96:97], v[120:121]
	v_mov_b32_e32 v116, v92
	v_mul_f32_e32 v106, v96, v97
	v_and_b32_e32 v96, 0xffff0000, v151
	v_sub_f32_e32 v96, v96, v114
	v_mul_f32_e32 v123, v96, v115
	v_mov_b32_e32 v96, v99
	v_mov_b32_e32 v97, v51
	v_pk_mul_f32 v[96:97], v[96:97], v[122:123]
	v_mov_b32_e32 v117, v60
	v_mul_f32_e32 v107, v96, v97
	v_cvt_pk_bf16_f32 v96, v152, v153
	v_cvt_pk_bf16_f32 v97, v154, v155
	v_cvt_pk_bf16_f32 v98, v144, v145
	v_cvt_pk_bf16_f32 v99, v146, v147
	global_store_dwordx4 v[192:193], v[96:99], off
	s_nop 1
	v_cvt_pk_bf16_f32 v96, v136, v137
	v_cvt_pk_bf16_f32 v97, v138, v139
	v_cvt_pk_bf16_f32 v98, v164, v165
	v_cvt_pk_bf16_f32 v99, v166, v135
	global_store_dwordx4 v[192:193], v[96:99], off offset:256
	s_nop 1
	v_cvt_pk_bf16_f32 v96, v124, v125
	v_cvt_pk_bf16_f32 v97, v126, v127
	v_cvt_pk_bf16_f32 v98, v160, v161
	v_cvt_pk_bf16_f32 v99, v162, v163
	global_store_dwordx4 v[132:133], v[96:99], off
	v_mul_f32_e32 v127, 0xbfb8aa3b, v77
	v_exp_f32_e32 v127, v127
	v_cvt_pk_bf16_f32 v96, v209, v220
	v_cvt_pk_bf16_f32 v97, v221, v210
	v_cvt_pk_bf16_f32 v98, v211, v212
	v_cvt_pk_bf16_f32 v99, v213, v134
	global_store_dwordx4 v[132:133], v[96:99], off offset:256
	v_add_f32_e32 v127, 1.0, v127
	s_nop 0
	v_cvt_pk_bf16_f32 v96, v167, v204
	v_cvt_pk_bf16_f32 v97, v205, v214
	v_cvt_pk_bf16_f32 v98, v196, v197
	v_cvt_pk_bf16_f32 v99, v198, v199
	global_store_dwordx4 v[112:113], v[96:99], off
	s_waitcnt vmcnt(0)
	s_nop 0
	v_pk_mul_f32 v[96:97], v[156:157], s[54:55] op_sel_hi:[1,0]
	v_cvt_pk_bf16_f32 v98, v104, v105
	v_cvt_pk_bf16_f32 v99, v102, v103
	v_cvt_pk_bf16_f32 v100, v100, v101
	v_cvt_pk_bf16_f32 v101, v106, v107
	global_store_dwordx4 v[112:113], v[98:101], off offset:256
	v_fma_f32 v97, -v96, v96, v97
	v_max_f32_e32 v97, 0, v97
	v_add_f32_e32 v97, 0x3727c5ac, v97
	v_mul_f32_e32 v102, 0x4b800000, v97
	v_cmp_gt_f32_e32 vcc, s94, v97
	v_mul_f32_e32 v101, 0xbfb8aa3b, v93
	v_exp_f32_e32 v101, v101
	v_cndmask_b32_e32 v97, v97, v102, vcc
	v_mul_f32_e32 v102, 0xbfb8aa3b, v94
	v_exp_f32_e32 v103, v102
	v_mul_f32_e32 v102, 0xbfb8aa3b, v95
	v_exp_f32_e32 v105, v102
	v_add_f32_e32 v101, 1.0, v101
	v_rcp_f32_e32 v102, v101
	v_add_f32_e32 v101, 1.0, v103
	v_mul_f32_e32 v103, 0xbfb8aa3b, v88
	v_rcp_f32_e32 v104, v101
	v_add_f32_e32 v101, 1.0, v105
	v_exp_f32_e32 v103, v103
	v_mul_f32_e32 v105, 0xbfb8aa3b, v89
	v_exp_f32_e32 v105, v105
	v_mul_f32_e32 v100, 0xbfb8aa3b, v92
	v_rcp_f32_e32 v106, v101
	v_add_f32_e32 v101, 1.0, v103
	v_mul_f32_e32 v103, 0xbfb8aa3b, v90
	v_exp_f32_e32 v100, v100
	v_rcp_f32_e32 v108, v101
	v_add_f32_e32 v101, 1.0, v105
	v_exp_f32_e32 v103, v103
	v_mul_f32_e32 v105, 0xbfb8aa3b, v91
	v_exp_f32_e32 v105, v105
	v_rsq_f32_e32 v97, v97
	v_add_f32_e32 v100, 1.0, v100
	v_rcp_f32_e32 v110, v101
	v_add_f32_e32 v101, 1.0, v103
	v_rcp_f32_e32 v100, v100
	v_rcp_f32_e32 v112, v101
	v_add_f32_e32 v101, 1.0, v105
	v_mul_f32_e32 v98, 0x45800000, v97
	v_rcp_f32_e32 v114, v101
	v_lshlrev_b32_e32 v101, 16, v140
	v_and_b32_e32 v92, 0xffff0000, v140
	v_cndmask_b32_e32 v97, v97, v98, vcc
	v_sub_f32_e32 v101, v101, v96
	v_sub_f32_e32 v92, v92, v96
	v_mul_f32_e32 v101, v101, v97
	v_mul_f32_e32 v103, v92, v97
	v_mov_b32_e32 v92, v93
	v_mov_b32_e32 v93, v61
	v_pk_mul_f32 v[100:101], v[116:117], v[100:101]
	v_pk_mul_f32 v[92:93], v[92:93], v[102:103]
	v_mul_f32_e32 v100, v100, v101
	v_mul_f32_e32 v101, v92, v93
	v_lshlrev_b32_e32 v92, 16, v141
	v_sub_f32_e32 v92, v92, v96
	v_mul_f32_e32 v105, v92, v97
	v_mov_b32_e32 v92, v94
	v_mov_b32_e32 v93, v62
	v_pk_mul_f32 v[92:93], v[92:93], v[104:105]
	v_lshl_add_u64 v[98:99], s[96:97], 0, v[190:191]
	v_mul_f32_e32 v94, v92, v93
	v_and_b32_e32 v92, 0xffff0000, v141
	v_sub_f32_e32 v92, v92, v96
	v_mul_f32_e32 v107, v92, v97
	v_mov_b32_e32 v92, v95
	v_mov_b32_e32 v93, v63
	v_pk_mul_f32 v[92:93], v[92:93], v[106:107]
	v_lshl_add_u64 v[98:99], v[98:99], 0, v[184:185]
	v_mul_f32_e32 v95, v92, v93
	v_lshlrev_b32_e32 v92, 16, v142
	v_sub_f32_e32 v92, v92, v96
	v_mul_f32_e32 v109, v92, v97
	v_mov_b32_e32 v92, v88
	v_and_b32_e32 v88, 0xffff0000, v142
	v_sub_f32_e32 v88, v88, v96
	v_mov_b32_e32 v93, v68
	v_mul_f32_e32 v111, v88, v97
	v_mov_b32_e32 v88, v89
	v_mov_b32_e32 v89, v69
	v_pk_mul_f32 v[92:93], v[92:93], v[108:109]
	v_pk_mul_f32 v[88:89], v[88:89], v[110:111]
	v_mul_f32_e32 v92, v92, v93
	v_mul_f32_e32 v93, v88, v89
	v_lshlrev_b32_e32 v88, 16, v143
	v_sub_f32_e32 v88, v88, v96
	v_mul_f32_e32 v113, v88, v97
	v_mov_b32_e32 v88, v90
	v_mov_b32_e32 v89, v70
	v_pk_mul_f32 v[88:89], v[88:89], v[112:113]
	v_mov_b32_e32 v108, v84
	v_mul_f32_e32 v102, v88, v89
	v_and_b32_e32 v88, 0xffff0000, v143
	v_sub_f32_e32 v88, v88, v96
	v_mul_f32_e32 v115, v88, v97
	v_mov_b32_e32 v88, v91
	v_mov_b32_e32 v89, v71
	v_pk_mul_f32 v[88:89], v[88:89], v[114:115]
	v_mov_b32_e32 v109, v56
	v_mul_f32_e32 v91, v88, v89
	v_cvt_pk_bf16_f32 v88, v100, v101
	v_cvt_pk_bf16_f32 v89, v94, v95
	v_cvt_pk_bf16_f32 v90, v92, v93
	v_mul_f32_e32 v93, 0xbfb8aa3b, v85
	v_exp_f32_e32 v93, v93
	v_cvt_pk_bf16_f32 v91, v102, v91
	global_store_dwordx4 v[98:99], v[88:91], off
	v_mul_f32_e32 v92, 0xbfb8aa3b, v84
	v_exp_f32_e32 v92, v92
	v_mul_f32_e32 v90, 0xbfb8aa3b, v86
	v_exp_f32_e32 v91, v90
	v_mul_f32_e32 v90, 0xbfb8aa3b, v87
	v_add_f32_e32 v89, 1.0, v93
	v_exp_f32_e32 v93, v90
	v_rcp_f32_e32 v90, v89
	v_add_f32_e32 v89, 1.0, v91
; DI float bflo(unsigned w) { return __uint_as_float(w << 16); }
; DI float bfhi(unsigned w) { return __uint_as_float(w & 0xffff0000u); }
; DI void store8(bf16_t* p, f32x4 a, f32x4 b) { u32x4 w = {cvt_pk_bf16(a[0], a[1]), cvt_pk_bf16(a[2], a[3]), cvt_pk_bf16(b[0], b[1]), cvt_pk_bf16(b[2], b[3])}; *(u32x4*)p = w; }
; DI f32x4 silu4(f32x4 v) { f32x4 r; r[0] = silu_f(v[0]); r[1] = silu_f(v[1]); r[2] = silu_f(v[2]); r[3] = silu_f(v[3]); return r; }
;     DI void operator()(const AccT& acc, const pg8::Unit& u, int wr, int wc, int fr, int fq) const {
;     ...
;             for (int m = 0; m < 4; ++m) { const size_t row = (size_t)u.pm * 256 + wr * 64 + fr + ai * 128 + m * 16;
;                 st[m] = *(const float2*)(stats + (row * 4 + head) * 2);
; #pragma unroll
;                 for (int bj = 0; bj < 2; ++bj) ov[m][bj] = *(const u32x4*)(o + row * 2048 + col0 + bj * 128); }
; #pragma unroll
;             for (int m = 0; m < 4; ++m) { const size_t row = (size_t)u.pm * 256 + wr * 64 + fr + ai * 128 + m * 16;
;                 const float mean = st[m].x * (1.f / 512.f), var = fmaxf(st[m].y * (1.f / 512.f) - mean * mean, 0.f), rstd = rsqrtf(var + 1e-5f);
; #pragma unroll
;                 for (int bj = 0; bj < 2; ++bj) { bf16_t* op = o + row * 2048 + col0 + bj * 128; const u32x4 w = ov[m][bj];
;                     const f32x4 s0 = silu4(acc[ai][bj][m][0]), s1 = silu4(acc[ai][bj][m][1]);
;                     f32x4 y0, y1;
;                     y0[0] = (bflo(w[0]) - mean) * rstd * g0[bj][0] * s0[0]; y0[1] = (bfhi(w[0]) - mean) * rstd * g0[bj][1] * s0[1];
;                     y0[2] = (bflo(w[1]) - mean) * rstd * g0[bj][2] * s0[2]; y0[3] = (bfhi(w[1]) - mean) * rstd * g0[bj][3] * s0[3];
;                     y1[0] = (bflo(w[2]) - mean) * rstd * g1[bj][0] * s1[0]; y1[1] = (bfhi(w[2]) - mean) * rstd * g1[bj][1] * s1[1];
;                     y1[2] = (bflo(w[3]) - mean) * rstd * g1[bj][2] * s1[2]; y1[3] = (bfhi(w[3]) - mean) * rstd * g1[bj][3] * s1[3];
;                     store8(op, y0, y1); } } }
	v_mul_f32_e32 v91, 0xbfb8aa3b, v80
	v_add_f32_e32 v88, 1.0, v92
	v_rcp_f32_e32 v92, v89
	v_add_f32_e32 v89, 1.0, v93
	v_exp_f32_e32 v91, v91
	v_mul_f32_e32 v93, 0xbfb8aa3b, v81
	v_exp_f32_e32 v93, v93
	v_rcp_f32_e32 v94, v89
	v_add_f32_e32 v89, 1.0, v91
	v_mul_f32_e32 v91, 0xbfb8aa3b, v82
	v_rcp_f32_e32 v100, v89
	v_add_f32_e32 v89, 1.0, v93
	v_exp_f32_e32 v91, v91
	v_mul_f32_e32 v93, 0xbfb8aa3b, v83
	v_exp_f32_e32 v93, v93
	v_rcp_f32_e32 v102, v89
	v_add_f32_e32 v89, 1.0, v91
	v_rcp_f32_e32 v88, v88
	v_rcp_f32_e32 v104, v89
	v_add_f32_e32 v89, 1.0, v93
	v_rcp_f32_e32 v106, v89
	v_lshlrev_b32_e32 v89, 16, v128
	v_and_b32_e32 v84, 0xffff0000, v128
	v_sub_f32_e32 v89, v89, v96
	v_sub_f32_e32 v84, v84, v96
	v_mul_f32_e32 v89, v89, v97
	v_mul_f32_e32 v91, v84, v97
	v_mov_b32_e32 v84, v85
	v_mov_b32_e32 v85, v57
	v_pk_mul_f32 v[88:89], v[108:109], v[88:89]
	v_pk_mul_f32 v[84:85], v[84:85], v[90:91]
	v_mul_f32_e32 v88, v88, v89
	v_mul_f32_e32 v89, v84, v85
	v_lshlrev_b32_e32 v84, 16, v129
	v_sub_f32_e32 v84, v84, v96
	v_mul_f32_e32 v93, v84, v97
	v_mov_b32_e32 v84, v86
	v_mov_b32_e32 v85, v58
	v_pk_mul_f32 v[84:85], v[84:85], v[92:93]
	v_mul_f32_e32 v128, 0xbfb8aa3b, v78
	v_mul_f32_e32 v86, v84, v85
	v_and_b32_e32 v84, 0xffff0000, v129
	v_sub_f32_e32 v84, v84, v96
	v_mul_f32_e32 v95, v84, v97
	v_mov_b32_e32 v84, v87
	v_mov_b32_e32 v85, v59
	v_pk_mul_f32 v[84:85], v[84:85], v[94:95]
	v_exp_f32_e32 v129, v128
	v_mul_f32_e32 v87, v84, v85
	v_lshlrev_b32_e32 v84, 16, v130
	v_sub_f32_e32 v84, v84, v96
	v_mul_f32_e32 v101, v84, v97
	v_mov_b32_e32 v84, v80
	v_and_b32_e32 v80, 0xffff0000, v130
	v_sub_f32_e32 v80, v80, v96
	v_mov_b32_e32 v85, v48
	v_mul_f32_e32 v103, v80, v97
	v_mov_b32_e32 v80, v81
	v_mov_b32_e32 v81, v49
	v_pk_mul_f32 v[84:85], v[84:85], v[100:101]
	v_pk_mul_f32 v[80:81], v[80:81], v[102:103]
	v_mul_f32_e32 v84, v84, v85
	v_mul_f32_e32 v85, v80, v81
	v_lshlrev_b32_e32 v80, 16, v131
	v_sub_f32_e32 v80, v80, v96
	v_mul_f32_e32 v105, v80, v97
	v_mov_b32_e32 v80, v82
	v_mov_b32_e32 v81, v50
	v_pk_mul_f32 v[80:81], v[80:81], v[104:105]
	v_mul_f32_e32 v128, 0xbfb8aa3b, v79
	v_mul_f32_e32 v90, v80, v81
	v_and_b32_e32 v80, 0xffff0000, v131
	v_sub_f32_e32 v80, v80, v96
	v_mul_f32_e32 v107, v80, v97
	v_mov_b32_e32 v80, v83
	v_mov_b32_e32 v81, v51
	v_pk_mul_f32 v[80:81], v[80:81], v[106:107]
	v_exp_f32_e32 v131, v128
	v_mul_f32_e32 v83, v80, v81
	v_cvt_pk_bf16_f32 v80, v88, v89
	v_cvt_pk_bf16_f32 v81, v86, v87
	v_cvt_pk_bf16_f32 v82, v84, v85
	v_cvt_pk_bf16_f32 v83, v90, v83
	global_store_dwordx4 v[98:99], v[80:83], off offset:256
	v_rcp_f32_e32 v128, v127
	v_add_f32_e32 v127, 1.0, v129
	v_lshl_add_u64 v[80:81], v[188:189], 0, s[38:39]
	v_lshlrev_b64 v[82:83], 5, v[80:81]
	v_lshl_add_u64 v[82:83], s[16:17], 0, v[82:83]
	global_load_dwordx2 v[82:83], v[82:83], off
	v_lshlrev_b64 v[106:107], 12, v[80:81]
	v_lshl_add_u64 v[80:81], v[186:187], 0, v[106:107]
	global_load_dwordx4 v[122:125], v[80:81], off
	global_load_dwordx4 v[100:103], v[80:81], off offset:256
	v_lshl_add_u64 v[80:81], v[188:189], 0, s[20:21]
	v_lshlrev_b64 v[116:117], 12, v[80:81]
	v_lshlrev_b64 v[84:85], 5, v[80:81]
	v_lshl_add_u64 v[80:81], v[186:187], 0, v[116:117]
	s_mov_b64 s[20:21], 0xa0
	global_load_dwordx4 v[96:99], v[80:81], off
	global_load_dwordx4 v[92:95], v[80:81], off offset:256
	v_lshl_add_u64 v[80:81], v[188:189], 0, s[20:21]
	s_mov_b64 s[20:21], 0xb0
	v_lshl_add_u64 v[120:121], s[16:17], 0, v[84:85]
	v_lshlrev_b64 v[84:85], 5, v[80:81]
	v_lshlrev_b64 v[110:111], 12, v[80:81]
	v_lshl_add_u64 v[80:81], v[188:189], 0, s[20:21]
	v_lshl_add_u64 v[112:113], s[16:17], 0, v[84:85]
	v_lshlrev_b64 v[84:85], 5, v[80:81]
	v_lshlrev_b64 v[104:105], 12, v[80:81]
	v_lshl_add_u64 v[114:115], v[186:187], 0, v[110:111]
	global_load_dwordx4 v[88:91], v[114:115], off offset:256
	v_lshl_add_u64 v[108:109], s[16:17], 0, v[84:85]
	v_mul_f32_e32 v129, 0xbfb8aa3b, v72
	v_rcp_f32_e32 v130, v127
	v_add_f32_e32 v127, 1.0, v131
	v_exp_f32_e32 v129, v129
	v_mul_f32_e32 v131, 0xbfb8aa3b, v73
	v_exp_f32_e32 v131, v131
	v_rcp_f32_e32 v132, v127
	v_add_f32_e32 v127, 1.0, v129
	v_mul_f32_e32 v129, 0xbfb8aa3b, v74
	v_rcp_f32_e32 v134, v127
	v_add_f32_e32 v127, 1.0, v131
	v_exp_f32_e32 v129, v129
	v_mul_f32_e32 v131, 0xbfb8aa3b, v75
	v_exp_f32_e32 v131, v131
	v_rcp_f32_e32 v136, v127
	v_add_f32_e32 v127, 1.0, v129
	v_rcp_f32_e32 v138, v127
	v_add_f32_e32 v127, 1.0, v131
	v_rcp_f32_e32 v140, v127
	v_mov_b32_e32 v142, v76
	v_mov_b32_e32 v143, v60
	v_lshl_add_u64 v[106:107], s[96:97], 0, v[106:107]
	v_lshl_add_u64 v[106:107], v[106:107], 0, v[184:185]
	s_mov_b32 s16, s10
	s_mov_b64 s[20:21], s[12:13]
	s_waitcnt vmcnt(0)
; DI float bflo(unsigned w) { return __uint_as_float(w << 16); }
; DI float bfhi(unsigned w) { return __uint_as_float(w & 0xffff0000u); }
; DI void store8(bf16_t* p, f32x4 a, f32x4 b) { u32x4 w = {cvt_pk_bf16(a[0], a[1]), cvt_pk_bf16(a[2], a[3]), cvt_pk_bf16(b[0], b[1]), cvt_pk_bf16(b[2], b[3])}; *(u32x4*)p = w; }
; DI f32x4 silu4(f32x4 v) { f32x4 r; r[0] = silu_f(v[0]); r[1] = silu_f(v[1]); r[2] = silu_f(v[2]); r[3] = silu_f(v[3]); return r; }
;     DI void operator()(const AccT& acc, const pg8::Unit& u, int wr, int wc, int fr, int fq) const {
;     ...
;             for (int m = 0; m < 4; ++m) { const size_t row = (size_t)u.pm * 256 + wr * 64 + fr + ai * 128 + m * 16;
;                 st[m] = *(const float2*)(stats + (row * 4 + head) * 2);
; #pragma unroll
;                 for (int bj = 0; bj < 2; ++bj) ov[m][bj] = *(const u32x4*)(o + row * 2048 + col0 + bj * 128); }
; #pragma unroll
;             for (int m = 0; m < 4; ++m) { const size_t row = (size_t)u.pm * 256 + wr * 64 + fr + ai * 128 + m * 16;
;                 const float mean = st[m].x * (1.f / 512.f), var = fmaxf(st[m].y * (1.f / 512.f) - mean * mean, 0.f), rstd = rsqrtf(var + 1e-5f);
; #pragma unroll
;                 for (int bj = 0; bj < 2; ++bj) { bf16_t* op = o + row * 2048 + col0 + bj * 128; const u32x4 w = ov[m][bj];
;                     const f32x4 s0 = silu4(acc[ai][bj][m][0]), s1 = silu4(acc[ai][bj][m][1]);
;                     f32x4 y0, y1;
;                     y0[0] = (bflo(w[0]) - mean) * rstd * g0[bj][0] * s0[0]; y0[1] = (bfhi(w[0]) - mean) * rstd * g0[bj][1] * s0[1];
;                     y0[2] = (bflo(w[1]) - mean) * rstd * g0[bj][2] * s0[2]; y0[3] = (bfhi(w[1]) - mean) * rstd * g0[bj][3] * s0[3];
;                     y1[0] = (bflo(w[2]) - mean) * rstd * g1[bj][0] * s1[0]; y1[1] = (bfhi(w[2]) - mean) * rstd * g1[bj][1] * s1[1];
;                     y1[2] = (bflo(w[3]) - mean) * rstd * g1[bj][2] * s1[2]; y1[3] = (bfhi(w[3]) - mean) * rstd * g1[bj][3] * s1[3];
;                     store8(op, y0, y1); } } }
	v_pk_mul_f32 v[118:119], v[82:83], s[54:55] op_sel_hi:[1,0]
	s_nop 0
	v_fma_f32 v80, -v118, v118, v119
	v_max_f32_e32 v80, 0, v80
	v_add_f32_e32 v80, 0x3727c5ac, v80
	v_mul_f32_e32 v81, 0x4b800000, v80
	v_cmp_gt_f32_e32 vcc, s94, v80
	v_lshlrev_b32_e32 v127, 16, v122
	v_and_b32_e32 v122, 0xffff0000, v122
	v_cndmask_b32_e32 v80, v80, v81, vcc
	v_rsq_f32_e32 v119, v80
	v_lshl_add_u64 v[80:81], v[186:187], 0, v[104:105]
	global_load_dwordx4 v[84:87], v[80:81], off
	s_nop 0
	global_load_dwordx4 v[80:83], v[80:81], off offset:256
	v_sub_f32_e32 v122, v122, v118
	global_load_dwordx2 v[120:121], v[120:121], off
	v_mul_f32_e32 v126, 0x45800000, v119
	v_cndmask_b32_e32 v119, v119, v126, vcc
	v_mul_f32_e32 v129, v122, v119
	v_lshlrev_b32_e32 v122, 16, v123
	v_sub_f32_e32 v122, v122, v118
	v_mul_f32_e32 v131, v122, v119
	v_and_b32_e32 v122, 0xffff0000, v123
	v_sub_f32_e32 v122, v122, v118
	v_mul_f32_e32 v133, v122, v119
	v_mov_b32_e32 v122, v79
	v_mov_b32_e32 v123, v63
	v_pk_mul_f32 v[122:123], v[122:123], v[132:133]
	v_mul_f32_e32 v126, 0xbfb8aa3b, v76
	v_mul_f32_e32 v79, v122, v123
	v_lshlrev_b32_e32 v122, 16, v124
	v_sub_f32_e32 v122, v122, v118
	v_mul_f32_e32 v135, v122, v119
	v_mov_b32_e32 v122, v72
	v_mov_b32_e32 v123, v68
	v_pk_mul_f32 v[122:123], v[122:123], v[134:135]
	v_exp_f32_e32 v126, v126
	v_mul_f32_e32 v72, v122, v123
	v_and_b32_e32 v122, 0xffff0000, v124
	v_sub_f32_e32 v122, v122, v118
	v_mul_f32_e32 v137, v122, v119
	v_mov_b32_e32 v122, v73
	v_mov_b32_e32 v123, v69
	v_pk_mul_f32 v[122:123], v[122:123], v[136:137]
	v_add_f32_e32 v126, 1.0, v126
	v_mul_f32_e32 v73, v122, v123
	v_lshlrev_b32_e32 v122, 16, v125
	v_sub_f32_e32 v122, v122, v118
	v_mul_f32_e32 v139, v122, v119
	v_mov_b32_e32 v122, v74
	v_mov_b32_e32 v123, v70
	v_pk_mul_f32 v[122:123], v[122:123], v[138:139]
	v_rcp_f32_e32 v126, v126
	v_mul_f32_e32 v74, v122, v123
	v_and_b32_e32 v122, 0xffff0000, v125
	v_sub_f32_e32 v122, v122, v118
	v_sub_f32_e32 v127, v127, v118
	v_mul_f32_e32 v141, v122, v119
	v_mov_b32_e32 v122, v75
	v_mul_f32_e32 v75, 0xbfb8aa3b, v64
	v_mul_f32_e32 v127, v127, v119
	v_exp_f32_e32 v124, v75
	v_pk_mul_f32 v[126:127], v[142:143], v[126:127]
	v_mov_b32_e32 v123, v71
	v_mul_f32_e32 v76, v126, v127
	v_mov_b32_e32 v126, v77
	v_mov_b32_e32 v127, v61
	v_pk_mul_f32 v[122:123], v[122:123], v[140:141]
	v_pk_mul_f32 v[126:127], v[126:127], v[128:129]
	v_mul_f32_e32 v75, v122, v123
	v_mul_f32_e32 v122, 0xbfb8aa3b, v65
	v_mul_f32_e32 v77, v126, v127
	v_mov_b32_e32 v126, v78
	v_mov_b32_e32 v127, v62
	v_exp_f32_e32 v123, v122
	v_add_f32_e32 v122, 1.0, v124
	v_mul_f32_e32 v124, 0xbfb8aa3b, v66
	v_pk_mul_f32 v[126:127], v[126:127], v[130:131]
	v_exp_f32_e32 v125, v124
	v_mul_f32_e32 v124, 0xbfb8aa3b, v67
	v_mul_f32_e32 v78, v126, v127
	v_exp_f32_e32 v127, v124
	v_add_f32_e32 v123, 1.0, v123
	v_rcp_f32_e32 v124, v123
	v_add_f32_e32 v123, 1.0, v125
	v_mul_f32_e32 v125, 0xbfb8aa3b, v52
	v_rcp_f32_e32 v126, v123
	v_add_f32_e32 v123, 1.0, v127
	v_exp_f32_e32 v125, v125
	v_mul_f32_e32 v127, 0xbfb8aa3b, v53
	v_exp_f32_e32 v127, v127
	v_rcp_f32_e32 v128, v123
	v_add_f32_e32 v123, 1.0, v125
	v_mul_f32_e32 v125, 0xbfb8aa3b, v54
	v_rcp_f32_e32 v130, v123
	v_add_f32_e32 v123, 1.0, v127
	v_exp_f32_e32 v125, v125
	v_mul_f32_e32 v127, 0xbfb8aa3b, v55
	v_exp_f32_e32 v127, v127
	v_rcp_f32_e32 v132, v123
	v_add_f32_e32 v123, 1.0, v125
	v_rcp_f32_e32 v134, v123
	v_add_f32_e32 v123, 1.0, v127
	v_rcp_f32_e32 v136, v123
	v_lshlrev_b32_e32 v123, 16, v100
	v_and_b32_e32 v100, 0xffff0000, v100
	v_sub_f32_e32 v100, v100, v118
	v_mul_f32_e32 v125, v100, v119
	v_lshlrev_b32_e32 v100, 16, v101
	v_sub_f32_e32 v100, v100, v118
	v_mul_f32_e32 v127, v100, v119
	v_and_b32_e32 v100, 0xffff0000, v101
	v_sub_f32_e32 v100, v100, v118
	v_mul_f32_e32 v129, v100, v119
	v_mov_b32_e32 v100, v67
	v_mov_b32_e32 v101, v59
	v_pk_mul_f32 v[100:101], v[100:101], v[128:129]
	v_sub_f32_e32 v123, v123, v118
	v_mul_f32_e32 v67, v100, v101
	v_lshlrev_b32_e32 v100, 16, v102
	v_sub_f32_e32 v100, v100, v118
	v_mul_f32_e32 v131, v100, v119
	v_mov_b32_e32 v100, v52
	v_and_b32_e32 v52, 0xffff0000, v102
	v_sub_f32_e32 v52, v52, v118
	v_mov_b32_e32 v101, v48
	v_mul_f32_e32 v133, v52, v119
	v_mov_b32_e32 v52, v53
	v_mov_b32_e32 v53, v49
	v_pk_mul_f32 v[100:101], v[100:101], v[130:131]
	v_pk_mul_f32 v[52:53], v[52:53], v[132:133]
	v_mul_f32_e32 v100, v100, v101
	v_mul_f32_e32 v101, v52, v53
	v_lshlrev_b32_e32 v52, 16, v103
	v_sub_f32_e32 v52, v52, v118
	v_mul_f32_e32 v135, v52, v119
	v_mov_b32_e32 v52, v54
	v_mov_b32_e32 v53, v50
	v_pk_mul_f32 v[52:53], v[52:53], v[134:135]
	v_rcp_f32_e32 v122, v122
	v_mul_f32_e32 v102, v52, v53
	v_and_b32_e32 v52, 0xffff0000, v103
	v_sub_f32_e32 v52, v52, v118
	v_mul_f32_e32 v137, v52, v119
	v_mov_b32_e32 v52, v55
	s_waitcnt vmcnt(0)
; DI float bflo(unsigned w) { return __uint_as_float(w << 16); }
; DI float bfhi(unsigned w) { return __uint_as_float(w & 0xffff0000u); }
; DI void store8(bf16_t* p, f32x4 a, f32x4 b) { u32x4 w = {cvt_pk_bf16(a[0], a[1]), cvt_pk_bf16(a[2], a[3]), cvt_pk_bf16(b[0], b[1]), cvt_pk_bf16(b[2], b[3])}; *(u32x4*)p = w; }
; DI f32x4 silu4(f32x4 v) { f32x4 r; r[0] = silu_f(v[0]); r[1] = silu_f(v[1]); r[2] = silu_f(v[2]); r[3] = silu_f(v[3]); return r; }
;     DI void operator()(const AccT& acc, const pg8::Unit& u, int wr, int wc, int fr, int fq) const {
;     ...
;             for (int m = 0; m < 4; ++m) { const size_t row = (size_t)u.pm * 256 + wr * 64 + fr + ai * 128 + m * 16;
;                 st[m] = *(const float2*)(stats + (row * 4 + head) * 2);
; #pragma unroll
;                 for (int bj = 0; bj < 2; ++bj) ov[m][bj] = *(const u32x4*)(o + row * 2048 + col0 + bj * 128); }
; #pragma unroll
;             for (int m = 0; m < 4; ++m) { const size_t row = (size_t)u.pm * 256 + wr * 64 + fr + ai * 128 + m * 16;
;                 const float mean = st[m].x * (1.f / 512.f), var = fmaxf(st[m].y * (1.f / 512.f) - mean * mean, 0.f), rstd = rsqrtf(var + 1e-5f);
; #pragma unroll
;                 for (int bj = 0; bj < 2; ++bj) { bf16_t* op = o + row * 2048 + col0 + bj * 128; const u32x4 w = ov[m][bj];
;                     const f32x4 s0 = silu4(acc[ai][bj][m][0]), s1 = silu4(acc[ai][bj][m][1]);
;                     f32x4 y0, y1;
;                     y0[0] = (bflo(w[0]) - mean) * rstd * g0[bj][0] * s0[0]; y0[1] = (bfhi(w[0]) - mean) * rstd * g0[bj][1] * s0[1];
;                     y0[2] = (bflo(w[1]) - mean) * rstd * g0[bj][2] * s0[2]; y0[3] = (bfhi(w[1]) - mean) * rstd * g0[bj][3] * s0[3];
;                     y1[0] = (bflo(w[2]) - mean) * rstd * g1[bj][0] * s1[0]; y1[1] = (bfhi(w[2]) - mean) * rstd * g1[bj][1] * s1[1];
;                     y1[2] = (bflo(w[3]) - mean) * rstd * g1[bj][2] * s1[2]; y1[3] = (bfhi(w[3]) - mean) * rstd * g1[bj][3] * s1[3];
;                     store8(op, y0, y1); } } }
	v_pk_mul_f32 v[54:55], v[120:121], s[54:55] op_sel_hi:[1,0]
	v_mul_f32_e32 v118, 0xbfb8aa3b, v46
	v_fma_f32 v53, -v54, v54, v55
	v_max_f32_e32 v53, 0, v53
	v_add_f32_e32 v53, 0x3727c5ac, v53
	v_mul_f32_e32 v55, 0x4b800000, v53
	v_cmp_gt_f32_e32 vcc, s94, v53
	v_mul_f32_e32 v123, v123, v119
	v_exp_f32_e32 v119, v118
	v_cndmask_b32_e32 v53, v53, v55, vcc
	v_rsq_f32_e32 v103, v53
	v_mov_b32_e32 v53, v51
	v_pk_mul_f32 v[52:53], v[52:53], v[136:137]
	v_mul_f32_e32 v118, 0xbfb8aa3b, v47
	v_mul_f32_e32 v55, v52, v53
	v_mul_f32_e32 v52, 0x45800000, v103
	v_cndmask_b32_e32 v103, v103, v52, vcc
	v_lshl_add_u64 v[52:53], s[96:97], 0, v[116:117]
	v_mul_f32_e32 v117, 0xbfb8aa3b, v45
	v_exp_f32_e32 v117, v117
	v_exp_f32_e32 v121, v118
	v_mov_b32_e32 v138, v64
	v_mov_b32_e32 v139, v56
	v_add_f32_e32 v117, 1.0, v117
	v_pk_mul_f32 v[122:123], v[138:139], v[122:123]
	v_rcp_f32_e32 v118, v117
	v_add_f32_e32 v117, 1.0, v119
	v_mul_f32_e32 v119, 0xbfb8aa3b, v40
	v_mul_f32_e32 v64, v122, v123
	v_mov_b32_e32 v122, v65
	v_mov_b32_e32 v123, v57
	v_rcp_f32_e32 v120, v117
	v_add_f32_e32 v117, 1.0, v121
	v_exp_f32_e32 v119, v119
	v_mul_f32_e32 v121, 0xbfb8aa3b, v41
	v_pk_mul_f32 v[122:123], v[122:123], v[124:125]
	v_exp_f32_e32 v121, v121
	v_mul_f32_e32 v65, v122, v123
	v_mov_b32_e32 v122, v66
	v_mov_b32_e32 v123, v58
	v_pk_mul_f32 v[122:123], v[122:123], v[126:127]
	v_mul_f32_e32 v116, 0xbfb8aa3b, v44
	v_mul_f32_e32 v66, v122, v123
	v_rcp_f32_e32 v122, v117
	v_add_f32_e32 v117, 1.0, v119
	v_mul_f32_e32 v119, 0xbfb8aa3b, v42
	v_rcp_f32_e32 v124, v117
	v_add_f32_e32 v117, 1.0, v121
	v_exp_f32_e32 v119, v119
	v_mul_f32_e32 v121, 0xbfb8aa3b, v43
	v_exp_f32_e32 v121, v121
	v_rcp_f32_e32 v126, v117
	v_add_f32_e32 v117, 1.0, v119
	v_rcp_f32_e32 v128, v117
	v_add_f32_e32 v117, 1.0, v121
	v_rcp_f32_e32 v130, v117
	v_lshlrev_b32_e32 v117, 16, v96
	v_and_b32_e32 v96, 0xffff0000, v96
	v_sub_f32_e32 v96, v96, v54
	v_mul_f32_e32 v119, v96, v103
	v_lshlrev_b32_e32 v96, 16, v97
	v_sub_f32_e32 v96, v96, v54
	v_mul_f32_e32 v121, v96, v103
	v_and_b32_e32 v96, 0xffff0000, v97
	v_sub_f32_e32 v96, v96, v54
	v_mul_f32_e32 v123, v96, v103
	v_mov_b32_e32 v96, v47
	v_mov_b32_e32 v97, v63
	v_pk_mul_f32 v[96:97], v[96:97], v[122:123]
	v_exp_f32_e32 v116, v116
	v_mul_f32_e32 v47, v96, v97
	v_lshlrev_b32_e32 v96, 16, v98
	v_sub_f32_e32 v96, v96, v54
	v_mul_f32_e32 v125, v96, v103
	v_mov_b32_e32 v96, v40
	v_and_b32_e32 v40, 0xffff0000, v98
	v_sub_f32_e32 v40, v40, v54
	v_mov_b32_e32 v97, v68
	v_mul_f32_e32 v127, v40, v103
	v_mov_b32_e32 v40, v41
	v_mov_b32_e32 v41, v69
	v_pk_mul_f32 v[96:97], v[96:97], v[124:125]
	v_pk_mul_f32 v[40:41], v[40:41], v[126:127]
	v_add_f32_e32 v116, 1.0, v116
	v_mul_f32_e32 v96, v96, v97
	v_mul_f32_e32 v97, v40, v41
	v_lshlrev_b32_e32 v40, 16, v99
	v_rcp_f32_e32 v116, v116
	v_sub_f32_e32 v40, v40, v54
	v_mul_f32_e32 v129, v40, v103
	v_mov_b32_e32 v40, v42
	v_mov_b32_e32 v41, v70
	v_sub_f32_e32 v117, v117, v54
	v_pk_mul_f32 v[40:41], v[40:41], v[128:129]
	v_mul_f32_e32 v117, v117, v103
	v_mov_b32_e32 v132, v44
	v_mov_b32_e32 v133, v60
	v_mul_f32_e32 v98, v40, v41
	v_mul_f32_e32 v41, 0xbfb8aa3b, v36
	v_pk_mul_f32 v[116:117], v[132:133], v[116:117]
	v_and_b32_e32 v40, 0xffff0000, v99
	v_exp_f32_e32 v42, v41
	v_mul_f32_e32 v44, v116, v117
	v_mov_b32_e32 v116, v45
	v_mov_b32_e32 v117, v61
	v_sub_f32_e32 v40, v40, v54
	v_pk_mul_f32 v[116:117], v[116:117], v[118:119]
	v_mul_f32_e32 v131, v40, v103
	v_mov_b32_e32 v40, v43
	v_mov_b32_e32 v41, v71
	v_mul_f32_e32 v45, v116, v117
	v_mov_b32_e32 v116, v46
	v_mov_b32_e32 v117, v62
	v_pk_mul_f32 v[40:41], v[40:41], v[130:131]
	v_pk_mul_f32 v[116:117], v[116:117], v[120:121]
	v_mul_f32_e32 v99, v40, v41
	v_add_f32_e32 v40, 1.0, v42
	v_mul_f32_e32 v41, 0xbfb8aa3b, v37
	v_mul_f32_e32 v46, v116, v117
	v_exp_f32_e32 v117, v41
	v_rcp_f32_e32 v116, v40
	global_load_dwordx4 v[40:43], v[114:115], off
	s_nop 0
	global_load_dwordx2 v[112:113], v[112:113], off
	v_mul_f32_e32 v115, 0xbfb8aa3b, v38
	v_add_f32_e32 v114, 1.0, v117
	v_exp_f32_e32 v115, v115
	v_mul_f32_e32 v117, 0xbfb8aa3b, v39
	v_exp_f32_e32 v117, v117
	v_mul_f32_e32 v119, 0xbfb8aa3b, v33
	v_add_f32_e32 v115, 1.0, v115
	v_rcp_f32_e32 v118, v115
	v_add_f32_e32 v115, 1.0, v117
	v_mul_f32_e32 v117, 0xbfb8aa3b, v32
	v_exp_f32_e32 v117, v117
	v_exp_f32_e32 v119, v119
	v_rcp_f32_e32 v120, v115
	v_rcp_f32_e32 v114, v114
	v_add_f32_e32 v115, 1.0, v117
	v_mul_f32_e32 v117, 0xbfb8aa3b, v34
	v_rcp_f32_e32 v122, v115
	v_add_f32_e32 v115, 1.0, v119
	v_exp_f32_e32 v117, v117
	v_mul_f32_e32 v119, 0xbfb8aa3b, v35
	v_exp_f32_e32 v119, v119
	v_rcp_f32_e32 v124, v115
	v_add_f32_e32 v115, 1.0, v117
	v_rcp_f32_e32 v126, v115
	v_add_f32_e32 v115, 1.0, v119
	v_rcp_f32_e32 v128, v115
	v_lshlrev_b32_e32 v115, 16, v92
	v_mov_b32_e32 v130, v36
	v_and_b32_e32 v36, 0xffff0000, v92
	v_sub_f32_e32 v115, v115, v54
	v_sub_f32_e32 v36, v36, v54
	v_mul_f32_e32 v117, v115, v103
	v_mul_f32_e32 v115, v36, v103
	v_mov_b32_e32 v36, v37
	v_mov_b32_e32 v37, v57
	v_mov_b32_e32 v131, v56
	v_pk_mul_f32 v[36:37], v[36:37], v[114:115]
	v_pk_mul_f32 v[116:117], v[130:131], v[116:117]
	v_mul_f32_e32 v131, v36, v37
	v_lshlrev_b32_e32 v36, 16, v93
	v_sub_f32_e32 v36, v36, v54
	v_mul_f32_e32 v119, v36, v103
	v_mov_b32_e32 v36, v38
	v_mov_b32_e32 v37, v58
	v_pk_mul_f32 v[36:37], v[36:37], v[118:119]
	v_mul_f32_e32 v38, 0xbfb8aa3b, v30
	v_mul_f32_e32 v132, v36, v37
	v_and_b32_e32 v36, 0xffff0000, v93
	v_sub_f32_e32 v36, v36, v54
	v_mul_f32_e32 v121, v36, v103
	v_mov_b32_e32 v36, v39
	v_mov_b32_e32 v37, v59
	v_pk_mul_f32 v[36:37], v[36:37], v[120:121]
	v_exp_f32_e32 v39, v38
	v_mul_f32_e32 v120, v36, v37
	v_lshlrev_b32_e32 v36, 16, v94
	v_sub_f32_e32 v36, v36, v54
	v_mul_f32_e32 v123, v36, v103
	v_mov_b32_e32 v36, v32
	v_and_b32_e32 v32, 0xffff0000, v94
	v_sub_f32_e32 v32, v32, v54
	v_mul_f32_e32 v125, v32, v103
	v_mov_b32_e32 v32, v33
	v_mov_b32_e32 v33, v49
	v_mov_b32_e32 v37, v48
	v_pk_mul_f32 v[32:33], v[32:33], v[124:125]
	v_pk_mul_f32 v[36:37], v[36:37], v[122:123]
	v_mul_f32_e32 v122, v32, v33
	v_lshlrev_b32_e32 v32, 16, v95
	v_sub_f32_e32 v32, v32, v54
	v_mul_f32_e32 v127, v32, v103
	v_mov_b32_e32 v32, v34
	v_mov_b32_e32 v33, v50
	v_pk_mul_f32 v[32:33], v[32:33], v[126:127]
	v_mul_f32_e32 v121, v36, v37
	v_mul_f32_e32 v123, v32, v33
	v_and_b32_e32 v32, 0xffff0000, v95
	v_sub_f32_e32 v32, v32, v54
	v_mul_f32_e32 v37, 0xbfb8aa3b, v29
	v_mul_f32_e32 v129, v32, v103
	v_mov_b32_e32 v32, v35
	s_waitcnt vmcnt(0)
; DI float bflo(unsigned w) { return __uint_as_float(w << 16); }
; DI float bfhi(unsigned w) { return __uint_as_float(w & 0xffff0000u); }
; DI void store8(bf16_t* p, f32x4 a, f32x4 b) { u32x4 w = {cvt_pk_bf16(a[0], a[1]), cvt_pk_bf16(a[2], a[3]), cvt_pk_bf16(b[0], b[1]), cvt_pk_bf16(b[2], b[3])}; *(u32x4*)p = w; }
; DI f32x4 silu4(f32x4 v) { f32x4 r; r[0] = silu_f(v[0]); r[1] = silu_f(v[1]); r[2] = silu_f(v[2]); r[3] = silu_f(v[3]); return r; }
;     DI void operator()(const AccT& acc, const pg8::Unit& u, int wr, int wc, int fr, int fq) const {
;     ...
;             for (int m = 0; m < 4; ++m) { const size_t row = (size_t)u.pm * 256 + wr * 64 + fr + ai * 128 + m * 16;
;                 st[m] = *(const float2*)(stats + (row * 4 + head) * 2);
; #pragma unroll
;                 for (int bj = 0; bj < 2; ++bj) ov[m][bj] = *(const u32x4*)(o + row * 2048 + col0 + bj * 128); }
; #pragma unroll
;             for (int m = 0; m < 4; ++m) { const size_t row = (size_t)u.pm * 256 + wr * 64 + fr + ai * 128 + m * 16;
;                 const float mean = st[m].x * (1.f / 512.f), var = fmaxf(st[m].y * (1.f / 512.f) - mean * mean, 0.f), rstd = rsqrtf(var + 1e-5f);
; #pragma unroll
;                 for (int bj = 0; bj < 2; ++bj) { bf16_t* op = o + row * 2048 + col0 + bj * 128; const u32x4 w = ov[m][bj];
;                     const f32x4 s0 = silu4(acc[ai][bj][m][0]), s1 = silu4(acc[ai][bj][m][1]);
;                     f32x4 y0, y1;
;                     y0[0] = (bflo(w[0]) - mean) * rstd * g0[bj][0] * s0[0]; y0[1] = (bfhi(w[0]) - mean) * rstd * g0[bj][1] * s0[1];
;                     y0[2] = (bflo(w[1]) - mean) * rstd * g0[bj][2] * s0[2]; y0[3] = (bfhi(w[1]) - mean) * rstd * g0[bj][3] * s0[3];
;                     y1[0] = (bflo(w[2]) - mean) * rstd * g1[bj][0] * s1[0]; y1[1] = (bfhi(w[2]) - mean) * rstd * g1[bj][1] * s1[1];
;                     y1[2] = (bflo(w[3]) - mean) * rstd * g1[bj][2] * s1[2]; y1[3] = (bfhi(w[3]) - mean) * rstd * g1[bj][3] * s1[3];
;                     store8(op, y0, y1); } } }
	v_pk_mul_f32 v[34:35], v[112:113], s[54:55] op_sel_hi:[1,0]
	v_exp_f32_e32 v37, v37
	v_fma_f32 v33, -v34, v34, v35
	v_mul_f32_e32 v38, 0xbfb8aa3b, v31
	v_max_f32_e32 v33, 0, v33
	v_exp_f32_e32 v93, v38
	v_add_f32_e32 v33, 0x3727c5ac, v33
	v_mul_f32_e32 v35, 0x4b800000, v33
	v_cmp_gt_f32_e32 vcc, s94, v33
	v_add_f32_e32 v37, 1.0, v37
	v_rcp_f32_e32 v38, v37
	v_cndmask_b32_e32 v33, v33, v35, vcc
	v_add_f32_e32 v37, 1.0, v39
	v_mul_f32_e32 v39, 0xbfb8aa3b, v24
	v_rsq_f32_e32 v35, v33
	v_rcp_f32_e32 v92, v37
	v_add_f32_e32 v37, 1.0, v93
	v_exp_f32_e32 v39, v39
	v_mul_f32_e32 v93, 0xbfb8aa3b, v25
	v_exp_f32_e32 v93, v93
	v_mov_b32_e32 v33, v51
	v_pk_mul_f32 v[32:33], v[32:33], v[128:129]
	v_mul_f32_e32 v36, 0xbfb8aa3b, v28
	v_mul_f32_e32 v54, v32, v33
	v_mul_f32_e32 v32, 0x45800000, v35
	v_rcp_f32_e32 v94, v37
	v_add_f32_e32 v37, 1.0, v39
	v_mul_f32_e32 v39, 0xbfb8aa3b, v26
	v_cndmask_b32_e32 v35, v35, v32, vcc
	v_lshl_add_u64 v[32:33], s[96:97], 0, v[110:111]
	v_exp_f32_e32 v36, v36
	v_rcp_f32_e32 v110, v37
	v_add_f32_e32 v37, 1.0, v93
	v_exp_f32_e32 v39, v39
	v_mul_f32_e32 v93, 0xbfb8aa3b, v27
	v_exp_f32_e32 v93, v93
	v_add_f32_e32 v36, 1.0, v36
	v_rcp_f32_e32 v112, v37
	v_add_f32_e32 v37, 1.0, v39
	v_rcp_f32_e32 v36, v36
	v_rcp_f32_e32 v114, v37
	v_add_f32_e32 v37, 1.0, v93
	v_mov_b32_e32 v118, v28
	v_and_b32_e32 v28, 0xffff0000, v40
	v_mul_f32_e32 v130, v116, v117
	v_rcp_f32_e32 v116, v37
	v_lshlrev_b32_e32 v37, 16, v40
	v_sub_f32_e32 v28, v28, v34
	v_sub_f32_e32 v37, v37, v34
	v_mul_f32_e32 v39, v28, v35
	v_mov_b32_e32 v28, v29
	v_mov_b32_e32 v29, v61
	v_mul_f32_e32 v37, v37, v35
	v_mov_b32_e32 v119, v60
	v_pk_mul_f32 v[28:29], v[28:29], v[38:39]
	v_pk_mul_f32 v[36:37], v[118:119], v[36:37]
	v_mul_f32_e32 v118, v28, v29
	v_lshlrev_b32_e32 v28, 16, v41
	v_sub_f32_e32 v28, v28, v34
	v_mul_f32_e32 v93, v28, v35
	v_mov_b32_e32 v28, v30
	v_mov_b32_e32 v29, v62
	v_pk_mul_f32 v[28:29], v[28:29], v[92:93]
	global_load_dwordx2 v[92:93], v[108:109], off
	v_mul_f32_e32 v119, v28, v29
	v_and_b32_e32 v28, 0xffff0000, v41
	v_sub_f32_e32 v28, v28, v34
	v_mul_f32_e32 v95, v28, v35
	v_mov_b32_e32 v28, v31
	v_mov_b32_e32 v29, v63
	v_pk_mul_f32 v[28:29], v[28:29], v[94:95]
	v_mul_f32_e32 v103, v36, v37
	v_mul_f32_e32 v124, v28, v29
	v_lshlrev_b32_e32 v28, 16, v42
	v_sub_f32_e32 v28, v28, v34
	v_mul_f32_e32 v111, v28, v35
	v_mov_b32_e32 v28, v24
	v_and_b32_e32 v24, 0xffff0000, v42
	v_sub_f32_e32 v24, v24, v34
	v_mul_f32_e32 v113, v24, v35
	v_mov_b32_e32 v24, v25
	v_mov_b32_e32 v25, v69
	v_mov_b32_e32 v29, v68
	v_pk_mul_f32 v[24:25], v[24:25], v[112:113]
	v_pk_mul_f32 v[28:29], v[28:29], v[110:111]
	v_mul_f32_e32 v111, v24, v25
	v_lshlrev_b32_e32 v24, 16, v43
	v_sub_f32_e32 v24, v24, v34
	v_mul_f32_e32 v115, v24, v35
	v_mov_b32_e32 v24, v26
	v_mov_b32_e32 v25, v70
	v_pk_mul_f32 v[24:25], v[24:25], v[114:115]
	v_mul_f32_e32 v26, 0xbfb8aa3b, v20
	v_mul_f32_e32 v112, v24, v25
	v_and_b32_e32 v24, 0xffff0000, v43
	v_sub_f32_e32 v24, v24, v34
	v_mul_f32_e32 v117, v24, v35
	v_mov_b32_e32 v24, v27
	v_exp_f32_e32 v26, v26
	v_mul_f32_e32 v27, 0xbfb8aa3b, v21
	v_exp_f32_e32 v27, v27
	v_mov_b32_e32 v25, v71
	v_pk_mul_f32 v[24:25], v[24:25], v[116:117]
	v_mul_f32_e32 v110, v28, v29
	v_mul_f32_e32 v113, v24, v25
	v_add_f32_e32 v24, 1.0, v26
	v_mul_f32_e32 v26, 0xbfb8aa3b, v22
	v_add_f32_e32 v25, 1.0, v27
	v_exp_f32_e32 v27, v26
	v_mul_f32_e32 v26, 0xbfb8aa3b, v23
	v_exp_f32_e32 v29, v26
	v_rcp_f32_e32 v26, v25
	v_add_f32_e32 v25, 1.0, v27
	v_mul_f32_e32 v27, 0xbfb8aa3b, v16
	v_rcp_f32_e32 v28, v25
	v_add_f32_e32 v25, 1.0, v29
	v_exp_f32_e32 v27, v27
	v_mul_f32_e32 v29, 0xbfb8aa3b, v17
	v_exp_f32_e32 v29, v29
	v_rcp_f32_e32 v30, v25
	v_add_f32_e32 v25, 1.0, v27
	v_mul_f32_e32 v27, 0xbfb8aa3b, v18
	v_rcp_f32_e32 v36, v25
	v_add_f32_e32 v25, 1.0, v29
	v_exp_f32_e32 v27, v27
	v_mul_f32_e32 v29, 0xbfb8aa3b, v19
	v_exp_f32_e32 v29, v29
	v_rcp_f32_e32 v38, v25
	v_add_f32_e32 v25, 1.0, v27
	v_rcp_f32_e32 v24, v24
	v_rcp_f32_e32 v40, v25
	v_add_f32_e32 v25, 1.0, v29
	v_rcp_f32_e32 v42, v25
	v_lshlrev_b32_e32 v25, 16, v88
	v_mov_b32_e32 v94, v20
	v_and_b32_e32 v20, 0xffff0000, v88
	v_sub_f32_e32 v25, v25, v34
	v_sub_f32_e32 v20, v20, v34
	v_mul_f32_e32 v25, v25, v35
	v_mov_b32_e32 v95, v56
	v_mul_f32_e32 v27, v20, v35
	v_mov_b32_e32 v20, v21
	v_mov_b32_e32 v21, v57
	v_pk_mul_f32 v[24:25], v[94:95], v[24:25]
	v_pk_mul_f32 v[20:21], v[20:21], v[26:27]
	v_mul_f32_e32 v24, v24, v25
	v_mul_f32_e32 v25, v20, v21
	v_lshlrev_b32_e32 v20, 16, v89
	v_sub_f32_e32 v20, v20, v34
	v_mul_f32_e32 v29, v20, v35
	v_mov_b32_e32 v20, v22
	v_mov_b32_e32 v21, v58
	v_pk_mul_f32 v[20:21], v[20:21], v[28:29]
	v_lshl_add_u64 v[52:53], v[52:53], 0, v[184:185]
	v_mul_f32_e32 v22, v20, v21
	v_and_b32_e32 v20, 0xffff0000, v89
	v_sub_f32_e32 v20, v20, v34
	v_mul_f32_e32 v31, v20, v35
	v_mov_b32_e32 v20, v23
	v_mov_b32_e32 v21, v59
	v_pk_mul_f32 v[20:21], v[20:21], v[30:31]
	v_lshl_add_u64 v[32:33], v[32:33], 0, v[184:185]
	v_mul_f32_e32 v23, v20, v21
	v_lshlrev_b32_e32 v20, 16, v90
	v_sub_f32_e32 v20, v20, v34
	v_mul_f32_e32 v37, v20, v35
	v_mov_b32_e32 v20, v16
	v_and_b32_e32 v16, 0xffff0000, v90
	v_sub_f32_e32 v16, v16, v34
	v_mov_b32_e32 v21, v48
	v_mul_f32_e32 v39, v16, v35
	v_mov_b32_e32 v16, v17
	v_mov_b32_e32 v17, v49
	v_pk_mul_f32 v[20:21], v[20:21], v[36:37]
	v_pk_mul_f32 v[16:17], v[16:17], v[38:39]
	v_mul_f32_e32 v20, v20, v21
	v_mul_f32_e32 v21, v16, v17
	v_lshlrev_b32_e32 v16, 16, v91
	v_sub_f32_e32 v16, v16, v34
	v_mul_f32_e32 v41, v16, v35
	v_mov_b32_e32 v16, v18
	v_mov_b32_e32 v17, v50
	v_pk_mul_f32 v[16:17], v[16:17], v[40:41]
	v_mov_b32_e32 v36, v12
	v_mul_f32_e32 v26, v16, v17
	v_and_b32_e32 v16, 0xffff0000, v91
	v_sub_f32_e32 v16, v16, v34
	v_mul_f32_e32 v43, v16, v35
	v_mov_b32_e32 v16, v19
	v_mov_b32_e32 v17, v51
	v_pk_mul_f32 v[16:17], v[16:17], v[42:43]
	v_mov_b32_e32 v37, v60
	v_mul_f32_e32 v27, v16, v17
	v_cvt_pk_bf16_f32 v16, v76, v77
	v_cvt_pk_bf16_f32 v17, v78, v79
	v_cvt_pk_bf16_f32 v18, v72, v73
	v_cvt_pk_bf16_f32 v19, v74, v75
	global_store_dwordx4 v[106:107], v[16:19], off
	v_mov_b32_e32 v60, v13
	s_nop 0
	v_cvt_pk_bf16_f32 v16, v64, v65
	v_cvt_pk_bf16_f32 v17, v66, v67
	v_cvt_pk_bf16_f32 v18, v100, v101
	v_cvt_pk_bf16_f32 v19, v102, v55
	global_store_dwordx4 v[106:107], v[16:19], off offset:256
	s_nop 1
	v_cvt_pk_bf16_f32 v16, v44, v45
	v_cvt_pk_bf16_f32 v17, v46, v47
	v_cvt_pk_bf16_f32 v18, v96, v97
	v_cvt_pk_bf16_f32 v19, v98, v99
	global_store_dwordx4 v[52:53], v[16:19], off
	s_nop 1
	v_cvt_pk_bf16_f32 v16, v130, v131
	v_cvt_pk_bf16_f32 v17, v132, v120
	v_cvt_pk_bf16_f32 v18, v121, v122
	v_cvt_pk_bf16_f32 v19, v123, v54
	global_store_dwordx4 v[52:53], v[16:19], off offset:256
	s_nop 1
	v_cvt_pk_bf16_f32 v16, v103, v118
	v_cvt_pk_bf16_f32 v17, v119, v124
	v_cvt_pk_bf16_f32 v18, v110, v111
	v_cvt_pk_bf16_f32 v19, v112, v113
	global_store_dwordx4 v[32:33], v[16:19], off
	s_waitcnt vmcnt(0)
; DI float bflo(unsigned w) { return __uint_as_float(w << 16); }
; DI float bfhi(unsigned w) { return __uint_as_float(w & 0xffff0000u); }
; #define PG8_WAIT_V(n) asm volatile("s_waitcnt vmcnt(" #n ")" ::: "memory")
; #define PG8_BAR __builtin_amdgcn_s_barrier()
; DI void store8(bf16_t* p, f32x4 a, f32x4 b) { u32x4 w = {cvt_pk_bf16(a[0], a[1]), cvt_pk_bf16(a[2], a[3]), cvt_pk_bf16(b[0], b[1]), cvt_pk_bf16(b[2], b[3])}; *(u32x4*)p = w; }
; DI f32x4 silu4(f32x4 v) { f32x4 r; r[0] = silu_f(v[0]); r[1] = silu_f(v[1]); r[2] = silu_f(v[2]); r[3] = silu_f(v[3]); return r; }
; template <class Epi, class Sched>
; __device__ __forceinline__ void gemm_phase(PG8_LAS unsigned char* lds, const Gemm g, const Sched& S, const Epi& E) {
;     ...
;     PG8_WAIT_V(0);
;     if (wr == 0) PG8_BAR;
;     PG8_BAR;
;     DI void operator()(const AccT& acc, const pg8::Unit& u, int wr, int wc, int fr, int fq) const {
;     ...
;             for (int m = 0; m < 4; ++m) { const size_t row = (size_t)u.pm * 256 + wr * 64 + fr + ai * 128 + m * 16;
;                 const float mean = st[m].x * (1.f / 512.f), var = fmaxf(st[m].y * (1.f / 512.f) - mean * mean, 0.f), rstd = rsqrtf(var + 1e-5f);
; #pragma unroll
;                 for (int bj = 0; bj < 2; ++bj) { bf16_t* op = o + row * 2048 + col0 + bj * 128; const u32x4 w = ov[m][bj];
;                     const f32x4 s0 = silu4(acc[ai][bj][m][0]), s1 = silu4(acc[ai][bj][m][1]);
;                     f32x4 y0, y1;
;                     y0[0] = (bflo(w[0]) - mean) * rstd * g0[bj][0] * s0[0]; y0[1] = (bfhi(w[0]) - mean) * rstd * g0[bj][1] * s0[1];
;                     y0[2] = (bflo(w[1]) - mean) * rstd * g0[bj][2] * s0[2]; y0[3] = (bfhi(w[1]) - mean) * rstd * g0[bj][3] * s0[3];
;                     y1[0] = (bflo(w[2]) - mean) * rstd * g1[bj][0] * s1[0]; y1[1] = (bfhi(w[2]) - mean) * rstd * g1[bj][1] * s1[1];
;                     y1[2] = (bflo(w[3]) - mean) * rstd * g1[bj][2] * s1[2]; y1[3] = (bfhi(w[3]) - mean) * rstd * g1[bj][3] * s1[3];
;                     store8(op, y0, y1); } } }
	s_nop 0
	v_pk_mul_f32 v[16:17], v[92:93], s[54:55] op_sel_hi:[1,0]
	v_cvt_pk_bf16_f32 v18, v24, v25
	v_cvt_pk_bf16_f32 v19, v22, v23
	v_cvt_pk_bf16_f32 v20, v20, v21
	v_cvt_pk_bf16_f32 v21, v26, v27
	global_store_dwordx4 v[32:33], v[18:21], off offset:256
	v_fma_f32 v17, -v16, v16, v17
	v_max_f32_e32 v17, 0, v17
	v_add_f32_e32 v17, 0x3727c5ac, v17
	v_mul_f32_e32 v22, 0x4b800000, v17
	v_cmp_gt_f32_e32 vcc, s94, v17
	v_mul_f32_e32 v21, 0xbfb8aa3b, v13
	v_exp_f32_e32 v21, v21
	v_cndmask_b32_e32 v17, v17, v22, vcc
	v_mul_f32_e32 v22, 0xbfb8aa3b, v14
	v_exp_f32_e32 v23, v22
	v_mul_f32_e32 v22, 0xbfb8aa3b, v15
	v_exp_f32_e32 v25, v22
	v_add_f32_e32 v21, 1.0, v21
	v_rcp_f32_e32 v22, v21
	v_add_f32_e32 v21, 1.0, v23
	v_mul_f32_e32 v23, 0xbfb8aa3b, v8
	v_rcp_f32_e32 v24, v21
	v_add_f32_e32 v21, 1.0, v25
	v_exp_f32_e32 v23, v23
	v_mul_f32_e32 v25, 0xbfb8aa3b, v9
	v_exp_f32_e32 v25, v25
	v_mul_f32_e32 v20, 0xbfb8aa3b, v12
	v_rcp_f32_e32 v26, v21
	v_add_f32_e32 v21, 1.0, v23
	v_mul_f32_e32 v23, 0xbfb8aa3b, v10
	v_exp_f32_e32 v20, v20
	v_rcp_f32_e32 v28, v21
	v_add_f32_e32 v21, 1.0, v25
	v_exp_f32_e32 v23, v23
	v_mul_f32_e32 v25, 0xbfb8aa3b, v11
	v_exp_f32_e32 v25, v25
	v_rsq_f32_e32 v17, v17
	v_add_f32_e32 v20, 1.0, v20
	v_rcp_f32_e32 v30, v21
	v_add_f32_e32 v21, 1.0, v23
	v_rcp_f32_e32 v20, v20
	v_rcp_f32_e32 v32, v21
	v_add_f32_e32 v21, 1.0, v25
	v_mul_f32_e32 v18, 0x45800000, v17
	v_rcp_f32_e32 v34, v21
	v_lshlrev_b32_e32 v21, 16, v84
	v_and_b32_e32 v12, 0xffff0000, v84
	v_cndmask_b32_e32 v17, v17, v18, vcc
	v_sub_f32_e32 v21, v21, v16
	v_sub_f32_e32 v12, v12, v16
	v_mul_f32_e32 v21, v21, v17
	v_mul_f32_e32 v23, v12, v17
	v_pk_mul_f32 v[20:21], v[36:37], v[20:21]
	v_pk_mul_f32 v[12:13], v[60:61], v[22:23]
	v_mul_f32_e32 v20, v20, v21
	v_mul_f32_e32 v21, v12, v13
	v_lshlrev_b32_e32 v12, 16, v85
	v_sub_f32_e32 v12, v12, v16
	v_mul_f32_e32 v25, v12, v17
	v_mov_b32_e32 v12, v14
	v_mov_b32_e32 v13, v62
	v_pk_mul_f32 v[12:13], v[12:13], v[24:25]
	v_mov_b32_e32 v62, v15
	v_mul_f32_e32 v14, v12, v13
	v_and_b32_e32 v12, 0xffff0000, v85
	v_sub_f32_e32 v12, v12, v16
	v_mul_f32_e32 v27, v12, v17
	v_pk_mul_f32 v[12:13], v[62:63], v[26:27]
	v_lshl_add_u64 v[18:19], s[96:97], 0, v[104:105]
	v_mul_f32_e32 v15, v12, v13
	v_lshlrev_b32_e32 v12, 16, v86
	v_sub_f32_e32 v12, v12, v16
	v_mul_f32_e32 v29, v12, v17
	v_mov_b32_e32 v12, v8
	v_and_b32_e32 v8, 0xffff0000, v86
	v_sub_f32_e32 v8, v8, v16
	v_mov_b32_e32 v13, v68
	v_mul_f32_e32 v31, v8, v17
	v_mov_b32_e32 v68, v9
	v_pk_mul_f32 v[12:13], v[12:13], v[28:29]
	v_pk_mul_f32 v[8:9], v[68:69], v[30:31]
	v_mul_f32_e32 v12, v12, v13
	v_mul_f32_e32 v13, v8, v9
	v_lshlrev_b32_e32 v8, 16, v87
	v_sub_f32_e32 v8, v8, v16
	v_mul_f32_e32 v33, v8, v17
	v_mov_b32_e32 v8, v10
	v_mov_b32_e32 v9, v70
	v_pk_mul_f32 v[8:9], v[8:9], v[32:33]
	v_mov_b32_e32 v70, v11
	v_mul_f32_e32 v22, v8, v9
	v_and_b32_e32 v8, 0xffff0000, v87
	v_sub_f32_e32 v8, v8, v16
	v_mul_f32_e32 v35, v8, v17
	v_pk_mul_f32 v[8:9], v[70:71], v[34:35]
	v_lshl_add_u64 v[18:19], v[18:19], 0, v[184:185]
	v_mul_f32_e32 v11, v8, v9
	v_cvt_pk_bf16_f32 v8, v20, v21
	v_cvt_pk_bf16_f32 v9, v14, v15
	v_cvt_pk_bf16_f32 v10, v12, v13
	v_mul_f32_e32 v13, 0xbfb8aa3b, v5
	v_exp_f32_e32 v13, v13
	v_cvt_pk_bf16_f32 v11, v22, v11
	global_store_dwordx4 v[18:19], v[8:11], off
	v_mul_f32_e32 v12, 0xbfb8aa3b, v4
	v_exp_f32_e32 v12, v12
	v_mul_f32_e32 v10, 0xbfb8aa3b, v6
	v_exp_f32_e32 v11, v10
	v_mul_f32_e32 v10, 0xbfb8aa3b, v7
	v_add_f32_e32 v9, 1.0, v13
	v_exp_f32_e32 v13, v10
	v_rcp_f32_e32 v10, v9
	v_add_f32_e32 v9, 1.0, v11
	v_mul_f32_e32 v11, 0xbfb8aa3b, v0
	v_add_f32_e32 v8, 1.0, v12
	v_rcp_f32_e32 v12, v9
	v_add_f32_e32 v9, 1.0, v13
	v_exp_f32_e32 v11, v11
	v_mul_f32_e32 v13, 0xbfb8aa3b, v1
	v_exp_f32_e32 v13, v13
	v_rcp_f32_e32 v14, v9
	v_add_f32_e32 v9, 1.0, v11
	v_mul_f32_e32 v11, 0xbfb8aa3b, v2
	v_rcp_f32_e32 v20, v9
	v_add_f32_e32 v9, 1.0, v13
	v_exp_f32_e32 v11, v11
	v_mul_f32_e32 v13, 0xbfb8aa3b, v3
	v_exp_f32_e32 v13, v13
	v_rcp_f32_e32 v22, v9
	v_add_f32_e32 v9, 1.0, v11
	v_rcp_f32_e32 v8, v8
	v_rcp_f32_e32 v24, v9
	v_add_f32_e32 v9, 1.0, v13
	v_rcp_f32_e32 v26, v9
	v_lshlrev_b32_e32 v9, 16, v80
	v_mov_b32_e32 v28, v4
	v_and_b32_e32 v4, 0xffff0000, v80
	v_sub_f32_e32 v9, v9, v16
	v_sub_f32_e32 v4, v4, v16
	v_mul_f32_e32 v9, v9, v17
	v_mov_b32_e32 v29, v56
	v_mul_f32_e32 v11, v4, v17
	v_mov_b32_e32 v56, v5
	v_pk_mul_f32 v[8:9], v[28:29], v[8:9]
	v_pk_mul_f32 v[4:5], v[56:57], v[10:11]
	v_mul_f32_e32 v8, v8, v9
	v_mul_f32_e32 v9, v4, v5
	v_lshlrev_b32_e32 v4, 16, v81
	v_sub_f32_e32 v4, v4, v16
	v_mul_f32_e32 v13, v4, v17
	v_mov_b32_e32 v4, v6
	v_mov_b32_e32 v5, v58
	v_pk_mul_f32 v[4:5], v[4:5], v[12:13]
	v_mov_b32_e32 v58, v7
	v_mul_f32_e32 v6, v4, v5
	v_and_b32_e32 v4, 0xffff0000, v81
	v_sub_f32_e32 v4, v4, v16
	v_mul_f32_e32 v15, v4, v17
	v_pk_mul_f32 v[4:5], v[58:59], v[14:15]
	s_and_b64 vcc, exec, s[4:5]
	v_mul_f32_e32 v7, v4, v5
	v_lshlrev_b32_e32 v4, 16, v82
	v_sub_f32_e32 v4, v4, v16
	v_mul_f32_e32 v21, v4, v17
	v_mov_b32_e32 v4, v0
	v_and_b32_e32 v0, 0xffff0000, v82
	v_sub_f32_e32 v0, v0, v16
	v_mov_b32_e32 v5, v48
	v_mul_f32_e32 v23, v0, v17
	v_mov_b32_e32 v48, v1
	v_pk_mul_f32 v[4:5], v[4:5], v[20:21]
	v_pk_mul_f32 v[0:1], v[48:49], v[22:23]
	v_mul_f32_e32 v4, v4, v5
	v_mul_f32_e32 v5, v0, v1
	v_lshlrev_b32_e32 v0, 16, v83
	v_sub_f32_e32 v0, v0, v16
	v_mul_f32_e32 v25, v0, v17
	v_mov_b32_e32 v0, v2
	v_mov_b32_e32 v1, v50
	v_pk_mul_f32 v[0:1], v[0:1], v[24:25]
	v_mov_b32_e32 v50, v3
	v_mul_f32_e32 v10, v0, v1
	v_and_b32_e32 v0, 0xffff0000, v83
	v_sub_f32_e32 v0, v0, v16
	v_mul_f32_e32 v27, v0, v17
	v_pk_mul_f32 v[0:1], v[50:51], v[26:27]
	s_nop 0
	v_mul_f32_e32 v3, v0, v1
	v_cvt_pk_bf16_f32 v0, v8, v9
	v_cvt_pk_bf16_f32 v1, v6, v7
	v_cvt_pk_bf16_f32 v2, v4, v5
	v_cvt_pk_bf16_f32 v3, v10, v3
	global_store_dwordx4 v[18:19], v[0:3], off offset:256
	s_cbranch_vccz .LBB0_513
	s_waitcnt vmcnt(0)
	v_readlane_b32 s54, v255, 42
	v_readlane_b32 s52, v255, 44
	v_readlane_b32 s64, v255, 53
	v_readlane_b32 s66, v255, 55
	s_cmpk_gt_u32 s47, 0xff
	v_readlane_b32 s55, v255, 43
	v_readlane_b32 s53, v255, 45
	v_readlane_b32 s56, v255, 46
	v_readlane_b32 s57, v255, 47
	v_readlane_b32 s58, v255, 48
	v_readlane_b32 s59, v255, 49
	v_readlane_b32 s65, v255, 54
	v_readlane_b32 s67, v255, 56
	v_readlane_b32 s63, v255, 57
	s_cbranch_scc1 .LBB0_520
	s_barrier

; #define PG8_STAGE(bufoff, gbase, voff) do { _Pragma("unroll") for (int _i = 0; _i < 2; ++_i) \
;         __builtin_amdgcn_global_load_lds((const unsigned*)((const char*)(gbase) + (voff)[_i]), (PG8_LAS unsigned*)(lds + (bufoff) + ldsw + _i * 8192), 16, 0, 0); } while (0)
; #define PG8_LDA(dst, b, h) do { _Pragma("unroll") for (int m = 0; m < 4; ++m) _Pragma("unroll") for (int k = 0; k < 2; ++k) dst[m][k] = *(const PG8_LAS bf16x8*)(lds + PG8_SA(b, h) + aoff + m * 2048 + k * 1024); } while (0)
; #define PG8_LDB(dst, b, h) do { _Pragma("unroll") for (int n = 0; n < 2; ++n) _Pragma("unroll") for (int k = 0; k < 2; ++k) dst[n][k] = *(const PG8_LAS bf16x8*)(lds + PG8_SB(b, h) + boff + n * 2048 + k * 1024); } while (0)
; #define PG8_MMA(ai, bj, At, Bt) do { __builtin_amdgcn_s_setprio(1); _Pragma("unroll") for (int m = 0; m < 4; ++m) _Pragma("unroll") for (int n = 0; n < 2; ++n) _Pragma("unroll") for (int k = 0; k < 2; ++k) \
;         acc[ai][bj][m][n] = __builtin_amdgcn_mfma_f32_16x16x32_bf16(Bt[n][k], At[m][k], acc[ai][bj][m][n], 0, 0, 0); __builtin_amdgcn_s_setprio(0); } while (0)
; #define PG8_WAIT_L(n) asm volatile("s_waitcnt lgkmcnt(" #n ")" ::: "memory")
; #define PG8_BAR __builtin_amdgcn_s_barrier()
; #define PG8_SCHED __builtin_amdgcn_sched_barrier(0)
; template <class Epi, class Sched>
; __device__ __forceinline__ void gemm_phase(PG8_LAS unsigned char* lds, const Gemm g, const Sched& S, const Epi& E) {
;     ...
;             PG8_LDB(B0, 0, 0); PG8_SCHED; PG8_LDA(At, 0, 0); PG8_STAGE(PG8_SA(1, 1), a1 + hstep, voffA);
;             PG8_WAIT_L(8); PG8_BAR; PG8_WAIT_L(0); PG8_MMA(0, 0, At, B0); PG8_BAR; PG8_SCHED;
;             PG8_LDB(B1, 0, 1); PG8_STAGE(PG8_SB(0, 0), b2, voffB);
;             PG8_BAR; PG8_WAIT_L(0); PG8_MMA(0, 1, At, B1); PG8_BAR;
;             PG8_LDA(At, 0, 1); PG8_STAGE(PG8_SA(0, 0), a2, voffA);
;             PG8_BAR; PG8_WAIT_L(0); PG8_MMA(1, 0, At, B0); PG8_BAR; PG8_SCHED;
.LBB0_580:
	s_add_u32 s20, s18, 0xfff80080
	s_addc_u32 s21, s19, -1
	s_add_i32 s69, 0, 0x10000
	v_add_u32_e32 v142, s69, v144
	ds_read_b128 v[146:149], v142
	ds_read_b128 v[150:153], v142 offset:1024
	ds_read_b128 v[154:157], v142 offset:2048
	ds_read_b128 v[158:161], v142 offset:3072
	s_cmp_eq_u32 s88, 28
	s_cselect_b32 s71, s9, s21
	s_cselect_b32 s70, s11, s20
	s_cselect_b32 s21, s7, s83
	s_cselect_b32 s20, s81, s82
	v_lshl_add_u64 v[142:143], s[18:19], 0, v[138:139]
	s_add_i32 m0, s13, 0xc000
	ds_read_b128 v[162:165], v145
	ds_read_b128 v[166:169], v145 offset:1024
	ds_read_b128 v[170:173], v145 offset:2048
	ds_read_b128 v[174:177], v145 offset:3072
	ds_read_b128 v[184:187], v145 offset:4096
	ds_read_b128 v[188:191], v145 offset:5120
	ds_read_b128 v[192:195], v145 offset:6144
	ds_read_b128 v[196:199], v145 offset:7168
	global_load_lds_dwordx4 v[142:143], off
	v_lshl_add_u64 v[142:143], s[18:19], 0, v[140:141]
	s_add_i32 m0, s13, 0xe000
	s_nop 0
	global_load_lds_dwordx4 v[142:143], off
	s_waitcnt lgkmcnt(8)
	s_barrier
	s_waitcnt lgkmcnt(0)
	v_mfma_f32_16x16x32_bf16 v[124:127], v[146:149], v[162:165], v[124:127]
	v_mfma_f32_16x16x32_bf16 v[120:123], v[154:157], v[162:165], v[120:123]
	v_mfma_f32_16x16x32_bf16 v[116:119], v[146:149], v[170:173], v[116:119]
	v_mfma_f32_16x16x32_bf16 v[108:111], v[154:157], v[170:173], v[108:111]
	v_mfma_f32_16x16x32_bf16 v[100:103], v[146:149], v[184:187], v[100:103]
	v_mfma_f32_16x16x32_bf16 v[92:95], v[154:157], v[184:187], v[92:95]
	v_mfma_f32_16x16x32_bf16 v[84:87], v[146:149], v[192:195], v[84:87]
	v_mfma_f32_16x16x32_bf16 v[76:79], v[154:157], v[192:195], v[76:79]
	v_mfma_f32_16x16x32_bf16 v[124:127], v[150:153], v[166:169], v[124:127]
	v_mfma_f32_16x16x32_bf16 v[120:123], v[158:161], v[166:169], v[120:123]
	v_mfma_f32_16x16x32_bf16 v[116:119], v[150:153], v[174:177], v[116:119]
	v_mfma_f32_16x16x32_bf16 v[108:111], v[158:161], v[174:177], v[108:111]
	v_mfma_f32_16x16x32_bf16 v[100:103], v[150:153], v[188:191], v[100:103]
	v_mfma_f32_16x16x32_bf16 v[92:95], v[158:161], v[188:191], v[92:95]
	v_mfma_f32_16x16x32_bf16 v[84:87], v[150:153], v[196:199], v[84:87]
	v_mfma_f32_16x16x32_bf16 v[76:79], v[158:161], v[196:199], v[76:79]
	s_barrier
	s_add_i32 s89, 0, 0x14000
	v_add_u32_e32 v142, s89, v144
	s_add_i32 s69, s69, s72
	ds_read_b128 v[200:203], v142
	ds_read_b128 v[204:207], v142 offset:1024
	ds_read_b128 v[208:211], v142 offset:2048
	ds_read_b128 v[212:215], v142 offset:3072
	v_lshl_add_u64 v[142:143], s[20:21], 0, v[180:181]
	s_mov_b32 m0, s69
	v_lshl_add_u64 v[178:179], s[20:21], 0, v[128:129]
	global_load_lds_dwordx4 v[142:143], off
	s_add_i32 m0, s69, 0x2000
	s_nop 0
	global_load_lds_dwordx4 v[178:179], off
	s_barrier
	s_waitcnt lgkmcnt(0)
	v_mfma_f32_16x16x32_bf16 v[112:115], v[200:203], v[162:165], v[112:115]
	v_mfma_f32_16x16x32_bf16 v[104:107], v[208:211], v[162:165], v[104:107]
	v_mfma_f32_16x16x32_bf16 v[96:99], v[200:203], v[170:173], v[96:99]
	v_mfma_f32_16x16x32_bf16 v[88:91], v[208:211], v[170:173], v[88:91]
	v_mfma_f32_16x16x32_bf16 v[80:83], v[200:203], v[184:187], v[80:83]
	v_mfma_f32_16x16x32_bf16 v[72:75], v[208:211], v[184:187], v[72:75]
	v_mfma_f32_16x16x32_bf16 v[68:71], v[200:203], v[192:195], v[68:71]
	v_mfma_f32_16x16x32_bf16 v[64:67], v[208:211], v[192:195], v[64:67]
	v_mfma_f32_16x16x32_bf16 v[112:115], v[204:207], v[166:169], v[112:115]
	v_mfma_f32_16x16x32_bf16 v[104:107], v[212:215], v[166:169], v[104:107]
	v_mfma_f32_16x16x32_bf16 v[96:99], v[204:207], v[174:177], v[96:99]
	v_mfma_f32_16x16x32_bf16 v[88:91], v[212:215], v[174:177], v[88:91]
	v_mfma_f32_16x16x32_bf16 v[80:83], v[204:207], v[188:191], v[80:83]
	v_mfma_f32_16x16x32_bf16 v[72:75], v[212:215], v[188:191], v[72:75]
	v_mfma_f32_16x16x32_bf16 v[68:71], v[204:207], v[196:199], v[68:71]
	v_mfma_f32_16x16x32_bf16 v[64:67], v[212:215], v[196:199], v[64:67]
	s_mov_b32 m0, s13
	v_lshl_add_u64 v[216:217], s[70:71], 0, v[132:133]
	s_barrier
	ds_read_b128 v[162:165], v145 offset:16384
	ds_read_b128 v[166:169], v145 offset:17408
	ds_read_b128 v[170:173], v145 offset:18432
	ds_read_b128 v[174:177], v145 offset:19456
	ds_read_b128 v[184:187], v145 offset:20480
	ds_read_b128 v[188:191], v145 offset:21504
	ds_read_b128 v[192:195], v145 offset:22528
	ds_read_b128 v[196:199], v145 offset:23552
	global_load_lds_dwordx4 v[216:217], off
	v_lshl_add_u64 v[218:219], s[70:71], 0, v[130:131]
	s_mov_b32 m0, s75
	s_nop 0
	global_load_lds_dwordx4 v[218:219], off
	s_barrier
	s_waitcnt lgkmcnt(0)
	v_mfma_f32_16x16x32_bf16 v[60:63], v[146:149], v[162:165], v[60:63]
	v_mfma_f32_16x16x32_bf16 v[56:59], v[154:157], v[162:165], v[56:59]
	v_mfma_f32_16x16x32_bf16 v[52:55], v[146:149], v[170:173], v[52:55]
	v_mfma_f32_16x16x32_bf16 v[44:47], v[154:157], v[170:173], v[44:47]
	v_mfma_f32_16x16x32_bf16 v[36:39], v[146:149], v[184:187], v[36:39]
	v_mfma_f32_16x16x32_bf16 v[28:31], v[154:157], v[184:187], v[28:31]
	v_mfma_f32_16x16x32_bf16 v[20:23], v[146:149], v[192:195], v[20:23]
	v_mfma_f32_16x16x32_bf16 v[12:15], v[154:157], v[192:195], v[12:15]
	v_mfma_f32_16x16x32_bf16 v[60:63], v[150:153], v[166:169], v[60:63]
	v_mfma_f32_16x16x32_bf16 v[56:59], v[158:161], v[166:169], v[56:59]
	v_mfma_f32_16x16x32_bf16 v[52:55], v[150:153], v[174:177], v[52:55]
	v_mfma_f32_16x16x32_bf16 v[44:47], v[158:161], v[174:177], v[44:47]
	v_mfma_f32_16x16x32_bf16 v[36:39], v[150:153], v[188:191], v[36:39]
	v_mfma_f32_16x16x32_bf16 v[28:31], v[158:161], v[188:191], v[28:31]
	v_mfma_f32_16x16x32_bf16 v[20:23], v[150:153], v[196:199], v[20:23]
	v_mfma_f32_16x16x32_bf16 v[12:15], v[158:161], v[196:199], v[12:15]
	s_barrier
; #define PG8_STAGE(bufoff, gbase, voff) do { _Pragma("unroll") for (int _i = 0; _i < 2; ++_i) \
;         __builtin_amdgcn_global_load_lds((const unsigned*)((const char*)(gbase) + (voff)[_i]), (PG8_LAS unsigned*)(lds + (bufoff) + ldsw + _i * 8192), 16, 0, 0); } while (0)
; #define PG8_LDA(dst, b, h) do { _Pragma("unroll") for (int m = 0; m < 4; ++m) _Pragma("unroll") for (int k = 0; k < 2; ++k) dst[m][k] = *(const PG8_LAS bf16x8*)(lds + PG8_SA(b, h) + aoff + m * 2048 + k * 1024); } while (0)
; #define PG8_LDB(dst, b, h) do { _Pragma("unroll") for (int n = 0; n < 2; ++n) _Pragma("unroll") for (int k = 0; k < 2; ++k) dst[n][k] = *(const PG8_LAS bf16x8*)(lds + PG8_SB(b, h) + boff + n * 2048 + k * 1024); } while (0)
; #define PG8_MMA(ai, bj, At, Bt) do { __builtin_amdgcn_s_setprio(1); _Pragma("unroll") for (int m = 0; m < 4; ++m) _Pragma("unroll") for (int n = 0; n < 2; ++n) _Pragma("unroll") for (int k = 0; k < 2; ++k) \
;         acc[ai][bj][m][n] = __builtin_amdgcn_mfma_f32_16x16x32_bf16(Bt[n][k], At[m][k], acc[ai][bj][m][n], 0, 0, 0); __builtin_amdgcn_s_setprio(0); } while (0)
; #define PG8_WAIT_V(n) asm volatile("s_waitcnt vmcnt(" #n ")" ::: "memory")
; #define PG8_WAIT_L(n) asm volatile("s_waitcnt lgkmcnt(" #n ")" ::: "memory")
; #define PG8_BAR __builtin_amdgcn_s_barrier()
; #define PG8_SCHED __builtin_amdgcn_sched_barrier(0)
; template <class Epi, class Sched>
; __device__ __forceinline__ void gemm_phase(PG8_LAS unsigned char* lds, const Gemm g, const Sched& S, const Epi& E) {
;     ...
;             PG8_STAGE(PG8_SB(0, 1), b2 + hstep, voffB);
;             PG8_WAIT_V(6); PG8_BAR; PG8_MMA(1, 1, At, B1); PG8_BAR;
;             PG8_LDB(B0, 1, 0); PG8_SCHED; PG8_LDA(At, 1, 0); PG8_STAGE(PG8_SA(0, 1), a2 + hstep, voffA);
;             PG8_WAIT_L(8); PG8_BAR; PG8_WAIT_L(0); PG8_MMA(0, 0, At, B0); PG8_BAR; PG8_SCHED;
;             PG8_LDB(B1, 1, 1); PG8_STAGE(PG8_SB(1, 0), b3, voffB);
;             PG8_BAR; PG8_WAIT_L(0); PG8_MMA(0, 1, At, B1); PG8_BAR;
;             PG8_LDA(At, 1, 1); PG8_STAGE(PG8_SA(1, 0), a3, voffA);
;             PG8_BAR; PG8_WAIT_L(0); PG8_MMA(1, 0, At, B0); PG8_BAR; PG8_SCHED;
	s_add_u32 vcc_lo, s20, 0x80000
	s_addc_u32 vcc_hi, s21, 0
	s_add_i32 s69, s89, s72
	v_lshl_add_u64 v[146:147], vcc, 0, v[180:181]
	s_mov_b32 m0, s69
	s_nop 0
	global_load_lds_dwordx4 v[146:147], off
	v_lshl_add_u64 v[146:147], vcc, 0, v[128:129]
	s_add_i32 m0, s69, 0x2000
	s_nop 0
	global_load_lds_dwordx4 v[146:147], off
	s_waitcnt vmcnt(6)
	s_barrier
	v_mfma_f32_16x16x32_bf16 v[48:51], v[200:203], v[162:165], v[48:51]
	v_mfma_f32_16x16x32_bf16 v[40:43], v[208:211], v[162:165], v[40:43]
	v_mfma_f32_16x16x32_bf16 v[32:35], v[200:203], v[170:173], v[32:35]
	v_mfma_f32_16x16x32_bf16 v[24:27], v[208:211], v[170:173], v[24:27]
	v_mfma_f32_16x16x32_bf16 v[16:19], v[200:203], v[184:187], v[16:19]
	v_mfma_f32_16x16x32_bf16 v[8:11], v[208:211], v[184:187], v[8:11]
	v_mfma_f32_16x16x32_bf16 v[4:7], v[200:203], v[192:195], v[4:7]
	v_mfma_f32_16x16x32_bf16 v[0:3], v[208:211], v[192:195], v[0:3]
	v_mfma_f32_16x16x32_bf16 v[48:51], v[204:207], v[166:169], v[48:51]
	v_mfma_f32_16x16x32_bf16 v[40:43], v[212:215], v[166:169], v[40:43]
	v_mfma_f32_16x16x32_bf16 v[32:35], v[204:207], v[174:177], v[32:35]
	v_mfma_f32_16x16x32_bf16 v[24:27], v[212:215], v[174:177], v[24:27]
	v_mfma_f32_16x16x32_bf16 v[16:19], v[204:207], v[188:191], v[16:19]
	v_mfma_f32_16x16x32_bf16 v[8:11], v[212:215], v[188:191], v[8:11]
	v_mfma_f32_16x16x32_bf16 v[4:7], v[204:207], v[196:199], v[4:7]
	v_mfma_f32_16x16x32_bf16 v[0:3], v[212:215], v[196:199], v[0:3]
	s_add_i32 s69, 0, 0x18000
	v_add_u32_e32 v158, s69, v144
	s_barrier
	ds_read_b128 v[146:149], v158
	ds_read_b128 v[150:153], v158 offset:1024
	ds_read_b128 v[154:157], v158 offset:2048
	ds_read_b128 v[158:161], v158 offset:3072
	s_add_u32 s70, s70, 0x80000
	s_addc_u32 s71, s71, 0
	s_mov_b32 m0, s76
	v_lshl_add_u64 v[200:201], s[70:71], 0, v[132:133]
	ds_read_b128 v[162:165], v145 offset:32768
	ds_read_b128 v[166:169], v145 offset:33792
	ds_read_b128 v[170:173], v145 offset:34816
	ds_read_b128 v[174:177], v145 offset:35840
	ds_read_b128 v[184:187], v145 offset:36864
	ds_read_b128 v[188:191], v145 offset:37888
	ds_read_b128 v[192:195], v145 offset:38912
	ds_read_b128 v[196:199], v145 offset:39936
	global_load_lds_dwordx4 v[200:201], off
	v_lshl_add_u64 v[200:201], s[70:71], 0, v[130:131]
	s_mov_b32 m0, s77
	s_nop 0
	global_load_lds_dwordx4 v[200:201], off
	s_waitcnt lgkmcnt(8)
	s_barrier
	s_waitcnt lgkmcnt(0)
	v_mfma_f32_16x16x32_bf16 v[124:127], v[146:149], v[162:165], v[124:127]
	v_mfma_f32_16x16x32_bf16 v[120:123], v[154:157], v[162:165], v[120:123]
	v_mfma_f32_16x16x32_bf16 v[116:119], v[146:149], v[170:173], v[116:119]
	v_mfma_f32_16x16x32_bf16 v[108:111], v[154:157], v[170:173], v[108:111]
	v_mfma_f32_16x16x32_bf16 v[100:103], v[146:149], v[184:187], v[100:103]
	v_mfma_f32_16x16x32_bf16 v[92:95], v[154:157], v[184:187], v[92:95]
	v_mfma_f32_16x16x32_bf16 v[84:87], v[146:149], v[192:195], v[84:87]
	v_mfma_f32_16x16x32_bf16 v[76:79], v[154:157], v[192:195], v[76:79]
	v_mfma_f32_16x16x32_bf16 v[124:127], v[150:153], v[166:169], v[124:127]
	v_mfma_f32_16x16x32_bf16 v[120:123], v[158:161], v[166:169], v[120:123]
	v_mfma_f32_16x16x32_bf16 v[116:119], v[150:153], v[174:177], v[116:119]
	v_mfma_f32_16x16x32_bf16 v[108:111], v[158:161], v[174:177], v[108:111]
	v_mfma_f32_16x16x32_bf16 v[100:103], v[150:153], v[188:191], v[100:103]
	v_mfma_f32_16x16x32_bf16 v[92:95], v[158:161], v[188:191], v[92:95]
	v_mfma_f32_16x16x32_bf16 v[84:87], v[150:153], v[196:199], v[84:87]
	v_mfma_f32_16x16x32_bf16 v[76:79], v[158:161], v[196:199], v[76:79]
	s_barrier
	s_add_i32 s70, 0, 0x1c000
	s_add_i32 s69, s69, s72
	v_add_u32_e32 v212, s70, v144
	v_lshl_add_u64 v[142:143], v[142:143], 0, s[38:39]
	s_mov_b32 m0, s69
	ds_read_b128 v[200:203], v212
	ds_read_b128 v[204:207], v212 offset:1024
	ds_read_b128 v[208:211], v212 offset:2048
	ds_read_b128 v[212:215], v212 offset:3072
	global_load_lds_dwordx4 v[142:143], off
	v_lshl_add_u64 v[142:143], v[178:179], 0, s[38:39]
	s_add_i32 m0, s69, 0x2000
	s_nop 0
	global_load_lds_dwordx4 v[142:143], off
	s_barrier
	s_waitcnt lgkmcnt(0)
	v_mfma_f32_16x16x32_bf16 v[112:115], v[200:203], v[162:165], v[112:115]
	v_mfma_f32_16x16x32_bf16 v[104:107], v[208:211], v[162:165], v[104:107]
	v_mfma_f32_16x16x32_bf16 v[96:99], v[200:203], v[170:173], v[96:99]
	v_mfma_f32_16x16x32_bf16 v[88:91], v[208:211], v[170:173], v[88:91]
	v_mfma_f32_16x16x32_bf16 v[80:83], v[200:203], v[184:187], v[80:83]
	v_mfma_f32_16x16x32_bf16 v[72:75], v[208:211], v[184:187], v[72:75]
	v_mfma_f32_16x16x32_bf16 v[68:71], v[200:203], v[192:195], v[68:71]
	v_mfma_f32_16x16x32_bf16 v[64:67], v[208:211], v[192:195], v[64:67]
	v_mfma_f32_16x16x32_bf16 v[112:115], v[204:207], v[166:169], v[112:115]
	v_mfma_f32_16x16x32_bf16 v[104:107], v[212:215], v[166:169], v[104:107]
	v_mfma_f32_16x16x32_bf16 v[96:99], v[204:207], v[174:177], v[96:99]
	v_mfma_f32_16x16x32_bf16 v[88:91], v[212:215], v[174:177], v[88:91]
	v_mfma_f32_16x16x32_bf16 v[80:83], v[204:207], v[188:191], v[80:83]
	v_mfma_f32_16x16x32_bf16 v[72:75], v[212:215], v[188:191], v[72:75]
	v_mfma_f32_16x16x32_bf16 v[68:71], v[204:207], v[196:199], v[68:71]
	v_mfma_f32_16x16x32_bf16 v[64:67], v[212:215], v[196:199], v[64:67]
	s_mov_b32 m0, s78
	v_lshl_add_u64 v[142:143], v[216:217], 0, s[38:39]
	s_barrier
	ds_read_b128 v[162:165], v145 offset:49152
	ds_read_b128 v[166:169], v145 offset:50176
	ds_read_b128 v[170:173], v145 offset:51200
	ds_read_b128 v[174:177], v145 offset:52224
	ds_read_b128 v[184:187], v145 offset:53248
	ds_read_b128 v[188:191], v145 offset:54272
	ds_read_b128 v[192:195], v145 offset:55296
	ds_read_b128 v[196:199], v145 offset:56320
	global_load_lds_dwordx4 v[142:143], off
	v_lshl_add_u64 v[142:143], v[218:219], 0, s[38:39]
	s_mov_b32 m0, s79
	s_nop 0
	global_load_lds_dwordx4 v[142:143], off
	s_barrier
; #define PG8_STAGE(bufoff, gbase, voff) do { _Pragma("unroll") for (int _i = 0; _i < 2; ++_i) \
;         __builtin_amdgcn_global_load_lds((const unsigned*)((const char*)(gbase) + (voff)[_i]), (PG8_LAS unsigned*)(lds + (bufoff) + ldsw + _i * 8192), 16, 0, 0); } while (0)
; #define PG8_LDA(dst, b, h) do { _Pragma("unroll") for (int m = 0; m < 4; ++m) _Pragma("unroll") for (int k = 0; k < 2; ++k) dst[m][k] = *(const PG8_LAS bf16x8*)(lds + PG8_SA(b, h) + aoff + m * 2048 + k * 1024); } while (0)
; #define PG8_LDB(dst, b, h) do { _Pragma("unroll") for (int n = 0; n < 2; ++n) _Pragma("unroll") for (int k = 0; k < 2; ++k) dst[n][k] = *(const PG8_LAS bf16x8*)(lds + PG8_SB(b, h) + boff + n * 2048 + k * 1024); } while (0)
; #define PG8_WAIT_V(n) asm volatile("s_waitcnt vmcnt(" #n ")" ::: "memory")
; #define PG8_WAIT_L(n) asm volatile("s_waitcnt lgkmcnt(" #n ")" ::: "memory")
; #define PG8_BAR __builtin_amdgcn_s_barrier()
; #define PG8_SCHED __builtin_amdgcn_sched_barrier(0)
; template <class Epi, class Sched>
; __device__ __forceinline__ void gemm_phase(PG8_LAS unsigned char* lds, const Gemm g, const Sched& S, const Epi& E) {
;     ...
;             PG8_WAIT_V(6); PG8_BAR; PG8_MMA(1, 1, At, B1); PG8_BAR;
;             PG8_LDB(B0, 1, 0); PG8_SCHED; PG8_LDA(At, 1, 0); PG8_STAGE(PG8_SA(0, 1), a2 + hstep, voffA);
;             PG8_WAIT_L(8); PG8_BAR; PG8_WAIT_L(0); PG8_MMA(0, 0, At, B0); PG8_BAR; PG8_SCHED;
;             PG8_LDB(B1, 1, 1); PG8_STAGE(PG8_SB(1, 0), b3, voffB);
;             PG8_BAR; PG8_WAIT_L(0); PG8_MMA(0, 1, At, B1); PG8_BAR;
;             PG8_LDA(At, 1, 1); PG8_STAGE(PG8_SA(1, 0), a3, voffA);
;             PG8_BAR; PG8_WAIT_L(0); PG8_MMA(1, 0, At, B0); PG8_BAR; PG8_SCHED;
;             PG8_STAGE(PG8_SB(1, 1), b3 + hstep, voffB);
;             PG8_WAIT_V(6); PG8_BAR; PG8_MMA(1, 1, At, B1); PG8_BAR;
;         }
;         E(acc, cur, wr, wc, fr, fq); S.done(cur);
;     DI void operator()(const AccT& acc, const pg8::Unit& u, int wr, int wc, int fr, int fq) const {
;         bf16_t* dst = o + u.pn * 256 + wc * 32 + 8 * fq;
; #pragma unroll
;         for (int ai = 0; ai < 2; ++ai)
; #pragma unroll
;             for (int m = 0; m < 4; ++m) { const size_t row = (size_t)u.pm * 256 + wr * 64 + fr + ai * 128 + m * 16;
; #pragma unroll
;                 for (int bj = 0; bj < 2; ++bj) store8(dst + row * ldc + bj * 128, acc[ai][bj][m][0], acc[ai][bj][m][1]); }
	s_waitcnt lgkmcnt(0)
	v_mfma_f32_16x16x32_bf16 v[60:63], v[146:149], v[162:165], v[60:63]
	v_mfma_f32_16x16x32_bf16 v[56:59], v[154:157], v[162:165], v[56:59]
	v_mfma_f32_16x16x32_bf16 v[52:55], v[146:149], v[170:173], v[52:55]
	v_mfma_f32_16x16x32_bf16 v[44:47], v[154:157], v[170:173], v[44:47]
	v_mfma_f32_16x16x32_bf16 v[36:39], v[146:149], v[184:187], v[36:39]
	v_mfma_f32_16x16x32_bf16 v[28:31], v[154:157], v[184:187], v[28:31]
	v_mfma_f32_16x16x32_bf16 v[20:23], v[146:149], v[192:195], v[20:23]
	v_mfma_f32_16x16x32_bf16 v[12:15], v[154:157], v[192:195], v[12:15]
	v_mfma_f32_16x16x32_bf16 v[60:63], v[150:153], v[166:169], v[60:63]
	v_mfma_f32_16x16x32_bf16 v[56:59], v[158:161], v[166:169], v[56:59]
	v_mfma_f32_16x16x32_bf16 v[52:55], v[150:153], v[174:177], v[52:55]
	v_mfma_f32_16x16x32_bf16 v[44:47], v[158:161], v[174:177], v[44:47]
	v_mfma_f32_16x16x32_bf16 v[36:39], v[150:153], v[188:191], v[36:39]
	v_mfma_f32_16x16x32_bf16 v[28:31], v[158:161], v[188:191], v[28:31]
	v_mfma_f32_16x16x32_bf16 v[20:23], v[150:153], v[196:199], v[20:23]
	v_mfma_f32_16x16x32_bf16 v[12:15], v[158:161], v[196:199], v[12:15]
	s_barrier
	s_add_u32 s20, s20, 0x80080
	s_addc_u32 s21, s21, 0
	s_add_i32 s69, s70, s72
	v_lshl_add_u64 v[142:143], s[20:21], 0, v[180:181]
	s_mov_b32 m0, s69
	s_nop 0
	global_load_lds_dwordx4 v[142:143], off
	v_lshl_add_u64 v[142:143], s[20:21], 0, v[128:129]
	s_add_i32 m0, s69, 0x2000
	s_nop 0
	global_load_lds_dwordx4 v[142:143], off
	s_waitcnt vmcnt(6)
	s_barrier
	v_mfma_f32_16x16x32_bf16 v[48:51], v[200:203], v[162:165], v[48:51]
	v_mfma_f32_16x16x32_bf16 v[40:43], v[208:211], v[162:165], v[40:43]
	v_mfma_f32_16x16x32_bf16 v[32:35], v[200:203], v[170:173], v[32:35]
	v_mfma_f32_16x16x32_bf16 v[24:27], v[208:211], v[170:173], v[24:27]
	v_mfma_f32_16x16x32_bf16 v[16:19], v[200:203], v[184:187], v[16:19]
	v_mfma_f32_16x16x32_bf16 v[8:11], v[208:211], v[184:187], v[8:11]
	v_mfma_f32_16x16x32_bf16 v[4:7], v[200:203], v[192:195], v[4:7]
	v_mfma_f32_16x16x32_bf16 v[0:3], v[208:211], v[192:195], v[0:3]
	v_mfma_f32_16x16x32_bf16 v[48:51], v[204:207], v[166:169], v[48:51]
	v_mfma_f32_16x16x32_bf16 v[40:43], v[212:215], v[166:169], v[40:43]
	v_mfma_f32_16x16x32_bf16 v[32:35], v[204:207], v[174:177], v[32:35]
	v_mfma_f32_16x16x32_bf16 v[24:27], v[212:215], v[174:177], v[24:27]
	v_mfma_f32_16x16x32_bf16 v[16:19], v[204:207], v[188:191], v[16:19]
	v_mfma_f32_16x16x32_bf16 v[8:11], v[212:215], v[188:191], v[8:11]
	v_mfma_f32_16x16x32_bf16 v[4:7], v[204:207], v[196:199], v[4:7]
	v_mfma_f32_16x16x32_bf16 v[0:3], v[212:215], v[196:199], v[0:3]
	s_add_i32 s88, s88, 2
	s_add_u32 s18, s18, 0x100
	s_addc_u32 s19, s19, 0
	s_add_u32 s82, s82, 0x100
	s_addc_u32 s83, s83, 0
	s_cmp_gt_u32 s88, 29
	s_barrier
	s_cbranch_scc0 .LBB0_580
	s_lshl_b32 s18, s12, 8
	s_ashr_i32 s19, s18, 31
	s_ashr_i32 s11, s10, 31
	v_lshl_add_u64 v[142:143], s[18:19], 1, v[134:135]
	s_lshl_b64 s[10:11], s[10:11], 19
	v_lshl_add_u64 v[142:143], v[142:143], 0, s[10:11]
	v_lshl_add_u64 v[142:143], v[142:143], 0, v[136:137]
	s_mov_b32 s7, 0x8000
	v_cvt_pk_bf16_f32 v124, v124, v125
	v_cvt_pk_bf16_f32 v125, v126, v127
	v_cvt_pk_bf16_f32 v126, v120, v121
	v_cvt_pk_bf16_f32 v127, v122, v123
	global_store_dwordx4 v[142:143], v[124:127], off
	v_cvt_pk_bf16_f32 v112, v112, v113
	v_cvt_pk_bf16_f32 v113, v114, v115
	v_cvt_pk_bf16_f32 v114, v104, v105
	v_cvt_pk_bf16_f32 v115, v106, v107
	global_store_dwordx4 v[142:143], v[112:115], off offset:256
	v_cvt_pk_bf16_f32 v104, v116, v117
	v_cvt_pk_bf16_f32 v105, v118, v119
	v_cvt_pk_bf16_f32 v106, v108, v109
	v_add_co_u32_e32 v108, vcc, s7, v142
	s_mov_b32 s7, 0x10000
	s_nop 0
	v_addc_co_u32_e32 v109, vcc, 0, v143, vcc
	v_cvt_pk_bf16_f32 v107, v110, v111
	global_store_dwordx4 v[108:109], v[104:107], off
	v_cvt_pk_bf16_f32 v96, v96, v97
	v_cvt_pk_bf16_f32 v97, v98, v99
	v_cvt_pk_bf16_f32 v98, v88, v89
	v_cvt_pk_bf16_f32 v99, v90, v91
	global_store_dwordx4 v[108:109], v[96:99], off offset:256
	v_cvt_pk_bf16_f32 v88, v100, v101
	v_cvt_pk_bf16_f32 v89, v102, v103
	v_cvt_pk_bf16_f32 v90, v92, v93
	v_add_co_u32_e32 v92, vcc, s7, v142
	s_mov_b32 s7, 0x18000
	s_nop 0
	v_addc_co_u32_e32 v93, vcc, 0, v143, vcc
	v_cvt_pk_bf16_f32 v91, v94, v95
	global_store_dwordx4 v[92:93], v[88:91], off
	v_cvt_pk_bf16_f32 v80, v80, v81
	v_cvt_pk_bf16_f32 v81, v82, v83
	v_cvt_pk_bf16_f32 v82, v72, v73
	v_cvt_pk_bf16_f32 v83, v74, v75
	global_store_dwordx4 v[92:93], v[80:83], off offset:256
	v_cvt_pk_bf16_f32 v72, v84, v85
	v_cvt_pk_bf16_f32 v73, v86, v87
	v_cvt_pk_bf16_f32 v74, v76, v77
	v_add_co_u32_e32 v76, vcc, s7, v142
	s_mov_b32 s7, 0x40000
	s_nop 0
	v_addc_co_u32_e32 v77, vcc, 0, v143, vcc
	v_cvt_pk_bf16_f32 v75, v78, v79
	global_store_dwordx4 v[76:77], v[72:75], off
	v_cvt_pk_bf16_f32 v68, v68, v69
	v_cvt_pk_bf16_f32 v69, v70, v71
	v_cvt_pk_bf16_f32 v70, v64, v65
	v_cvt_pk_bf16_f32 v71, v66, v67
	global_store_dwordx4 v[76:77], v[68:71], off offset:256
	v_cvt_pk_bf16_f32 v60, v60, v61
	v_cvt_pk_bf16_f32 v61, v62, v63
	v_cvt_pk_bf16_f32 v62, v56, v57
	v_add_co_u32_e32 v56, vcc, s7, v142
	s_mov_b32 s7, 0x48000
	s_nop 0
	v_addc_co_u32_e32 v57, vcc, 0, v143, vcc
	v_cvt_pk_bf16_f32 v63, v58, v59
	global_store_dwordx4 v[56:57], v[60:63], off
	v_cvt_pk_bf16_f32 v48, v48, v49
	v_cvt_pk_bf16_f32 v49, v50, v51
	v_cvt_pk_bf16_f32 v50, v40, v41
	v_cvt_pk_bf16_f32 v51, v42, v43
	global_store_dwordx4 v[56:57], v[48:51], off offset:256
	v_cvt_pk_bf16_f32 v40, v52, v53
	v_cvt_pk_bf16_f32 v41, v54, v55
	v_cvt_pk_bf16_f32 v42, v44, v45
	v_add_co_u32_e32 v44, vcc, s7, v142
	s_mov_b32 s7, 0x50000
	s_nop 0
	v_addc_co_u32_e32 v45, vcc, 0, v143, vcc
	v_cvt_pk_bf16_f32 v43, v46, v47
	global_store_dwordx4 v[44:45], v[40:43], off
	v_cvt_pk_bf16_f32 v32, v32, v33
	v_cvt_pk_bf16_f32 v33, v34, v35
	v_cvt_pk_bf16_f32 v34, v24, v25
	v_cvt_pk_bf16_f32 v35, v26, v27
	global_store_dwordx4 v[44:45], v[32:35], off offset:256
	v_cvt_pk_bf16_f32 v24, v36, v37
	v_cvt_pk_bf16_f32 v25, v38, v39
	v_cvt_pk_bf16_f32 v26, v28, v29
	v_add_co_u32_e32 v28, vcc, s7, v142
	s_mov_b32 s7, 0x58000
	s_nop 0
	v_addc_co_u32_e32 v29, vcc, 0, v143, vcc
	v_cvt_pk_bf16_f32 v27, v30, v31
	global_store_dwordx4 v[28:29], v[24:27], off
	v_cvt_pk_bf16_f32 v16, v16, v17
	v_cvt_pk_bf16_f32 v17, v18, v19
	v_cvt_pk_bf16_f32 v18, v8, v9
	v_cvt_pk_bf16_f32 v19, v10, v11
	global_store_dwordx4 v[28:29], v[16:19], off offset:256
	v_cvt_pk_bf16_f32 v8, v20, v21
	v_cvt_pk_bf16_f32 v9, v22, v23
	v_cvt_pk_bf16_f32 v10, v12, v13
	v_add_co_u32_e32 v12, vcc, s7, v142
	s_mov_b32 s12, s6
	s_nop 0
	v_addc_co_u32_e32 v13, vcc, 0, v143, vcc
	s_and_b64 vcc, exec, s[0:1]
	s_mov_b32 s10, s8
	s_mov_b64 s[20:21], s[16:17]
	s_mov_b64 s[18:19], s[14:15]
	v_cvt_pk_bf16_f32 v11, v14, v15
	global_store_dwordx4 v[12:13], v[8:11], off
	v_cvt_pk_bf16_f32 v4, v4, v5
	v_cvt_pk_bf16_f32 v5, v6, v7
	v_cvt_pk_bf16_f32 v6, v0, v1
	v_cvt_pk_bf16_f32 v7, v2, v3
	global_store_dwordx4 v[12:13], v[4:7], off offset:256
	s_cbranch_vccz .LBB0_577
	s_waitcnt vmcnt(0)
	s_cmpk_gt_u32 s47, 0xff
	s_cbranch_scc1 .LBB0_584
	s_barrier

; #define PG8_STAGE(bufoff, gbase, voff) do { _Pragma("unroll") for (int _i = 0; _i < 2; ++_i) \
;         __builtin_amdgcn_global_load_lds((const unsigned*)((const char*)(gbase) + (voff)[_i]), (PG8_LAS unsigned*)(lds + (bufoff) + ldsw + _i * 8192), 16, 0, 0); } while (0)
; #define PG8_LDA(dst, b, h) do { _Pragma("unroll") for (int m = 0; m < 4; ++m) _Pragma("unroll") for (int k = 0; k < 2; ++k) dst[m][k] = *(const PG8_LAS bf16x8*)(lds + PG8_SA(b, h) + aoff + m * 2048 + k * 1024); } while (0)
; #define PG8_LDB(dst, b, h) do { _Pragma("unroll") for (int n = 0; n < 2; ++n) _Pragma("unroll") for (int k = 0; k < 2; ++k) dst[n][k] = *(const PG8_LAS bf16x8*)(lds + PG8_SB(b, h) + boff + n * 2048 + k * 1024); } while (0)
; #define PG8_MMA(ai, bj, At, Bt) do { __builtin_amdgcn_s_setprio(1); _Pragma("unroll") for (int m = 0; m < 4; ++m) _Pragma("unroll") for (int n = 0; n < 2; ++n) _Pragma("unroll") for (int k = 0; k < 2; ++k) \
;         acc[ai][bj][m][n] = __builtin_amdgcn_mfma_f32_16x16x32_bf16(Bt[n][k], At[m][k], acc[ai][bj][m][n], 0, 0, 0); __builtin_amdgcn_s_setprio(0); } while (0)
; #define PG8_WAIT_L(n) asm volatile("s_waitcnt lgkmcnt(" #n ")" ::: "memory")
; #define PG8_BAR __builtin_amdgcn_s_barrier()
; #define PG8_SCHED __builtin_amdgcn_sched_barrier(0)
; template <class Epi, class Sched>
; __device__ __forceinline__ void gemm_phase(PG8_LAS unsigned char* lds, const Gemm g, const Sched& S, const Epi& E) {
;     ...
;             PG8_LDB(B0, 0, 0); PG8_SCHED; PG8_LDA(At, 0, 0); PG8_STAGE(PG8_SA(1, 1), a1 + hstep, voffA);
;             PG8_WAIT_L(8); PG8_BAR; PG8_WAIT_L(0); PG8_MMA(0, 0, At, B0); PG8_BAR; PG8_SCHED;
;             PG8_LDB(B1, 0, 1); PG8_STAGE(PG8_SB(0, 0), b2, voffB);
;             PG8_BAR; PG8_WAIT_L(0); PG8_MMA(0, 1, At, B1); PG8_BAR;
;             PG8_LDA(At, 0, 1); PG8_STAGE(PG8_SA(0, 0), a2, voffA);
;             PG8_BAR; PG8_WAIT_L(0); PG8_MMA(1, 0, At, B0); PG8_BAR; PG8_SCHED;
.LBB0_648:
	s_add_u32 s16, s14, 0xfffc0080
	s_addc_u32 s17, s15, -1
	s_add_i32 s80, 0, 0x10000
	v_add_u32_e32 v146, s80, v139
	ds_read_b128 v[150:153], v146
	ds_read_b128 v[154:157], v146 offset:1024
	ds_read_b128 v[158:161], v146 offset:2048
	ds_read_b128 v[162:165], v146 offset:3072
	s_cmp_eq_u32 s79, 12
	s_cselect_b32 s19, s9, s17
	s_cselect_b32 s18, s75, s16
	s_cselect_b32 s17, s1, s78
	s_cselect_b32 s16, s76, s77
	v_lshl_add_u64 v[146:147], s[14:15], 0, v[142:143]
	s_add_i32 m0, s46, 0xc000
	ds_read_b128 v[166:169], v148
	ds_read_b128 v[170:173], v148 offset:1024
	ds_read_b128 v[174:177], v148 offset:2048
	ds_read_b128 v[184:187], v148 offset:3072
	ds_read_b128 v[188:191], v148 offset:4096
	ds_read_b128 v[192:195], v148 offset:5120
	ds_read_b128 v[196:199], v148 offset:6144
	ds_read_b128 v[200:203], v148 offset:7168
	global_load_lds_dwordx4 v[146:147], off
	v_lshl_add_u64 v[146:147], s[14:15], 0, v[144:145]
	s_add_i32 m0, s46, 0xe000
	s_nop 0
	global_load_lds_dwordx4 v[146:147], off
	s_waitcnt lgkmcnt(8)
	s_barrier
	s_waitcnt lgkmcnt(0)
	v_mfma_f32_16x16x32_bf16 v[124:127], v[150:153], v[166:169], v[124:127]
	v_mfma_f32_16x16x32_bf16 v[120:123], v[158:161], v[166:169], v[120:123]
	v_mfma_f32_16x16x32_bf16 v[108:111], v[150:153], v[174:177], v[108:111]
	v_mfma_f32_16x16x32_bf16 v[104:107], v[158:161], v[174:177], v[104:107]
	v_mfma_f32_16x16x32_bf16 v[92:95], v[150:153], v[188:191], v[92:95]
	v_mfma_f32_16x16x32_bf16 v[88:91], v[158:161], v[188:191], v[88:91]
	v_mfma_f32_16x16x32_bf16 v[76:79], v[150:153], v[196:199], v[76:79]
	v_mfma_f32_16x16x32_bf16 v[72:75], v[158:161], v[196:199], v[72:75]
	v_mfma_f32_16x16x32_bf16 v[124:127], v[154:157], v[170:173], v[124:127]
	v_mfma_f32_16x16x32_bf16 v[120:123], v[162:165], v[170:173], v[120:123]
	v_mfma_f32_16x16x32_bf16 v[108:111], v[154:157], v[184:187], v[108:111]
	v_mfma_f32_16x16x32_bf16 v[104:107], v[162:165], v[184:187], v[104:107]
	v_mfma_f32_16x16x32_bf16 v[92:95], v[154:157], v[192:195], v[92:95]
	v_mfma_f32_16x16x32_bf16 v[88:91], v[162:165], v[192:195], v[88:91]
	v_mfma_f32_16x16x32_bf16 v[76:79], v[154:157], v[200:203], v[76:79]
	v_mfma_f32_16x16x32_bf16 v[72:75], v[162:165], v[200:203], v[72:75]
	s_barrier
	s_add_i32 s82, 0, 0x14000
	v_add_u32_e32 v146, s82, v139
	s_add_i32 s80, s80, s21
	ds_read_b128 v[204:207], v146
	ds_read_b128 v[208:211], v146 offset:1024
	ds_read_b128 v[212:215], v146 offset:2048
	ds_read_b128 v[216:219], v146 offset:3072
	v_lshl_add_u64 v[146:147], s[16:17], 0, v[132:133]
	s_mov_b32 m0, s80
	v_lshl_add_u64 v[178:179], s[16:17], 0, v[128:129]
	global_load_lds_dwordx4 v[146:147], off
	s_add_i32 m0, s80, 0x2000
	s_nop 0
	global_load_lds_dwordx4 v[178:179], off
	s_barrier
	s_waitcnt lgkmcnt(0)
	v_mfma_f32_16x16x32_bf16 v[116:119], v[204:207], v[166:169], v[116:119]
	v_mfma_f32_16x16x32_bf16 v[112:115], v[212:215], v[166:169], v[112:115]
	v_mfma_f32_16x16x32_bf16 v[100:103], v[204:207], v[174:177], v[100:103]
	v_mfma_f32_16x16x32_bf16 v[96:99], v[212:215], v[174:177], v[96:99]
	v_mfma_f32_16x16x32_bf16 v[84:87], v[204:207], v[188:191], v[84:87]
	v_mfma_f32_16x16x32_bf16 v[80:83], v[212:215], v[188:191], v[80:83]
	v_mfma_f32_16x16x32_bf16 v[68:71], v[204:207], v[196:199], v[68:71]
	v_mfma_f32_16x16x32_bf16 v[64:67], v[212:215], v[196:199], v[64:67]
	v_mfma_f32_16x16x32_bf16 v[116:119], v[208:211], v[170:173], v[116:119]
	v_mfma_f32_16x16x32_bf16 v[112:115], v[216:219], v[170:173], v[112:115]
	v_mfma_f32_16x16x32_bf16 v[100:103], v[208:211], v[184:187], v[100:103]
	v_mfma_f32_16x16x32_bf16 v[96:99], v[216:219], v[184:187], v[96:99]
	v_mfma_f32_16x16x32_bf16 v[84:87], v[208:211], v[192:195], v[84:87]
	v_mfma_f32_16x16x32_bf16 v[80:83], v[216:219], v[192:195], v[80:83]
	v_mfma_f32_16x16x32_bf16 v[68:71], v[208:211], v[200:203], v[68:71]
	v_mfma_f32_16x16x32_bf16 v[64:67], v[216:219], v[200:203], v[64:67]
	s_mov_b32 m0, s46
	v_lshl_add_u64 v[220:221], s[18:19], 0, v[134:135]
	s_barrier
	ds_read_b128 v[166:169], v148 offset:16384
	ds_read_b128 v[170:173], v148 offset:17408
	ds_read_b128 v[174:177], v148 offset:18432
	ds_read_b128 v[184:187], v148 offset:19456
	ds_read_b128 v[188:191], v148 offset:20480
	ds_read_b128 v[192:195], v148 offset:21504
	ds_read_b128 v[196:199], v148 offset:22528
	ds_read_b128 v[200:203], v148 offset:23552
	global_load_lds_dwordx4 v[220:221], off
	v_lshl_add_u64 v[222:223], s[18:19], 0, v[130:131]
	s_mov_b32 m0, s47
	s_nop 0
	global_load_lds_dwordx4 v[222:223], off
	s_barrier
	s_waitcnt lgkmcnt(0)
	v_mfma_f32_16x16x32_bf16 v[60:63], v[150:153], v[166:169], v[60:63]
	v_mfma_f32_16x16x32_bf16 v[56:59], v[158:161], v[166:169], v[56:59]
	v_mfma_f32_16x16x32_bf16 v[44:47], v[150:153], v[174:177], v[44:47]
	v_mfma_f32_16x16x32_bf16 v[40:43], v[158:161], v[174:177], v[40:43]
	v_mfma_f32_16x16x32_bf16 v[28:31], v[150:153], v[188:191], v[28:31]
	v_mfma_f32_16x16x32_bf16 v[24:27], v[158:161], v[188:191], v[24:27]
	v_mfma_f32_16x16x32_bf16 v[12:15], v[150:153], v[196:199], v[12:15]
	v_mfma_f32_16x16x32_bf16 v[8:11], v[158:161], v[196:199], v[8:11]
	v_mfma_f32_16x16x32_bf16 v[60:63], v[154:157], v[170:173], v[60:63]
	v_mfma_f32_16x16x32_bf16 v[56:59], v[162:165], v[170:173], v[56:59]
	v_mfma_f32_16x16x32_bf16 v[44:47], v[154:157], v[184:187], v[44:47]
	v_mfma_f32_16x16x32_bf16 v[40:43], v[162:165], v[184:187], v[40:43]
	v_mfma_f32_16x16x32_bf16 v[28:31], v[154:157], v[192:195], v[28:31]
	v_mfma_f32_16x16x32_bf16 v[24:27], v[162:165], v[192:195], v[24:27]
	v_mfma_f32_16x16x32_bf16 v[12:15], v[154:157], v[200:203], v[12:15]
	v_mfma_f32_16x16x32_bf16 v[8:11], v[162:165], v[200:203], v[8:11]
	s_barrier
; #define PG8_STAGE(bufoff, gbase, voff) do { _Pragma("unroll") for (int _i = 0; _i < 2; ++_i) \
;         __builtin_amdgcn_global_load_lds((const unsigned*)((const char*)(gbase) + (voff)[_i]), (PG8_LAS unsigned*)(lds + (bufoff) + ldsw + _i * 8192), 16, 0, 0); } while (0)
; #define PG8_LDA(dst, b, h) do { _Pragma("unroll") for (int m = 0; m < 4; ++m) _Pragma("unroll") for (int k = 0; k < 2; ++k) dst[m][k] = *(const PG8_LAS bf16x8*)(lds + PG8_SA(b, h) + aoff + m * 2048 + k * 1024); } while (0)
; #define PG8_LDB(dst, b, h) do { _Pragma("unroll") for (int n = 0; n < 2; ++n) _Pragma("unroll") for (int k = 0; k < 2; ++k) dst[n][k] = *(const PG8_LAS bf16x8*)(lds + PG8_SB(b, h) + boff + n * 2048 + k * 1024); } while (0)
; #define PG8_MMA(ai, bj, At, Bt) do { __builtin_amdgcn_s_setprio(1); _Pragma("unroll") for (int m = 0; m < 4; ++m) _Pragma("unroll") for (int n = 0; n < 2; ++n) _Pragma("unroll") for (int k = 0; k < 2; ++k) \
;         acc[ai][bj][m][n] = __builtin_amdgcn_mfma_f32_16x16x32_bf16(Bt[n][k], At[m][k], acc[ai][bj][m][n], 0, 0, 0); __builtin_amdgcn_s_setprio(0); } while (0)
; #define PG8_WAIT_V(n) asm volatile("s_waitcnt vmcnt(" #n ")" ::: "memory")
; #define PG8_WAIT_L(n) asm volatile("s_waitcnt lgkmcnt(" #n ")" ::: "memory")
; #define PG8_BAR __builtin_amdgcn_s_barrier()
; #define PG8_SCHED __builtin_amdgcn_sched_barrier(0)
; template <class Epi, class Sched>
; __device__ __forceinline__ void gemm_phase(PG8_LAS unsigned char* lds, const Gemm g, const Sched& S, const Epi& E) {
;     ...
;             PG8_STAGE(PG8_SB(0, 1), b2 + hstep, voffB);
;             PG8_WAIT_V(6); PG8_BAR; PG8_MMA(1, 1, At, B1); PG8_BAR;
;             PG8_LDB(B0, 1, 0); PG8_SCHED; PG8_LDA(At, 1, 0); PG8_STAGE(PG8_SA(0, 1), a2 + hstep, voffA);
;             PG8_WAIT_L(8); PG8_BAR; PG8_WAIT_L(0); PG8_MMA(0, 0, At, B0); PG8_BAR; PG8_SCHED;
;             PG8_LDB(B1, 1, 1); PG8_STAGE(PG8_SB(1, 0), b3, voffB);
;             PG8_BAR; PG8_WAIT_L(0); PG8_MMA(0, 1, At, B1); PG8_BAR;
	s_add_u32 s80, s16, 0x40000
	s_addc_u32 s81, s17, 0
	s_add_i32 s82, s82, s21
	v_lshl_add_u64 v[150:151], s[80:81], 0, v[132:133]
	s_mov_b32 m0, s82
	s_nop 0
	global_load_lds_dwordx4 v[150:151], off
	v_lshl_add_u64 v[150:151], s[80:81], 0, v[128:129]
	s_add_i32 m0, s82, 0x2000
	s_nop 0
	global_load_lds_dwordx4 v[150:151], off
	s_waitcnt vmcnt(6)
	s_barrier
	v_mfma_f32_16x16x32_bf16 v[52:55], v[204:207], v[166:169], v[52:55]
	v_mfma_f32_16x16x32_bf16 v[48:51], v[212:215], v[166:169], v[48:51]
	v_mfma_f32_16x16x32_bf16 v[36:39], v[204:207], v[174:177], v[36:39]
	v_mfma_f32_16x16x32_bf16 v[32:35], v[212:215], v[174:177], v[32:35]
	v_mfma_f32_16x16x32_bf16 v[20:23], v[204:207], v[188:191], v[20:23]
	v_mfma_f32_16x16x32_bf16 v[16:19], v[212:215], v[188:191], v[16:19]
	v_mfma_f32_16x16x32_bf16 v[4:7], v[204:207], v[196:199], v[4:7]
	v_mfma_f32_16x16x32_bf16 v[0:3], v[212:215], v[196:199], v[0:3]
	v_mfma_f32_16x16x32_bf16 v[52:55], v[208:211], v[170:173], v[52:55]
	v_mfma_f32_16x16x32_bf16 v[48:51], v[216:219], v[170:173], v[48:51]
	v_mfma_f32_16x16x32_bf16 v[36:39], v[208:211], v[184:187], v[36:39]
	v_mfma_f32_16x16x32_bf16 v[32:35], v[216:219], v[184:187], v[32:35]
	v_mfma_f32_16x16x32_bf16 v[20:23], v[208:211], v[192:195], v[20:23]
	v_mfma_f32_16x16x32_bf16 v[16:19], v[216:219], v[192:195], v[16:19]
	v_mfma_f32_16x16x32_bf16 v[4:7], v[208:211], v[200:203], v[4:7]
	v_mfma_f32_16x16x32_bf16 v[0:3], v[216:219], v[200:203], v[0:3]
	s_add_i32 s80, 0, 0x18000
	v_add_u32_e32 v149, s80, v139
	s_barrier
	ds_read_b128 v[150:153], v149
	ds_read_b128 v[154:157], v149 offset:1024
	ds_read_b128 v[158:161], v149 offset:2048
	ds_read_b128 v[162:165], v149 offset:3072
	s_add_u32 s18, s18, 0x40000
	s_addc_u32 s19, s19, 0
	s_mov_b32 m0, s70
	v_lshl_add_u64 v[204:205], s[18:19], 0, v[134:135]
	ds_read_b128 v[166:169], v148 offset:32768
	ds_read_b128 v[170:173], v148 offset:33792
	ds_read_b128 v[174:177], v148 offset:34816
	ds_read_b128 v[184:187], v148 offset:35840
	ds_read_b128 v[188:191], v148 offset:36864
	ds_read_b128 v[192:195], v148 offset:37888
	ds_read_b128 v[196:199], v148 offset:38912
	ds_read_b128 v[200:203], v148 offset:39936
	global_load_lds_dwordx4 v[204:205], off
	v_lshl_add_u64 v[204:205], s[18:19], 0, v[130:131]
	s_mov_b32 m0, s71
	s_nop 0
	global_load_lds_dwordx4 v[204:205], off
	s_waitcnt lgkmcnt(8)
	s_barrier
	s_waitcnt lgkmcnt(0)
	v_mfma_f32_16x16x32_bf16 v[124:127], v[150:153], v[166:169], v[124:127]
	v_mfma_f32_16x16x32_bf16 v[120:123], v[158:161], v[166:169], v[120:123]
	v_mfma_f32_16x16x32_bf16 v[108:111], v[150:153], v[174:177], v[108:111]
	v_mfma_f32_16x16x32_bf16 v[104:107], v[158:161], v[174:177], v[104:107]
	v_mfma_f32_16x16x32_bf16 v[92:95], v[150:153], v[188:191], v[92:95]
	v_mfma_f32_16x16x32_bf16 v[88:91], v[158:161], v[188:191], v[88:91]
	v_mfma_f32_16x16x32_bf16 v[76:79], v[150:153], v[196:199], v[76:79]
	v_mfma_f32_16x16x32_bf16 v[72:75], v[158:161], v[196:199], v[72:75]
	v_mfma_f32_16x16x32_bf16 v[124:127], v[154:157], v[170:173], v[124:127]
	v_mfma_f32_16x16x32_bf16 v[120:123], v[162:165], v[170:173], v[120:123]
	v_mfma_f32_16x16x32_bf16 v[108:111], v[154:157], v[184:187], v[108:111]
	v_mfma_f32_16x16x32_bf16 v[104:107], v[162:165], v[184:187], v[104:107]
	v_mfma_f32_16x16x32_bf16 v[92:95], v[154:157], v[192:195], v[92:95]
	v_mfma_f32_16x16x32_bf16 v[88:91], v[162:165], v[192:195], v[88:91]
	v_mfma_f32_16x16x32_bf16 v[76:79], v[154:157], v[200:203], v[76:79]
	v_mfma_f32_16x16x32_bf16 v[72:75], v[162:165], v[200:203], v[72:75]
	s_barrier
	s_add_i32 s18, 0, 0x1c000
	s_add_i32 s19, s80, s21
	v_add_u32_e32 v149, s18, v139
	v_lshl_add_u64 v[146:147], v[146:147], 0, s[38:39]
	s_mov_b32 m0, s19
	ds_read_b128 v[204:207], v149
	ds_read_b128 v[208:211], v149 offset:1024
	ds_read_b128 v[212:215], v149 offset:2048
	ds_read_b128 v[216:219], v149 offset:3072
	global_load_lds_dwordx4 v[146:147], off
	v_lshl_add_u64 v[146:147], v[178:179], 0, s[38:39]
	s_add_i32 m0, s19, 0x2000
	s_nop 0
	global_load_lds_dwordx4 v[146:147], off
	s_barrier
; #define PG8_STAGE(bufoff, gbase, voff) do { _Pragma("unroll") for (int _i = 0; _i < 2; ++_i) \
;         __builtin_amdgcn_global_load_lds((const unsigned*)((const char*)(gbase) + (voff)[_i]), (PG8_LAS unsigned*)(lds + (bufoff) + ldsw + _i * 8192), 16, 0, 0); } while (0)
; #define PG8_LDA(dst, b, h) do { _Pragma("unroll") for (int m = 0; m < 4; ++m) _Pragma("unroll") for (int k = 0; k < 2; ++k) dst[m][k] = *(const PG8_LAS bf16x8*)(lds + PG8_SA(b, h) + aoff + m * 2048 + k * 1024); } while (0)
; #define PG8_MMA(ai, bj, At, Bt) do { __builtin_amdgcn_s_setprio(1); _Pragma("unroll") for (int m = 0; m < 4; ++m) _Pragma("unroll") for (int n = 0; n < 2; ++n) _Pragma("unroll") for (int k = 0; k < 2; ++k) \
;         acc[ai][bj][m][n] = __builtin_amdgcn_mfma_f32_16x16x32_bf16(Bt[n][k], At[m][k], acc[ai][bj][m][n], 0, 0, 0); __builtin_amdgcn_s_setprio(0); } while (0)
; #define PG8_WAIT_V(n) asm volatile("s_waitcnt vmcnt(" #n ")" ::: "memory")
; #define PG8_WAIT_L(n) asm volatile("s_waitcnt lgkmcnt(" #n ")" ::: "memory")
; template <class Epi, class Sched>
; __device__ __forceinline__ void gemm_phase(PG8_LAS unsigned char* lds, const Gemm g, const Sched& S, const Epi& E) {
;     ...
;             PG8_BAR; PG8_WAIT_L(0); PG8_MMA(0, 1, At, B1); PG8_BAR;
;             PG8_LDA(At, 1, 1); PG8_STAGE(PG8_SA(1, 0), a3, voffA);
;             PG8_BAR; PG8_WAIT_L(0); PG8_MMA(1, 0, At, B0); PG8_BAR; PG8_SCHED;
;             PG8_STAGE(PG8_SB(1, 1), b3 + hstep, voffB);
;             PG8_WAIT_V(6); PG8_BAR; PG8_MMA(1, 1, At, B1); PG8_BAR;
;     DI void operator()(const AccT& acc, const pg8::Unit& u, int wr, int wc, int fr, int fq) const {
;     ...
;         if (pn < 8) {
;             bf16_t* dst = (pn < 4 ? q : sg) + (pn & 3) * 256 + cl; const bool act = pn >= 4;
; #pragma unroll
;             for (int ai = 0; ai < 2; ++ai)
; #pragma unroll
;                 for (int m = 0; m < 4; ++m) { const size_t row = (size_t)pm * 256 + lrow0 + ai * 128 + m * 16;
; #pragma unroll
;                     for (int bj = 0; bj < 2; ++bj) { f32x4 v0 = acc[ai][bj][m][0], v1 = acc[ai][bj][m][1]; if (act) { v0 = silu4(v0); v1 = silu4(v1); }
;                         store8(dst + row * 1024 + bj * 128, v0, v1); } }
;         } else {
;             bf16_t* dst = (pn == 8 ? kb : vb) + cl;
;             const int kvbase = pm < 128 ? (pm >> 4) * KVS + (pm & 15) * 256 : (pm - 128) * KVS + SEQ;
	s_waitcnt lgkmcnt(0)
	v_mfma_f32_16x16x32_bf16 v[116:119], v[204:207], v[166:169], v[116:119]
	v_mfma_f32_16x16x32_bf16 v[112:115], v[212:215], v[166:169], v[112:115]
	v_mfma_f32_16x16x32_bf16 v[100:103], v[204:207], v[174:177], v[100:103]
	v_mfma_f32_16x16x32_bf16 v[96:99], v[212:215], v[174:177], v[96:99]
	v_mfma_f32_16x16x32_bf16 v[84:87], v[204:207], v[188:191], v[84:87]
	v_mfma_f32_16x16x32_bf16 v[80:83], v[212:215], v[188:191], v[80:83]
	v_mfma_f32_16x16x32_bf16 v[68:71], v[204:207], v[196:199], v[68:71]
	v_mfma_f32_16x16x32_bf16 v[64:67], v[212:215], v[196:199], v[64:67]
	v_mfma_f32_16x16x32_bf16 v[116:119], v[208:211], v[170:173], v[116:119]
	v_mfma_f32_16x16x32_bf16 v[112:115], v[216:219], v[170:173], v[112:115]
	v_mfma_f32_16x16x32_bf16 v[100:103], v[208:211], v[184:187], v[100:103]
	v_mfma_f32_16x16x32_bf16 v[96:99], v[216:219], v[184:187], v[96:99]
	v_mfma_f32_16x16x32_bf16 v[84:87], v[208:211], v[192:195], v[84:87]
	v_mfma_f32_16x16x32_bf16 v[80:83], v[216:219], v[192:195], v[80:83]
	v_mfma_f32_16x16x32_bf16 v[68:71], v[208:211], v[200:203], v[68:71]
	v_mfma_f32_16x16x32_bf16 v[64:67], v[216:219], v[200:203], v[64:67]
	s_mov_b32 m0, s72
	v_lshl_add_u64 v[146:147], v[220:221], 0, s[38:39]
	s_barrier
	ds_read_b128 v[166:169], v148 offset:49152
	ds_read_b128 v[170:173], v148 offset:50176
	ds_read_b128 v[174:177], v148 offset:51200
	ds_read_b128 v[184:187], v148 offset:52224
	ds_read_b128 v[188:191], v148 offset:53248
	ds_read_b128 v[192:195], v148 offset:54272
	ds_read_b128 v[196:199], v148 offset:55296
	ds_read_b128 v[200:203], v148 offset:56320
	global_load_lds_dwordx4 v[146:147], off
	v_lshl_add_u64 v[146:147], v[222:223], 0, s[38:39]
	s_mov_b32 m0, s73
	s_nop 0
	global_load_lds_dwordx4 v[146:147], off
	s_barrier
	s_waitcnt lgkmcnt(0)
	v_mfma_f32_16x16x32_bf16 v[60:63], v[150:153], v[166:169], v[60:63]
	v_mfma_f32_16x16x32_bf16 v[56:59], v[158:161], v[166:169], v[56:59]
	v_mfma_f32_16x16x32_bf16 v[44:47], v[150:153], v[174:177], v[44:47]
	v_mfma_f32_16x16x32_bf16 v[40:43], v[158:161], v[174:177], v[40:43]
	v_mfma_f32_16x16x32_bf16 v[28:31], v[150:153], v[188:191], v[28:31]
	v_mfma_f32_16x16x32_bf16 v[24:27], v[158:161], v[188:191], v[24:27]
	v_mfma_f32_16x16x32_bf16 v[12:15], v[150:153], v[196:199], v[12:15]
	v_mfma_f32_16x16x32_bf16 v[8:11], v[158:161], v[196:199], v[8:11]
	v_mfma_f32_16x16x32_bf16 v[60:63], v[154:157], v[170:173], v[60:63]
	v_mfma_f32_16x16x32_bf16 v[56:59], v[162:165], v[170:173], v[56:59]
	v_mfma_f32_16x16x32_bf16 v[44:47], v[154:157], v[184:187], v[44:47]
	v_mfma_f32_16x16x32_bf16 v[40:43], v[162:165], v[184:187], v[40:43]
	v_mfma_f32_16x16x32_bf16 v[28:31], v[154:157], v[192:195], v[28:31]
	v_mfma_f32_16x16x32_bf16 v[24:27], v[162:165], v[192:195], v[24:27]
	v_mfma_f32_16x16x32_bf16 v[12:15], v[154:157], v[200:203], v[12:15]
	v_mfma_f32_16x16x32_bf16 v[8:11], v[162:165], v[200:203], v[8:11]
	s_barrier
	s_add_u32 s16, s16, 0x40080
	s_addc_u32 s17, s17, 0
	s_add_i32 s18, s18, s21
	v_lshl_add_u64 v[146:147], s[16:17], 0, v[132:133]
	s_mov_b32 m0, s18
	s_nop 0
	global_load_lds_dwordx4 v[146:147], off
	v_lshl_add_u64 v[146:147], s[16:17], 0, v[128:129]
	s_add_i32 m0, s18, 0x2000
	s_nop 0
	global_load_lds_dwordx4 v[146:147], off
	s_waitcnt vmcnt(6)
	s_barrier
	v_mfma_f32_16x16x32_bf16 v[52:55], v[204:207], v[166:169], v[52:55]
	v_mfma_f32_16x16x32_bf16 v[48:51], v[212:215], v[166:169], v[48:51]
	v_mfma_f32_16x16x32_bf16 v[36:39], v[204:207], v[174:177], v[36:39]
	v_mfma_f32_16x16x32_bf16 v[32:35], v[212:215], v[174:177], v[32:35]
	v_mfma_f32_16x16x32_bf16 v[20:23], v[204:207], v[188:191], v[20:23]
	v_mfma_f32_16x16x32_bf16 v[16:19], v[212:215], v[188:191], v[16:19]
	v_mfma_f32_16x16x32_bf16 v[4:7], v[204:207], v[196:199], v[4:7]
	v_mfma_f32_16x16x32_bf16 v[0:3], v[212:215], v[196:199], v[0:3]
	v_mfma_f32_16x16x32_bf16 v[52:55], v[208:211], v[170:173], v[52:55]
	v_mfma_f32_16x16x32_bf16 v[48:51], v[216:219], v[170:173], v[48:51]
	v_mfma_f32_16x16x32_bf16 v[36:39], v[208:211], v[184:187], v[36:39]
	v_mfma_f32_16x16x32_bf16 v[32:35], v[216:219], v[184:187], v[32:35]
	v_mfma_f32_16x16x32_bf16 v[20:23], v[208:211], v[192:195], v[20:23]
	v_mfma_f32_16x16x32_bf16 v[16:19], v[216:219], v[192:195], v[16:19]
	v_mfma_f32_16x16x32_bf16 v[4:7], v[208:211], v[200:203], v[4:7]
	v_mfma_f32_16x16x32_bf16 v[0:3], v[216:219], v[200:203], v[0:3]
	s_add_i32 s79, s79, 2
	s_add_u32 s14, s14, 0x100
	s_addc_u32 s15, s15, 0
	s_add_u32 s77, s77, 0x100
	s_addc_u32 s78, s78, 0
	s_cmp_gt_u32 s79, 13
	s_barrier
	s_cbranch_scc0 .LBB0_648
	s_cmp_gt_i32 s7, 7
	s_mov_b64 s[14:15], -1
	s_cbranch_scc0 .LBB0_655
	s_cmpk_gt_i32 s6, 0x7f
	s_mov_b64 s[16:17], -1
	s_cbranch_scc0 .LBB0_652
	s_mul_i32 s1, s6, 0x1100
	s_add_i32 s14, s1, 0xfff79000
	s_mov_b64 s[16:17], 0

; #define PG8_STAGE(bufoff, gbase, voff) do { _Pragma("unroll") for (int _i = 0; _i < 2; ++_i) \
;         __builtin_amdgcn_global_load_lds((const unsigned*)((const char*)(gbase) + (voff)[_i]), (PG8_LAS unsigned*)(lds + (bufoff) + ldsw + _i * 8192), 16, 0, 0); } while (0)
; #define PG8_LDA(dst, b, h) do { _Pragma("unroll") for (int m = 0; m < 4; ++m) _Pragma("unroll") for (int k = 0; k < 2; ++k) dst[m][k] = *(const PG8_LAS bf16x8*)(lds + PG8_SA(b, h) + aoff + m * 2048 + k * 1024); } while (0)
; #define PG8_LDB(dst, b, h) do { _Pragma("unroll") for (int n = 0; n < 2; ++n) _Pragma("unroll") for (int k = 0; k < 2; ++k) dst[n][k] = *(const PG8_LAS bf16x8*)(lds + PG8_SB(b, h) + boff + n * 2048 + k * 1024); } while (0)
; #define PG8_MMA(ai, bj, At, Bt) do { __builtin_amdgcn_s_setprio(1); _Pragma("unroll") for (int m = 0; m < 4; ++m) _Pragma("unroll") for (int n = 0; n < 2; ++n) _Pragma("unroll") for (int k = 0; k < 2; ++k) \
;         acc[ai][bj][m][n] = __builtin_amdgcn_mfma_f32_16x16x32_bf16(Bt[n][k], At[m][k], acc[ai][bj][m][n], 0, 0, 0); __builtin_amdgcn_s_setprio(0); } while (0)
; #define PG8_WAIT_L(n) asm volatile("s_waitcnt lgkmcnt(" #n ")" ::: "memory")
; #define PG8_BAR __builtin_amdgcn_s_barrier()
; #define PG8_SCHED __builtin_amdgcn_sched_barrier(0)
; template <class Epi, class Sched>
; __device__ __forceinline__ void gemm_phase(PG8_LAS unsigned char* lds, const Gemm g, const Sched& S, const Epi& E) {
;     ...
;             PG8_LDB(B0, 0, 0); PG8_SCHED; PG8_LDA(At, 0, 0); PG8_STAGE(PG8_SA(1, 1), a1 + hstep, voffA);
;             PG8_WAIT_L(8); PG8_BAR; PG8_WAIT_L(0); PG8_MMA(0, 0, At, B0); PG8_BAR; PG8_SCHED;
;             PG8_LDB(B1, 0, 1); PG8_STAGE(PG8_SB(0, 0), b2, voffB);
;             PG8_BAR; PG8_WAIT_L(0); PG8_MMA(0, 1, At, B1); PG8_BAR;
;             PG8_LDA(At, 0, 1); PG8_STAGE(PG8_SA(0, 0), a2, voffA);
;             PG8_BAR; PG8_WAIT_L(0); PG8_MMA(1, 0, At, B0); PG8_BAR; PG8_SCHED;
.LBB0_912:
	s_add_u32 s16, s14, 0xfffc0080
	s_addc_u32 s17, s15, -1
	s_add_i32 s79, 0, 0x10000
	v_add_u32_e32 v142, s79, v144
	ds_read_b128 v[146:149], v142
	ds_read_b128 v[150:153], v142 offset:1024
	ds_read_b128 v[154:157], v142 offset:2048
	ds_read_b128 v[158:161], v142 offset:3072
	s_cmp_eq_u32 s78, 12
	s_cselect_b32 s19, s7, s17
	s_cselect_b32 s18, s74, s16
	s_cselect_b32 s17, s5, s77
	s_cselect_b32 s16, s75, s76
	v_lshl_add_u64 v[142:143], s[14:15], 0, v[138:139]
	s_add_i32 m0, s46, 0xc000
	ds_read_b128 v[162:165], v145
	ds_read_b128 v[166:169], v145 offset:1024
	ds_read_b128 v[170:173], v145 offset:2048
	ds_read_b128 v[174:177], v145 offset:3072
	ds_read_b128 v[184:187], v145 offset:4096
	ds_read_b128 v[188:191], v145 offset:5120
	ds_read_b128 v[192:195], v145 offset:6144
	ds_read_b128 v[196:199], v145 offset:7168
	global_load_lds_dwordx4 v[142:143], off
	v_lshl_add_u64 v[142:143], s[14:15], 0, v[140:141]
	s_add_i32 m0, s46, 0xe000
	s_nop 0
	global_load_lds_dwordx4 v[142:143], off
	s_waitcnt lgkmcnt(8)
	s_barrier
	s_waitcnt lgkmcnt(0)
	v_mfma_f32_16x16x32_bf16 v[124:127], v[146:149], v[162:165], v[124:127]
	v_mfma_f32_16x16x32_bf16 v[120:123], v[154:157], v[162:165], v[120:123]
	v_mfma_f32_16x16x32_bf16 v[116:119], v[146:149], v[170:173], v[116:119]
	v_mfma_f32_16x16x32_bf16 v[108:111], v[154:157], v[170:173], v[108:111]
	v_mfma_f32_16x16x32_bf16 v[100:103], v[146:149], v[184:187], v[100:103]
	v_mfma_f32_16x16x32_bf16 v[92:95], v[154:157], v[184:187], v[92:95]
	v_mfma_f32_16x16x32_bf16 v[84:87], v[146:149], v[192:195], v[84:87]
	v_mfma_f32_16x16x32_bf16 v[76:79], v[154:157], v[192:195], v[76:79]
	v_mfma_f32_16x16x32_bf16 v[124:127], v[150:153], v[166:169], v[124:127]
	v_mfma_f32_16x16x32_bf16 v[120:123], v[158:161], v[166:169], v[120:123]
	v_mfma_f32_16x16x32_bf16 v[116:119], v[150:153], v[174:177], v[116:119]
	v_mfma_f32_16x16x32_bf16 v[108:111], v[158:161], v[174:177], v[108:111]
	v_mfma_f32_16x16x32_bf16 v[100:103], v[150:153], v[188:191], v[100:103]
	v_mfma_f32_16x16x32_bf16 v[92:95], v[158:161], v[188:191], v[92:95]
	v_mfma_f32_16x16x32_bf16 v[84:87], v[150:153], v[196:199], v[84:87]
	v_mfma_f32_16x16x32_bf16 v[76:79], v[158:161], v[196:199], v[76:79]
	s_barrier
	s_add_i32 s82, 0, 0x14000
	v_add_u32_e32 v142, s82, v144
	s_add_i32 s79, s79, s21
	ds_read_b128 v[200:203], v142
	ds_read_b128 v[204:207], v142 offset:1024
	ds_read_b128 v[208:211], v142 offset:2048
	ds_read_b128 v[212:215], v142 offset:3072
	v_lshl_add_u64 v[142:143], s[16:17], 0, v[180:181]
	s_mov_b32 m0, s79
	v_lshl_add_u64 v[178:179], s[16:17], 0, v[128:129]
	global_load_lds_dwordx4 v[142:143], off
	s_add_i32 m0, s79, 0x2000
	s_nop 0
	global_load_lds_dwordx4 v[178:179], off
	s_barrier
	s_waitcnt lgkmcnt(0)
	v_mfma_f32_16x16x32_bf16 v[112:115], v[200:203], v[162:165], v[112:115]
	v_mfma_f32_16x16x32_bf16 v[104:107], v[208:211], v[162:165], v[104:107]
	v_mfma_f32_16x16x32_bf16 v[96:99], v[200:203], v[170:173], v[96:99]
	v_mfma_f32_16x16x32_bf16 v[88:91], v[208:211], v[170:173], v[88:91]
	v_mfma_f32_16x16x32_bf16 v[80:83], v[200:203], v[184:187], v[80:83]
	v_mfma_f32_16x16x32_bf16 v[72:75], v[208:211], v[184:187], v[72:75]
	v_mfma_f32_16x16x32_bf16 v[68:71], v[200:203], v[192:195], v[68:71]
	v_mfma_f32_16x16x32_bf16 v[64:67], v[208:211], v[192:195], v[64:67]
	v_mfma_f32_16x16x32_bf16 v[112:115], v[204:207], v[166:169], v[112:115]
	v_mfma_f32_16x16x32_bf16 v[104:107], v[212:215], v[166:169], v[104:107]
	v_mfma_f32_16x16x32_bf16 v[96:99], v[204:207], v[174:177], v[96:99]
	v_mfma_f32_16x16x32_bf16 v[88:91], v[212:215], v[174:177], v[88:91]
	v_mfma_f32_16x16x32_bf16 v[80:83], v[204:207], v[188:191], v[80:83]
	v_mfma_f32_16x16x32_bf16 v[72:75], v[212:215], v[188:191], v[72:75]
	v_mfma_f32_16x16x32_bf16 v[68:71], v[204:207], v[196:199], v[68:71]
	v_mfma_f32_16x16x32_bf16 v[64:67], v[212:215], v[196:199], v[64:67]
	s_mov_b32 m0, s46
	v_lshl_add_u64 v[216:217], s[18:19], 0, v[132:133]
	s_barrier
	ds_read_b128 v[162:165], v145 offset:16384
	ds_read_b128 v[166:169], v145 offset:17408
	ds_read_b128 v[170:173], v145 offset:18432
	ds_read_b128 v[174:177], v145 offset:19456
	ds_read_b128 v[184:187], v145 offset:20480
	ds_read_b128 v[188:191], v145 offset:21504
	ds_read_b128 v[192:195], v145 offset:22528
	ds_read_b128 v[196:199], v145 offset:23552
	global_load_lds_dwordx4 v[216:217], off
	v_lshl_add_u64 v[218:219], s[18:19], 0, v[130:131]
	s_mov_b32 m0, s47
	s_nop 0
	global_load_lds_dwordx4 v[218:219], off
	s_barrier
	s_waitcnt lgkmcnt(0)
	v_mfma_f32_16x16x32_bf16 v[60:63], v[146:149], v[162:165], v[60:63]
	v_mfma_f32_16x16x32_bf16 v[56:59], v[154:157], v[162:165], v[56:59]
	v_mfma_f32_16x16x32_bf16 v[52:55], v[146:149], v[170:173], v[52:55]
	v_mfma_f32_16x16x32_bf16 v[44:47], v[154:157], v[170:173], v[44:47]
	v_mfma_f32_16x16x32_bf16 v[36:39], v[146:149], v[184:187], v[36:39]
	v_mfma_f32_16x16x32_bf16 v[28:31], v[154:157], v[184:187], v[28:31]
	v_mfma_f32_16x16x32_bf16 v[20:23], v[146:149], v[192:195], v[20:23]
	v_mfma_f32_16x16x32_bf16 v[12:15], v[154:157], v[192:195], v[12:15]
	v_mfma_f32_16x16x32_bf16 v[60:63], v[150:153], v[166:169], v[60:63]
	v_mfma_f32_16x16x32_bf16 v[56:59], v[158:161], v[166:169], v[56:59]
	v_mfma_f32_16x16x32_bf16 v[52:55], v[150:153], v[174:177], v[52:55]
	v_mfma_f32_16x16x32_bf16 v[44:47], v[158:161], v[174:177], v[44:47]
	v_mfma_f32_16x16x32_bf16 v[36:39], v[150:153], v[188:191], v[36:39]
	v_mfma_f32_16x16x32_bf16 v[28:31], v[158:161], v[188:191], v[28:31]
	v_mfma_f32_16x16x32_bf16 v[20:23], v[150:153], v[196:199], v[20:23]
	v_mfma_f32_16x16x32_bf16 v[12:15], v[158:161], v[196:199], v[12:15]
	s_barrier
; #define PG8_STAGE(bufoff, gbase, voff) do { _Pragma("unroll") for (int _i = 0; _i < 2; ++_i) \
;         __builtin_amdgcn_global_load_lds((const unsigned*)((const char*)(gbase) + (voff)[_i]), (PG8_LAS unsigned*)(lds + (bufoff) + ldsw + _i * 8192), 16, 0, 0); } while (0)
; #define PG8_LDA(dst, b, h) do { _Pragma("unroll") for (int m = 0; m < 4; ++m) _Pragma("unroll") for (int k = 0; k < 2; ++k) dst[m][k] = *(const PG8_LAS bf16x8*)(lds + PG8_SA(b, h) + aoff + m * 2048 + k * 1024); } while (0)
; #define PG8_LDB(dst, b, h) do { _Pragma("unroll") for (int n = 0; n < 2; ++n) _Pragma("unroll") for (int k = 0; k < 2; ++k) dst[n][k] = *(const PG8_LAS bf16x8*)(lds + PG8_SB(b, h) + boff + n * 2048 + k * 1024); } while (0)
; #define PG8_MMA(ai, bj, At, Bt) do { __builtin_amdgcn_s_setprio(1); _Pragma("unroll") for (int m = 0; m < 4; ++m) _Pragma("unroll") for (int n = 0; n < 2; ++n) _Pragma("unroll") for (int k = 0; k < 2; ++k) \
;         acc[ai][bj][m][n] = __builtin_amdgcn_mfma_f32_16x16x32_bf16(Bt[n][k], At[m][k], acc[ai][bj][m][n], 0, 0, 0); __builtin_amdgcn_s_setprio(0); } while (0)
; #define PG8_WAIT_V(n) asm volatile("s_waitcnt vmcnt(" #n ")" ::: "memory")
; #define PG8_WAIT_L(n) asm volatile("s_waitcnt lgkmcnt(" #n ")" ::: "memory")
; #define PG8_BAR __builtin_amdgcn_s_barrier()
; #define PG8_SCHED __builtin_amdgcn_sched_barrier(0)
; template <class Epi, class Sched>
; __device__ __forceinline__ void gemm_phase(PG8_LAS unsigned char* lds, const Gemm g, const Sched& S, const Epi& E) {
;     ...
;             PG8_STAGE(PG8_SB(0, 1), b2 + hstep, voffB);
;             PG8_WAIT_V(6); PG8_BAR; PG8_MMA(1, 1, At, B1); PG8_BAR;
;             PG8_LDB(B0, 1, 0); PG8_SCHED; PG8_LDA(At, 1, 0); PG8_STAGE(PG8_SA(0, 1), a2 + hstep, voffA);
;             PG8_WAIT_L(8); PG8_BAR; PG8_WAIT_L(0); PG8_MMA(0, 0, At, B0); PG8_BAR; PG8_SCHED;
;             PG8_LDB(B1, 1, 1); PG8_STAGE(PG8_SB(1, 0), b3, voffB);
;             PG8_BAR; PG8_WAIT_L(0); PG8_MMA(0, 1, At, B1); PG8_BAR;
;             PG8_LDA(At, 1, 1); PG8_STAGE(PG8_SA(1, 0), a3, voffA);
;             PG8_BAR; PG8_WAIT_L(0); PG8_MMA(1, 0, At, B0); PG8_BAR; PG8_SCHED;
	s_add_u32 s80, s16, 0x40000
	s_addc_u32 s81, s17, 0
	s_add_i32 s79, s82, s21
	v_lshl_add_u64 v[146:147], s[80:81], 0, v[180:181]
	s_mov_b32 m0, s79
	s_nop 0
	global_load_lds_dwordx4 v[146:147], off
	v_lshl_add_u64 v[146:147], s[80:81], 0, v[128:129]
	s_add_i32 m0, s79, 0x2000
	s_nop 0
	global_load_lds_dwordx4 v[146:147], off
	s_waitcnt vmcnt(6)
	s_barrier
	v_mfma_f32_16x16x32_bf16 v[48:51], v[200:203], v[162:165], v[48:51]
	v_mfma_f32_16x16x32_bf16 v[40:43], v[208:211], v[162:165], v[40:43]
	v_mfma_f32_16x16x32_bf16 v[32:35], v[200:203], v[170:173], v[32:35]
	v_mfma_f32_16x16x32_bf16 v[24:27], v[208:211], v[170:173], v[24:27]
	v_mfma_f32_16x16x32_bf16 v[16:19], v[200:203], v[184:187], v[16:19]
	v_mfma_f32_16x16x32_bf16 v[8:11], v[208:211], v[184:187], v[8:11]
	v_mfma_f32_16x16x32_bf16 v[4:7], v[200:203], v[192:195], v[4:7]
	v_mfma_f32_16x16x32_bf16 v[0:3], v[208:211], v[192:195], v[0:3]
	v_mfma_f32_16x16x32_bf16 v[48:51], v[204:207], v[166:169], v[48:51]
	v_mfma_f32_16x16x32_bf16 v[40:43], v[212:215], v[166:169], v[40:43]
	v_mfma_f32_16x16x32_bf16 v[32:35], v[204:207], v[174:177], v[32:35]
	v_mfma_f32_16x16x32_bf16 v[24:27], v[212:215], v[174:177], v[24:27]
	v_mfma_f32_16x16x32_bf16 v[16:19], v[204:207], v[188:191], v[16:19]
	v_mfma_f32_16x16x32_bf16 v[8:11], v[212:215], v[188:191], v[8:11]
	v_mfma_f32_16x16x32_bf16 v[4:7], v[204:207], v[196:199], v[4:7]
	v_mfma_f32_16x16x32_bf16 v[0:3], v[212:215], v[196:199], v[0:3]
	s_add_i32 s79, 0, 0x18000
	v_add_u32_e32 v158, s79, v144
	s_barrier
	ds_read_b128 v[146:149], v158
	ds_read_b128 v[150:153], v158 offset:1024
	ds_read_b128 v[154:157], v158 offset:2048
	ds_read_b128 v[158:161], v158 offset:3072
	s_add_u32 s18, s18, 0x40000
	s_addc_u32 s19, s19, 0
	s_mov_b32 m0, s69
	v_lshl_add_u64 v[200:201], s[18:19], 0, v[132:133]
	ds_read_b128 v[162:165], v145 offset:32768
	ds_read_b128 v[166:169], v145 offset:33792
	ds_read_b128 v[170:173], v145 offset:34816
	ds_read_b128 v[174:177], v145 offset:35840
	ds_read_b128 v[184:187], v145 offset:36864
	ds_read_b128 v[188:191], v145 offset:37888
	ds_read_b128 v[192:195], v145 offset:38912
	ds_read_b128 v[196:199], v145 offset:39936
	global_load_lds_dwordx4 v[200:201], off
	v_lshl_add_u64 v[200:201], s[18:19], 0, v[130:131]
	s_mov_b32 m0, s70
	s_nop 0
	global_load_lds_dwordx4 v[200:201], off
	s_waitcnt lgkmcnt(8)
	s_barrier
	s_waitcnt lgkmcnt(0)
	v_mfma_f32_16x16x32_bf16 v[124:127], v[146:149], v[162:165], v[124:127]
	v_mfma_f32_16x16x32_bf16 v[120:123], v[154:157], v[162:165], v[120:123]
	v_mfma_f32_16x16x32_bf16 v[116:119], v[146:149], v[170:173], v[116:119]
	v_mfma_f32_16x16x32_bf16 v[108:111], v[154:157], v[170:173], v[108:111]
	v_mfma_f32_16x16x32_bf16 v[100:103], v[146:149], v[184:187], v[100:103]
	v_mfma_f32_16x16x32_bf16 v[92:95], v[154:157], v[184:187], v[92:95]
	v_mfma_f32_16x16x32_bf16 v[84:87], v[146:149], v[192:195], v[84:87]
	v_mfma_f32_16x16x32_bf16 v[76:79], v[154:157], v[192:195], v[76:79]
	v_mfma_f32_16x16x32_bf16 v[124:127], v[150:153], v[166:169], v[124:127]
	v_mfma_f32_16x16x32_bf16 v[120:123], v[158:161], v[166:169], v[120:123]
	v_mfma_f32_16x16x32_bf16 v[116:119], v[150:153], v[174:177], v[116:119]
	v_mfma_f32_16x16x32_bf16 v[108:111], v[158:161], v[174:177], v[108:111]
	v_mfma_f32_16x16x32_bf16 v[100:103], v[150:153], v[188:191], v[100:103]
	v_mfma_f32_16x16x32_bf16 v[92:95], v[158:161], v[188:191], v[92:95]
	v_mfma_f32_16x16x32_bf16 v[84:87], v[150:153], v[196:199], v[84:87]
	v_mfma_f32_16x16x32_bf16 v[76:79], v[158:161], v[196:199], v[76:79]
	s_barrier
	s_add_i32 s18, 0, 0x1c000
	s_add_i32 s19, s79, s21
	v_add_u32_e32 v212, s18, v144
	v_lshl_add_u64 v[142:143], v[142:143], 0, s[38:39]
	s_mov_b32 m0, s19
	ds_read_b128 v[200:203], v212
	ds_read_b128 v[204:207], v212 offset:1024
	ds_read_b128 v[208:211], v212 offset:2048
	ds_read_b128 v[212:215], v212 offset:3072
	global_load_lds_dwordx4 v[142:143], off
	v_lshl_add_u64 v[142:143], v[178:179], 0, s[38:39]
	s_add_i32 m0, s19, 0x2000
	s_nop 0
	global_load_lds_dwordx4 v[142:143], off
	s_barrier
	s_waitcnt lgkmcnt(0)
	v_mfma_f32_16x16x32_bf16 v[112:115], v[200:203], v[162:165], v[112:115]
	v_mfma_f32_16x16x32_bf16 v[104:107], v[208:211], v[162:165], v[104:107]
	v_mfma_f32_16x16x32_bf16 v[96:99], v[200:203], v[170:173], v[96:99]
	v_mfma_f32_16x16x32_bf16 v[88:91], v[208:211], v[170:173], v[88:91]
	v_mfma_f32_16x16x32_bf16 v[80:83], v[200:203], v[184:187], v[80:83]
	v_mfma_f32_16x16x32_bf16 v[72:75], v[208:211], v[184:187], v[72:75]
	v_mfma_f32_16x16x32_bf16 v[68:71], v[200:203], v[192:195], v[68:71]
	v_mfma_f32_16x16x32_bf16 v[64:67], v[208:211], v[192:195], v[64:67]
	v_mfma_f32_16x16x32_bf16 v[112:115], v[204:207], v[166:169], v[112:115]
	v_mfma_f32_16x16x32_bf16 v[104:107], v[212:215], v[166:169], v[104:107]
	v_mfma_f32_16x16x32_bf16 v[96:99], v[204:207], v[174:177], v[96:99]
	v_mfma_f32_16x16x32_bf16 v[88:91], v[212:215], v[174:177], v[88:91]
	v_mfma_f32_16x16x32_bf16 v[80:83], v[204:207], v[188:191], v[80:83]
	v_mfma_f32_16x16x32_bf16 v[72:75], v[212:215], v[188:191], v[72:75]
	v_mfma_f32_16x16x32_bf16 v[68:71], v[204:207], v[196:199], v[68:71]
	v_mfma_f32_16x16x32_bf16 v[64:67], v[212:215], v[196:199], v[64:67]
	s_mov_b32 m0, s71
	v_lshl_add_u64 v[142:143], v[216:217], 0, s[38:39]
	s_barrier
	ds_read_b128 v[162:165], v145 offset:49152
	ds_read_b128 v[166:169], v145 offset:50176
	ds_read_b128 v[170:173], v145 offset:51200
	ds_read_b128 v[174:177], v145 offset:52224
	ds_read_b128 v[184:187], v145 offset:53248
	ds_read_b128 v[188:191], v145 offset:54272
	ds_read_b128 v[192:195], v145 offset:55296
	ds_read_b128 v[196:199], v145 offset:56320
	global_load_lds_dwordx4 v[142:143], off
	v_lshl_add_u64 v[142:143], v[218:219], 0, s[38:39]
	s_mov_b32 m0, s72
	s_nop 0
	global_load_lds_dwordx4 v[142:143], off
	s_barrier
; #define PG8_STAGE(bufoff, gbase, voff) do { _Pragma("unroll") for (int _i = 0; _i < 2; ++_i) \
;         __builtin_amdgcn_global_load_lds((const unsigned*)((const char*)(gbase) + (voff)[_i]), (PG8_LAS unsigned*)(lds + (bufoff) + ldsw + _i * 8192), 16, 0, 0); } while (0)
; #define PG8_MMA(ai, bj, At, Bt) do { __builtin_amdgcn_s_setprio(1); _Pragma("unroll") for (int m = 0; m < 4; ++m) _Pragma("unroll") for (int n = 0; n < 2; ++n) _Pragma("unroll") for (int k = 0; k < 2; ++k) \
;         acc[ai][bj][m][n] = __builtin_amdgcn_mfma_f32_16x16x32_bf16(Bt[n][k], At[m][k], acc[ai][bj][m][n], 0, 0, 0); __builtin_amdgcn_s_setprio(0); } while (0)
; #define PG8_WAIT_V(n) asm volatile("s_waitcnt vmcnt(" #n ")" ::: "memory")
; #define PG8_WAIT_L(n) asm volatile("s_waitcnt lgkmcnt(" #n ")" ::: "memory")
; #define PG8_BAR __builtin_amdgcn_s_barrier()
; #define PG8_SCHED __builtin_amdgcn_sched_barrier(0)
; DI void store8(bf16_t* p, f32x4 a, f32x4 b) { u32x4 w = {cvt_pk_bf16(a[0], a[1]), cvt_pk_bf16(a[2], a[3]), cvt_pk_bf16(b[0], b[1]), cvt_pk_bf16(b[2], b[3])}; *(u32x4*)p = w; }
; template <class Epi, class Sched>
; __device__ __forceinline__ void gemm_phase(PG8_LAS unsigned char* lds, const Gemm g, const Sched& S, const Epi& E) {
;     ...
;             PG8_BAR; PG8_WAIT_L(0); PG8_MMA(1, 0, At, B0); PG8_BAR; PG8_SCHED;
;             PG8_STAGE(PG8_SB(1, 1), b3 + hstep, voffB);
;             PG8_WAIT_V(6); PG8_BAR; PG8_MMA(1, 1, At, B1); PG8_BAR;
;         }
;         E(acc, cur, wr, wc, fr, fq); S.done(cur);
;         if (!has_next) break;
;     DI void operator()(const AccT& acc, const pg8::Unit& u, int wr, int wc, int fr, int fq) const {
;         bf16_t* dst = o + u.pn * 256 + wc * 32 + 8 * fq;
; #pragma unroll
;         for (int ai = 0; ai < 2; ++ai)
; #pragma unroll
;             for (int m = 0; m < 4; ++m) { const size_t row = (size_t)u.pm * 256 + wr * 64 + fr + ai * 128 + m * 16;
; #pragma unroll
;                 for (int bj = 0; bj < 2; ++bj) store8(dst + row * ldc + bj * 128, acc[ai][bj][m][0], acc[ai][bj][m][1]); }
	s_waitcnt lgkmcnt(0)
	v_mfma_f32_16x16x32_bf16 v[60:63], v[146:149], v[162:165], v[60:63]
	v_mfma_f32_16x16x32_bf16 v[56:59], v[154:157], v[162:165], v[56:59]
	v_mfma_f32_16x16x32_bf16 v[52:55], v[146:149], v[170:173], v[52:55]
	v_mfma_f32_16x16x32_bf16 v[44:47], v[154:157], v[170:173], v[44:47]
	v_mfma_f32_16x16x32_bf16 v[36:39], v[146:149], v[184:187], v[36:39]
	v_mfma_f32_16x16x32_bf16 v[28:31], v[154:157], v[184:187], v[28:31]
	v_mfma_f32_16x16x32_bf16 v[20:23], v[146:149], v[192:195], v[20:23]
	v_mfma_f32_16x16x32_bf16 v[12:15], v[154:157], v[192:195], v[12:15]
	v_mfma_f32_16x16x32_bf16 v[60:63], v[150:153], v[166:169], v[60:63]
	v_mfma_f32_16x16x32_bf16 v[56:59], v[158:161], v[166:169], v[56:59]
	v_mfma_f32_16x16x32_bf16 v[52:55], v[150:153], v[174:177], v[52:55]
	v_mfma_f32_16x16x32_bf16 v[44:47], v[158:161], v[174:177], v[44:47]
	v_mfma_f32_16x16x32_bf16 v[36:39], v[150:153], v[188:191], v[36:39]
	v_mfma_f32_16x16x32_bf16 v[28:31], v[158:161], v[188:191], v[28:31]
	v_mfma_f32_16x16x32_bf16 v[20:23], v[150:153], v[196:199], v[20:23]
	v_mfma_f32_16x16x32_bf16 v[12:15], v[158:161], v[196:199], v[12:15]
	s_barrier
	s_add_u32 s16, s16, 0x40080
	s_addc_u32 s17, s17, 0
	s_add_i32 s18, s18, s21
	v_lshl_add_u64 v[142:143], s[16:17], 0, v[180:181]
	s_mov_b32 m0, s18
	s_nop 0
	global_load_lds_dwordx4 v[142:143], off
	v_lshl_add_u64 v[142:143], s[16:17], 0, v[128:129]
	s_add_i32 m0, s18, 0x2000
	s_nop 0
	global_load_lds_dwordx4 v[142:143], off
	s_waitcnt vmcnt(6)
	s_barrier
	v_mfma_f32_16x16x32_bf16 v[48:51], v[200:203], v[162:165], v[48:51]
	v_mfma_f32_16x16x32_bf16 v[40:43], v[208:211], v[162:165], v[40:43]
	v_mfma_f32_16x16x32_bf16 v[32:35], v[200:203], v[170:173], v[32:35]
	v_mfma_f32_16x16x32_bf16 v[24:27], v[208:211], v[170:173], v[24:27]
	v_mfma_f32_16x16x32_bf16 v[16:19], v[200:203], v[184:187], v[16:19]
	v_mfma_f32_16x16x32_bf16 v[8:11], v[208:211], v[184:187], v[8:11]
	v_mfma_f32_16x16x32_bf16 v[4:7], v[200:203], v[192:195], v[4:7]
	v_mfma_f32_16x16x32_bf16 v[0:3], v[208:211], v[192:195], v[0:3]
	v_mfma_f32_16x16x32_bf16 v[48:51], v[204:207], v[166:169], v[48:51]
	v_mfma_f32_16x16x32_bf16 v[40:43], v[212:215], v[166:169], v[40:43]
	v_mfma_f32_16x16x32_bf16 v[32:35], v[204:207], v[174:177], v[32:35]
	v_mfma_f32_16x16x32_bf16 v[24:27], v[212:215], v[174:177], v[24:27]
	v_mfma_f32_16x16x32_bf16 v[16:19], v[204:207], v[188:191], v[16:19]
	v_mfma_f32_16x16x32_bf16 v[8:11], v[212:215], v[188:191], v[8:11]
	v_mfma_f32_16x16x32_bf16 v[4:7], v[204:207], v[196:199], v[4:7]
	v_mfma_f32_16x16x32_bf16 v[0:3], v[212:215], v[196:199], v[0:3]
	s_add_i32 s78, s78, 2
	s_add_u32 s14, s14, 0x100
	s_addc_u32 s15, s15, 0
	s_add_u32 s76, s76, 0x100
	s_addc_u32 s77, s77, 0
	s_cmp_gt_u32 s78, 13
	s_barrier
	s_cbranch_scc0 .LBB0_912
	s_lshl_b32 s14, s13, 8
	s_ashr_i32 s15, s14, 31
	s_ashr_i32 s13, s12, 31
	v_lshl_add_u64 v[142:143], s[14:15], 1, v[134:135]
	s_lshl_b64 s[12:13], s[12:13], 19
	v_lshl_add_u64 v[142:143], v[142:143], 0, s[12:13]
	v_lshl_add_u64 v[142:143], v[142:143], 0, v[136:137]
	s_mov_b32 s5, 0x8000
	v_cvt_pk_bf16_f32 v124, v124, v125
	v_cvt_pk_bf16_f32 v125, v126, v127
	v_cvt_pk_bf16_f32 v126, v120, v121
	v_cvt_pk_bf16_f32 v127, v122, v123
	global_store_dwordx4 v[142:143], v[124:127], off
	v_cvt_pk_bf16_f32 v112, v112, v113
	v_cvt_pk_bf16_f32 v113, v114, v115
	v_cvt_pk_bf16_f32 v114, v104, v105
	v_cvt_pk_bf16_f32 v115, v106, v107
	global_store_dwordx4 v[142:143], v[112:115], off offset:256
	v_cvt_pk_bf16_f32 v104, v116, v117
	v_cvt_pk_bf16_f32 v105, v118, v119
	v_cvt_pk_bf16_f32 v106, v108, v109
	v_add_co_u32_e32 v108, vcc, s5, v142
	s_mov_b32 s5, 0x10000
	s_nop 0
	v_addc_co_u32_e32 v109, vcc, 0, v143, vcc
	v_cvt_pk_bf16_f32 v107, v110, v111
	global_store_dwordx4 v[108:109], v[104:107], off
	v_cvt_pk_bf16_f32 v96, v96, v97
	v_cvt_pk_bf16_f32 v97, v98, v99
	v_cvt_pk_bf16_f32 v98, v88, v89
	v_cvt_pk_bf16_f32 v99, v90, v91
	global_store_dwordx4 v[108:109], v[96:99], off offset:256
	v_cvt_pk_bf16_f32 v88, v100, v101
	v_cvt_pk_bf16_f32 v89, v102, v103
	v_cvt_pk_bf16_f32 v90, v92, v93
	v_add_co_u32_e32 v92, vcc, s5, v142
	s_mov_b32 s5, 0x18000
	s_nop 0
	v_addc_co_u32_e32 v93, vcc, 0, v143, vcc
	v_cvt_pk_bf16_f32 v91, v94, v95
	global_store_dwordx4 v[92:93], v[88:91], off
	v_cvt_pk_bf16_f32 v80, v80, v81
	v_cvt_pk_bf16_f32 v81, v82, v83
	v_cvt_pk_bf16_f32 v82, v72, v73
	v_cvt_pk_bf16_f32 v83, v74, v75
	global_store_dwordx4 v[92:93], v[80:83], off offset:256
	v_cvt_pk_bf16_f32 v72, v84, v85
	v_cvt_pk_bf16_f32 v73, v86, v87
	v_cvt_pk_bf16_f32 v74, v76, v77
	v_add_co_u32_e32 v76, vcc, s5, v142
	s_mov_b32 s5, 0x40000
	s_nop 0
	v_addc_co_u32_e32 v77, vcc, 0, v143, vcc
	v_cvt_pk_bf16_f32 v75, v78, v79
	global_store_dwordx4 v[76:77], v[72:75], off
	v_cvt_pk_bf16_f32 v68, v68, v69
	v_cvt_pk_bf16_f32 v69, v70, v71
	v_cvt_pk_bf16_f32 v70, v64, v65
	v_cvt_pk_bf16_f32 v71, v66, v67
	global_store_dwordx4 v[76:77], v[68:71], off offset:256
	v_cvt_pk_bf16_f32 v60, v60, v61
	v_cvt_pk_bf16_f32 v61, v62, v63
	v_cvt_pk_bf16_f32 v62, v56, v57
	v_add_co_u32_e32 v56, vcc, s5, v142
	s_mov_b32 s5, 0x48000
	s_nop 0
	v_addc_co_u32_e32 v57, vcc, 0, v143, vcc
	v_cvt_pk_bf16_f32 v63, v58, v59
	global_store_dwordx4 v[56:57], v[60:63], off
	v_cvt_pk_bf16_f32 v48, v48, v49
	v_cvt_pk_bf16_f32 v49, v50, v51
	v_cvt_pk_bf16_f32 v50, v40, v41
	v_cvt_pk_bf16_f32 v51, v42, v43
	global_store_dwordx4 v[56:57], v[48:51], off offset:256
	v_cvt_pk_bf16_f32 v40, v52, v53
	v_cvt_pk_bf16_f32 v41, v54, v55
	v_cvt_pk_bf16_f32 v42, v44, v45
	v_add_co_u32_e32 v44, vcc, s5, v142
	s_mov_b32 s5, 0x50000
	s_nop 0
	v_addc_co_u32_e32 v45, vcc, 0, v143, vcc
	v_cvt_pk_bf16_f32 v43, v46, v47
	global_store_dwordx4 v[44:45], v[40:43], off
	v_cvt_pk_bf16_f32 v32, v32, v33
	v_cvt_pk_bf16_f32 v33, v34, v35
	v_cvt_pk_bf16_f32 v34, v24, v25
	v_cvt_pk_bf16_f32 v35, v26, v27
	global_store_dwordx4 v[44:45], v[32:35], off offset:256
	v_cvt_pk_bf16_f32 v24, v36, v37
	v_cvt_pk_bf16_f32 v25, v38, v39
	v_cvt_pk_bf16_f32 v26, v28, v29
	v_add_co_u32_e32 v28, vcc, s5, v142
	s_mov_b32 s5, 0x58000
	s_nop 0
	v_addc_co_u32_e32 v29, vcc, 0, v143, vcc
	v_cvt_pk_bf16_f32 v27, v30, v31
	global_store_dwordx4 v[28:29], v[24:27], off
	v_cvt_pk_bf16_f32 v16, v16, v17
	v_cvt_pk_bf16_f32 v17, v18, v19
	v_cvt_pk_bf16_f32 v18, v8, v9
	v_cvt_pk_bf16_f32 v19, v10, v11
	global_store_dwordx4 v[28:29], v[16:19], off offset:256
	v_cvt_pk_bf16_f32 v8, v20, v21
	v_cvt_pk_bf16_f32 v9, v22, v23
	v_cvt_pk_bf16_f32 v10, v12, v13
	v_add_co_u32_e32 v12, vcc, s5, v142
	s_mov_b32 s13, s4
	s_nop 0
	v_addc_co_u32_e32 v13, vcc, 0, v143, vcc
	s_and_b64 vcc, exec, s[0:1]
	s_mov_b32 s12, s6
	s_mov_b64 s[16:17], s[10:11]
	s_mov_b64 s[14:15], s[8:9]
	v_cvt_pk_bf16_f32 v11, v14, v15
	global_store_dwordx4 v[12:13], v[8:11], off
	v_cvt_pk_bf16_f32 v4, v4, v5
	v_cvt_pk_bf16_f32 v5, v6, v7
	v_cvt_pk_bf16_f32 v6, v0, v1
	v_cvt_pk_bf16_f32 v7, v2, v3
	global_store_dwordx4 v[12:13], v[4:7], off offset:256
	s_cbranch_vccz .LBB0_909
	s_waitcnt vmcnt(0)
	s_cmpk_gt_u32 s20, 0xff
	s_cbranch_scc1 .LBB0_916
	s_barrier
